# removed compiler-inserted s_waitcnt lgkmcnt(0) between B-fragment and A-fragment ds_reads in GEMM K-loop phases 1 and 5 (38 sites)
# baseline (speedup 1.0000x reference)
.LBB0_127:
	ds_read_b128 v[148:151], v234
	ds_read_b128 v[152:155], v234 offset:1024
	ds_read_b128 v[156:159], v234 offset:2048
	ds_read_b128 v[160:163], v234 offset:3072
	s_add_u32 s8, s40, 0xfffc0080
	s_addc_u32 s9, s41, -1
	s_cmp_eq_u32 s29, s64
	s_cselect_b32 s45, s2, s9
	s_cselect_b32 s44, s17, s8
	s_cselect_b32 s43, s25, s63
	s_cselect_b32 s42, s27, s39
	v_lshl_add_u64 v[2:3], s[40:41], 0, v[214:215]
	s_add_i32 m0, s46, 0xc000
	ds_read_b128 v[164:167], v235
	ds_read_b128 v[168:171], v235 offset:1024
	ds_read_b128 v[172:175], v235 offset:2048
	ds_read_b128 v[176:179], v235 offset:3072
	ds_read_b128 v[180:183], v235 offset:4096
	ds_read_b128 v[184:187], v235 offset:5120
	ds_read_b128 v[188:191], v235 offset:6144
	ds_read_b128 v[192:195], v235 offset:7168
	global_load_lds_dwordx4 v[2:3], off
	v_lshl_add_u64 v[2:3], s[40:41], 0, v[216:217]
	s_add_i32 m0, s46, 0xe000
	s_nop 0
	global_load_lds_dwordx4 v[2:3], off
	s_waitcnt lgkmcnt(8)
	s_barrier
	s_waitcnt lgkmcnt(0)
	s_setprio 1
	s_waitcnt lgkmcnt(0)
	v_mfma_f32_16x16x32_bf16 v[72:75], v[148:151], v[164:167], v[72:75]
	v_mfma_f32_16x16x32_bf16 v[68:71], v[156:159], v[164:167], v[68:71]
	v_mfma_f32_16x16x32_bf16 v[56:59], v[148:151], v[172:175], v[56:59]
	v_mfma_f32_16x16x32_bf16 v[52:55], v[156:159], v[172:175], v[52:55]
	v_mfma_f32_16x16x32_bf16 v[40:43], v[148:151], v[180:183], v[40:43]
	v_mfma_f32_16x16x32_bf16 v[36:39], v[156:159], v[180:183], v[36:39]
	v_mfma_f32_16x16x32_bf16 v[24:27], v[148:151], v[188:191], v[24:27]
	v_mfma_f32_16x16x32_bf16 v[20:23], v[156:159], v[188:191], v[20:23]
	v_mfma_f32_16x16x32_bf16 v[72:75], v[152:155], v[168:171], v[72:75]
	v_mfma_f32_16x16x32_bf16 v[68:71], v[160:163], v[168:171], v[68:71]
	v_mfma_f32_16x16x32_bf16 v[56:59], v[152:155], v[176:179], v[56:59]
	v_mfma_f32_16x16x32_bf16 v[52:55], v[160:163], v[176:179], v[52:55]
	v_mfma_f32_16x16x32_bf16 v[40:43], v[152:155], v[184:187], v[40:43]
	v_mfma_f32_16x16x32_bf16 v[36:39], v[160:163], v[184:187], v[36:39]
	v_mfma_f32_16x16x32_bf16 v[24:27], v[152:155], v[192:195], v[24:27]
	v_mfma_f32_16x16x32_bf16 v[20:23], v[160:163], v[192:195], v[20:23]
	s_setprio 0
	s_barrier
	s_add_i32 s8, s59, s19
	v_lshl_add_u64 v[222:223], s[42:43], 0, v[198:199]
	s_mov_b32 m0, s8
	ds_read_b128 v[132:135], v237
	ds_read_b128 v[136:139], v237 offset:1024
	ds_read_b128 v[140:143], v237 offset:2048
	ds_read_b128 v[144:147], v237 offset:3072
	global_load_lds_dwordx4 v[222:223], off
	v_lshl_add_u64 v[224:225], s[42:43], 0, v[202:203]
	s_add_i32 m0, s8, 0x2000
	s_nop 0
	global_load_lds_dwordx4 v[224:225], off
	s_barrier
	s_waitcnt lgkmcnt(0)
	s_setprio 1
	s_waitcnt lgkmcnt(0)
	v_mfma_f32_16x16x32_bf16 v[64:67], v[132:135], v[164:167], v[64:67]
	v_mfma_f32_16x16x32_bf16 v[60:63], v[140:143], v[164:167], v[60:63]
	v_mfma_f32_16x16x32_bf16 v[48:51], v[132:135], v[172:175], v[48:51]
	v_mfma_f32_16x16x32_bf16 v[44:47], v[140:143], v[172:175], v[44:47]
	v_mfma_f32_16x16x32_bf16 v[32:35], v[132:135], v[180:183], v[32:35]
	v_mfma_f32_16x16x32_bf16 v[28:31], v[140:143], v[180:183], v[28:31]
	v_mfma_f32_16x16x32_bf16 v[16:19], v[132:135], v[188:191], v[16:19]
	v_mfma_f32_16x16x32_bf16 v[2:5], v[140:143], v[188:191], v[4:7]
	v_mfma_f32_16x16x32_bf16 v[64:67], v[136:139], v[168:171], v[64:67]
	v_mfma_f32_16x16x32_bf16 v[60:63], v[144:147], v[168:171], v[60:63]
	v_mfma_f32_16x16x32_bf16 v[48:51], v[136:139], v[176:179], v[48:51]
	v_mfma_f32_16x16x32_bf16 v[44:47], v[144:147], v[176:179], v[44:47]
	v_mfma_f32_16x16x32_bf16 v[32:35], v[136:139], v[184:187], v[32:35]
	v_mfma_f32_16x16x32_bf16 v[28:31], v[144:147], v[184:187], v[28:31]
	v_mfma_f32_16x16x32_bf16 v[16:19], v[136:139], v[192:195], v[16:19]
	v_mfma_f32_16x16x32_bf16 v[2:5], v[144:147], v[192:195], v[2:5]
	s_setprio 0
	s_mov_b32 m0, s46
	v_lshl_add_u64 v[226:227], s[44:45], 0, v[196:197]
	s_barrier
	ds_read_b128 v[188:191], v235 offset:16384
	ds_read_b128 v[192:195], v235 offset:17408
	ds_read_b128 v[180:183], v235 offset:18432
	ds_read_b128 v[184:187], v235 offset:19456
	ds_read_b128 v[172:175], v235 offset:20480
	ds_read_b128 v[176:179], v235 offset:21504
	ds_read_b128 v[164:167], v235 offset:22528
	ds_read_b128 v[168:171], v235 offset:23552
	global_load_lds_dwordx4 v[226:227], off
	v_lshl_add_u64 v[228:229], s[44:45], 0, v[200:201]
	s_mov_b32 m0, s47
	v_cmp_ne_u32_e64 s[8:9], 1, v245
	global_load_lds_dwordx4 v[228:229], off
	s_barrier
	s_waitcnt lgkmcnt(0)
	s_andn2_b64 vcc, exec, s[4:5]
	s_cbranch_vccnz .LBB0_129
	s_setprio 1
	s_waitcnt lgkmcnt(0)
	v_mfma_f32_16x16x32_bf16 v[128:131], v[148:151], v[188:191], v[128:131]
	v_mfma_f32_16x16x32_bf16 v[124:127], v[156:159], v[188:191], v[124:127]
	v_mfma_f32_16x16x32_bf16 v[112:115], v[148:151], v[180:183], v[112:115]
	v_mfma_f32_16x16x32_bf16 v[108:111], v[156:159], v[180:183], v[108:111]
	v_mfma_f32_16x16x32_bf16 v[96:99], v[148:151], v[172:175], v[96:99]
	v_mfma_f32_16x16x32_bf16 v[92:95], v[156:159], v[172:175], v[92:95]
	v_mfma_f32_16x16x32_bf16 v[80:83], v[148:151], v[164:167], v[80:83]
	v_mfma_f32_16x16x32_bf16 v[76:79], v[156:159], v[164:167], v[76:79]
	v_mfma_f32_16x16x32_bf16 v[128:131], v[152:155], v[192:195], v[128:131]
	v_mfma_f32_16x16x32_bf16 v[124:127], v[160:163], v[192:195], v[124:127]
	v_mfma_f32_16x16x32_bf16 v[112:115], v[152:155], v[184:187], v[112:115]
	v_mfma_f32_16x16x32_bf16 v[108:111], v[160:163], v[184:187], v[108:111]
	v_mfma_f32_16x16x32_bf16 v[96:99], v[152:155], v[176:179], v[96:99]
	v_mfma_f32_16x16x32_bf16 v[92:95], v[160:163], v[176:179], v[92:95]
	v_mfma_f32_16x16x32_bf16 v[80:83], v[152:155], v[168:171], v[80:83]
	v_mfma_f32_16x16x32_bf16 v[76:79], v[160:163], v[168:171], v[76:79]
	s_setprio 0

.LBB0_131:
	s_add_i32 s65, 0, 0x18000
	v_add_u32_e32 v1, s65, v230
	s_barrier
	ds_read_b128 v[148:151], v1
	ds_read_b128 v[152:155], v1 offset:1024
	ds_read_b128 v[156:159], v1 offset:2048
	ds_read_b128 v[160:163], v1 offset:3072
	s_add_u32 s44, s44, 0x40000
	s_addc_u32 s45, s45, 0
	s_mov_b32 m0, s50
	v_lshl_add_u64 v[6:7], s[44:45], 0, v[196:197]
	ds_read_b128 v[164:167], v235 offset:32768
	ds_read_b128 v[168:171], v235 offset:33792
	ds_read_b128 v[172:175], v235 offset:34816
	ds_read_b128 v[176:179], v235 offset:35840
	ds_read_b128 v[180:183], v235 offset:36864
	ds_read_b128 v[184:187], v235 offset:37888
	ds_read_b128 v[188:191], v235 offset:38912
	ds_read_b128 v[192:195], v235 offset:39936
	global_load_lds_dwordx4 v[6:7], off
	v_lshl_add_u64 v[6:7], s[44:45], 0, v[200:201]
	s_mov_b32 m0, s51
	s_nop 0
	global_load_lds_dwordx4 v[6:7], off
	s_waitcnt lgkmcnt(8)
	s_barrier
	s_waitcnt lgkmcnt(0)
	s_setprio 1
	s_waitcnt lgkmcnt(0)
	v_mfma_f32_16x16x32_bf16 v[72:75], v[148:151], v[164:167], v[72:75]
	v_mfma_f32_16x16x32_bf16 v[68:71], v[156:159], v[164:167], v[68:71]
	v_mfma_f32_16x16x32_bf16 v[56:59], v[148:151], v[172:175], v[56:59]
	v_mfma_f32_16x16x32_bf16 v[52:55], v[156:159], v[172:175], v[52:55]
	v_mfma_f32_16x16x32_bf16 v[40:43], v[148:151], v[180:183], v[40:43]
	v_mfma_f32_16x16x32_bf16 v[36:39], v[156:159], v[180:183], v[36:39]
	v_mfma_f32_16x16x32_bf16 v[24:27], v[148:151], v[188:191], v[24:27]
	v_mfma_f32_16x16x32_bf16 v[20:23], v[156:159], v[188:191], v[20:23]
	v_mfma_f32_16x16x32_bf16 v[72:75], v[152:155], v[168:171], v[72:75]
	v_mfma_f32_16x16x32_bf16 v[68:71], v[160:163], v[168:171], v[68:71]
	v_mfma_f32_16x16x32_bf16 v[56:59], v[152:155], v[176:179], v[56:59]
	v_mfma_f32_16x16x32_bf16 v[52:55], v[160:163], v[176:179], v[52:55]
	v_mfma_f32_16x16x32_bf16 v[40:43], v[152:155], v[184:187], v[40:43]
	v_mfma_f32_16x16x32_bf16 v[36:39], v[160:163], v[184:187], v[36:39]
	v_mfma_f32_16x16x32_bf16 v[24:27], v[152:155], v[192:195], v[24:27]
	v_mfma_f32_16x16x32_bf16 v[20:23], v[160:163], v[192:195], v[20:23]
	s_setprio 0
	s_barrier
	s_add_i32 s44, s65, s19
	v_add_u32_e32 v1, 0x1c000, v236
	v_lshl_add_u64 v[6:7], v[222:223], 0, s[22:23]
	s_mov_b32 m0, s44
	ds_read_b128 v[132:135], v1
	ds_read_b128 v[136:139], v1 offset:1024
	ds_read_b128 v[140:143], v1 offset:2048
	ds_read_b128 v[144:147], v1 offset:3072
	global_load_lds_dwordx4 v[6:7], off
	v_lshl_add_u64 v[6:7], v[224:225], 0, s[22:23]
	s_add_i32 m0, s44, 0x2000
	s_nop 0
	global_load_lds_dwordx4 v[6:7], off
	s_barrier
	s_waitcnt lgkmcnt(0)
	s_setprio 1
	s_waitcnt lgkmcnt(0)
	v_mfma_f32_16x16x32_bf16 v[64:67], v[132:135], v[164:167], v[64:67]
	v_mfma_f32_16x16x32_bf16 v[60:63], v[140:143], v[164:167], v[60:63]
	v_mfma_f32_16x16x32_bf16 v[48:51], v[132:135], v[172:175], v[48:51]
	v_mfma_f32_16x16x32_bf16 v[44:47], v[140:143], v[172:175], v[44:47]
	v_mfma_f32_16x16x32_bf16 v[32:35], v[132:135], v[180:183], v[32:35]
	v_mfma_f32_16x16x32_bf16 v[28:31], v[140:143], v[180:183], v[28:31]
	v_mfma_f32_16x16x32_bf16 v[16:19], v[132:135], v[188:191], v[16:19]
	v_mfma_f32_16x16x32_bf16 v[2:5], v[140:143], v[188:191], v[2:5]
	v_mfma_f32_16x16x32_bf16 v[64:67], v[136:139], v[168:171], v[64:67]
	v_mfma_f32_16x16x32_bf16 v[60:63], v[144:147], v[168:171], v[60:63]
	v_mfma_f32_16x16x32_bf16 v[48:51], v[136:139], v[176:179], v[48:51]
	v_mfma_f32_16x16x32_bf16 v[44:47], v[144:147], v[176:179], v[44:47]
	v_mfma_f32_16x16x32_bf16 v[32:35], v[136:139], v[184:187], v[32:35]
	v_mfma_f32_16x16x32_bf16 v[28:31], v[144:147], v[184:187], v[28:31]
	v_mfma_f32_16x16x32_bf16 v[16:19], v[136:139], v[192:195], v[16:19]
	v_mfma_f32_16x16x32_bf16 v[4:7], v[144:147], v[192:195], v[2:5]
	s_setprio 0
	s_mov_b32 m0, s53
	s_nop 0
	v_lshl_add_u64 v[2:3], v[226:227], 0, s[22:23]
	s_barrier
	ds_read_b128 v[188:191], v235 offset:49152
	ds_read_b128 v[192:195], v235 offset:50176
	ds_read_b128 v[180:183], v235 offset:51200
	ds_read_b128 v[184:187], v235 offset:52224
	ds_read_b128 v[172:175], v235 offset:53248
	ds_read_b128 v[176:179], v235 offset:54272
	ds_read_b128 v[164:167], v235 offset:55296
	ds_read_b128 v[168:171], v235 offset:56320
	global_load_lds_dwordx4 v[2:3], off
	v_lshl_add_u64 v[2:3], v[228:229], 0, s[22:23]
	s_mov_b32 m0, s54
	s_and_b64 vcc, exec, s[8:9]
	global_load_lds_dwordx4 v[2:3], off
	s_barrier
	s_waitcnt lgkmcnt(0)
	s_cbranch_vccnz .LBB0_133
	s_setprio 1
	s_waitcnt lgkmcnt(0)
	v_mfma_f32_16x16x32_bf16 v[128:131], v[148:151], v[188:191], v[128:131]
	v_mfma_f32_16x16x32_bf16 v[124:127], v[156:159], v[188:191], v[124:127]
	v_mfma_f32_16x16x32_bf16 v[112:115], v[148:151], v[180:183], v[112:115]
	v_mfma_f32_16x16x32_bf16 v[108:111], v[156:159], v[180:183], v[108:111]
	v_mfma_f32_16x16x32_bf16 v[96:99], v[148:151], v[172:175], v[96:99]
	v_mfma_f32_16x16x32_bf16 v[92:95], v[156:159], v[172:175], v[92:95]
	v_mfma_f32_16x16x32_bf16 v[80:83], v[148:151], v[164:167], v[80:83]
	v_mfma_f32_16x16x32_bf16 v[76:79], v[156:159], v[164:167], v[76:79]
	v_mfma_f32_16x16x32_bf16 v[128:131], v[152:155], v[192:195], v[128:131]
	v_mfma_f32_16x16x32_bf16 v[124:127], v[160:163], v[192:195], v[124:127]
	v_mfma_f32_16x16x32_bf16 v[112:115], v[152:155], v[184:187], v[112:115]
	v_mfma_f32_16x16x32_bf16 v[108:111], v[160:163], v[184:187], v[108:111]
	v_mfma_f32_16x16x32_bf16 v[96:99], v[152:155], v[176:179], v[96:99]
	v_mfma_f32_16x16x32_bf16 v[92:95], v[160:163], v[176:179], v[92:95]
	v_mfma_f32_16x16x32_bf16 v[80:83], v[152:155], v[168:171], v[80:83]
	v_mfma_f32_16x16x32_bf16 v[76:79], v[160:163], v[168:171], v[76:79]
	s_setprio 0

.LBB0_391:
	ds_read_b128 v[148:151], v205
	ds_read_b128 v[152:155], v205 offset:1024
	ds_read_b128 v[156:159], v205 offset:2048
	ds_read_b128 v[160:163], v205 offset:3072
	s_add_u32 s12, s30, 0xfff80080
	s_addc_u32 s13, s31, -1
	s_cmp_eq_u32 s21, s55
	s_cselect_b32 s37, s2, s13
	s_cselect_b32 s36, s5, s12
	s_cselect_b32 s35, s17, s54
	s_cselect_b32 s34, s19, s53
	v_lshl_add_u64 v[2:3], s[30:31], 0, v[214:215]
	s_add_i32 m0, s9, 0xc000
	ds_read_b128 v[164:167], v230
	ds_read_b128 v[168:171], v230 offset:1024
	ds_read_b128 v[172:175], v230 offset:2048
	ds_read_b128 v[176:179], v230 offset:3072
	ds_read_b128 v[180:183], v230 offset:4096
	ds_read_b128 v[184:187], v230 offset:5120
	ds_read_b128 v[188:191], v230 offset:6144
	ds_read_b128 v[192:195], v230 offset:7168
	global_load_lds_dwordx4 v[2:3], off
	v_lshl_add_u64 v[2:3], s[30:31], 0, v[216:217]
	s_add_i32 m0, s9, 0xe000
	s_nop 0
	global_load_lds_dwordx4 v[2:3], off
	s_waitcnt lgkmcnt(8)
	s_barrier
	s_waitcnt lgkmcnt(0)
	s_setprio 1
	s_waitcnt lgkmcnt(0)
	v_mfma_f32_16x16x32_bf16 v[84:87], v[148:151], v[164:167], v[84:87]
	v_mfma_f32_16x16x32_bf16 v[76:79], v[156:159], v[164:167], v[76:79]
	v_mfma_f32_16x16x32_bf16 v[64:67], v[148:151], v[172:175], v[64:67]
	v_mfma_f32_16x16x32_bf16 v[60:63], v[156:159], v[172:175], v[60:63]
	v_mfma_f32_16x16x32_bf16 v[48:51], v[148:151], v[180:183], v[48:51]
	v_mfma_f32_16x16x32_bf16 v[44:47], v[156:159], v[180:183], v[44:47]
	v_mfma_f32_16x16x32_bf16 v[32:35], v[148:151], v[188:191], v[32:35]
	v_mfma_f32_16x16x32_bf16 v[24:27], v[156:159], v[188:191], v[24:27]
	v_mfma_f32_16x16x32_bf16 v[84:87], v[152:155], v[168:171], v[84:87]
	v_mfma_f32_16x16x32_bf16 v[76:79], v[160:163], v[168:171], v[76:79]
	v_mfma_f32_16x16x32_bf16 v[64:67], v[152:155], v[176:179], v[64:67]
	v_mfma_f32_16x16x32_bf16 v[60:63], v[160:163], v[176:179], v[60:63]
	v_mfma_f32_16x16x32_bf16 v[48:51], v[152:155], v[184:187], v[48:51]
	v_mfma_f32_16x16x32_bf16 v[44:47], v[160:163], v[184:187], v[44:47]
	v_mfma_f32_16x16x32_bf16 v[32:35], v[152:155], v[192:195], v[32:35]
	v_mfma_f32_16x16x32_bf16 v[24:27], v[160:163], v[192:195], v[24:27]
	s_setprio 0
	s_barrier
	s_add_i32 s12, s51, s38
	v_lshl_add_u64 v[2:3], s[34:35], 0, v[198:199]
	s_mov_b32 m0, s12
	ds_read_b128 v[132:135], v232
	ds_read_b128 v[136:139], v232 offset:1024
	ds_read_b128 v[140:143], v232 offset:2048
	ds_read_b128 v[144:147], v232 offset:3072
	global_load_lds_dwordx4 v[2:3], off
	v_lshl_add_u64 v[220:221], s[34:35], 0, v[202:203]
	s_add_i32 m0, s12, 0x2000
	s_nop 0
	global_load_lds_dwordx4 v[220:221], off
	s_barrier
	s_waitcnt lgkmcnt(0)
	s_setprio 1
	s_waitcnt lgkmcnt(0)
	v_mfma_f32_16x16x32_bf16 v[72:75], v[132:135], v[164:167], v[72:75]
	v_mfma_f32_16x16x32_bf16 v[68:71], v[140:143], v[164:167], v[68:71]
	v_mfma_f32_16x16x32_bf16 v[56:59], v[132:135], v[172:175], v[56:59]
	v_mfma_f32_16x16x32_bf16 v[52:55], v[140:143], v[172:175], v[52:55]
	v_mfma_f32_16x16x32_bf16 v[40:43], v[132:135], v[180:183], v[40:43]
	v_mfma_f32_16x16x32_bf16 v[36:39], v[140:143], v[180:183], v[36:39]
	v_mfma_f32_16x16x32_bf16 v[20:23], v[132:135], v[188:191], v[20:23]
	v_mfma_f32_16x16x32_bf16 v[12:15], v[140:143], v[188:191], v[12:15]
	v_mfma_f32_16x16x32_bf16 v[72:75], v[136:139], v[168:171], v[72:75]
	v_mfma_f32_16x16x32_bf16 v[68:71], v[144:147], v[168:171], v[68:71]
	v_mfma_f32_16x16x32_bf16 v[56:59], v[136:139], v[176:179], v[56:59]
	v_mfma_f32_16x16x32_bf16 v[52:55], v[144:147], v[176:179], v[52:55]
	v_mfma_f32_16x16x32_bf16 v[40:43], v[136:139], v[184:187], v[40:43]
	v_mfma_f32_16x16x32_bf16 v[36:39], v[144:147], v[184:187], v[36:39]
	v_mfma_f32_16x16x32_bf16 v[20:23], v[136:139], v[192:195], v[20:23]
	v_mfma_f32_16x16x32_bf16 v[12:15], v[144:147], v[192:195], v[12:15]
	s_setprio 0
	s_mov_b32 m0, s9
	v_lshl_add_u64 v[222:223], s[36:37], 0, v[196:197]
	s_barrier
	ds_read_b128 v[188:191], v230 offset:16384
	ds_read_b128 v[192:195], v230 offset:17408
	ds_read_b128 v[180:183], v230 offset:18432
	ds_read_b128 v[184:187], v230 offset:19456
	ds_read_b128 v[172:175], v230 offset:20480
	ds_read_b128 v[176:179], v230 offset:21504
	ds_read_b128 v[164:167], v230 offset:22528
	ds_read_b128 v[168:171], v230 offset:23552
	global_load_lds_dwordx4 v[222:223], off
	v_lshl_add_u64 v[224:225], s[36:37], 0, v[200:201]
	s_mov_b32 m0, s39
	v_cmp_ne_u32_e64 s[12:13], 1, v233
	global_load_lds_dwordx4 v[224:225], off
	s_barrier
	s_waitcnt lgkmcnt(0)
	s_andn2_b64 vcc, exec, s[28:29]
	s_cbranch_vccnz .LBB0_393
	s_setprio 1
	s_waitcnt lgkmcnt(0)
	v_mfma_f32_16x16x32_bf16 v[128:131], v[148:151], v[188:191], v[128:131]
	v_mfma_f32_16x16x32_bf16 v[124:127], v[156:159], v[188:191], v[124:127]
	v_mfma_f32_16x16x32_bf16 v[112:115], v[148:151], v[180:183], v[112:115]
	v_mfma_f32_16x16x32_bf16 v[108:111], v[156:159], v[180:183], v[108:111]
	v_mfma_f32_16x16x32_bf16 v[96:99], v[148:151], v[172:175], v[96:99]
	v_mfma_f32_16x16x32_bf16 v[92:95], v[156:159], v[172:175], v[92:95]
	v_mfma_f32_16x16x32_bf16 v[28:31], v[148:151], v[164:167], v[28:31]
	v_mfma_f32_16x16x32_bf16 v[16:19], v[156:159], v[164:167], v[16:19]
	v_mfma_f32_16x16x32_bf16 v[128:131], v[152:155], v[192:195], v[128:131]
	v_mfma_f32_16x16x32_bf16 v[124:127], v[160:163], v[192:195], v[124:127]
	v_mfma_f32_16x16x32_bf16 v[112:115], v[152:155], v[184:187], v[112:115]
	v_mfma_f32_16x16x32_bf16 v[108:111], v[160:163], v[184:187], v[108:111]
	v_mfma_f32_16x16x32_bf16 v[96:99], v[152:155], v[176:179], v[96:99]
	v_mfma_f32_16x16x32_bf16 v[92:95], v[160:163], v[176:179], v[92:95]
	v_mfma_f32_16x16x32_bf16 v[28:31], v[152:155], v[168:171], v[28:31]
	v_mfma_f32_16x16x32_bf16 v[16:19], v[160:163], v[168:171], v[16:19]
	s_setprio 0

.LBB0_395:
	s_add_i32 s56, 0, 0x18000
	v_add_u32_e32 v1, s56, v226
	s_barrier
	ds_read_b128 v[148:151], v1
	ds_read_b128 v[152:155], v1 offset:1024
	ds_read_b128 v[156:159], v1 offset:2048
	ds_read_b128 v[160:163], v1 offset:3072
	s_add_u32 s36, s36, 0x80000
	s_addc_u32 s37, s37, 0
	s_mov_b32 m0, s42
	v_lshl_add_u64 v[132:133], s[36:37], 0, v[196:197]
	ds_read_b128 v[164:167], v230 offset:32768
	ds_read_b128 v[168:171], v230 offset:33792
	ds_read_b128 v[172:175], v230 offset:34816
	ds_read_b128 v[176:179], v230 offset:35840
	ds_read_b128 v[180:183], v230 offset:36864
	ds_read_b128 v[184:187], v230 offset:37888
	ds_read_b128 v[188:191], v230 offset:38912
	ds_read_b128 v[192:195], v230 offset:39936
	global_load_lds_dwordx4 v[132:133], off
	v_lshl_add_u64 v[132:133], s[36:37], 0, v[200:201]
	s_mov_b32 m0, s43
	s_nop 0
	global_load_lds_dwordx4 v[132:133], off
	s_waitcnt lgkmcnt(8)
	s_barrier
	s_waitcnt lgkmcnt(0)
	s_setprio 1
	s_waitcnt lgkmcnt(0)
	v_mfma_f32_16x16x32_bf16 v[84:87], v[148:151], v[164:167], v[84:87]
	v_mfma_f32_16x16x32_bf16 v[76:79], v[156:159], v[164:167], v[76:79]
	v_mfma_f32_16x16x32_bf16 v[64:67], v[148:151], v[172:175], v[64:67]
	v_mfma_f32_16x16x32_bf16 v[60:63], v[156:159], v[172:175], v[60:63]
	v_mfma_f32_16x16x32_bf16 v[48:51], v[148:151], v[180:183], v[48:51]
	v_mfma_f32_16x16x32_bf16 v[44:47], v[156:159], v[180:183], v[44:47]
	v_mfma_f32_16x16x32_bf16 v[32:35], v[148:151], v[188:191], v[32:35]
	v_mfma_f32_16x16x32_bf16 v[24:27], v[156:159], v[188:191], v[24:27]
	v_mfma_f32_16x16x32_bf16 v[84:87], v[152:155], v[168:171], v[84:87]
	v_mfma_f32_16x16x32_bf16 v[76:79], v[160:163], v[168:171], v[76:79]
	v_mfma_f32_16x16x32_bf16 v[64:67], v[152:155], v[176:179], v[64:67]
	v_mfma_f32_16x16x32_bf16 v[60:63], v[160:163], v[176:179], v[60:63]
	v_mfma_f32_16x16x32_bf16 v[48:51], v[152:155], v[184:187], v[48:51]
	v_mfma_f32_16x16x32_bf16 v[44:47], v[160:163], v[184:187], v[44:47]
	v_mfma_f32_16x16x32_bf16 v[32:35], v[152:155], v[192:195], v[32:35]
	v_mfma_f32_16x16x32_bf16 v[24:27], v[160:163], v[192:195], v[24:27]
	s_setprio 0
	s_barrier
	s_add_i32 s36, s56, s38
	v_add_u32_e32 v1, 0x1c000, v231
	v_lshl_add_u64 v[2:3], v[2:3], 0, s[14:15]
	s_mov_b32 m0, s36
	ds_read_b128 v[132:135], v1
	ds_read_b128 v[136:139], v1 offset:1024
	ds_read_b128 v[140:143], v1 offset:2048
	ds_read_b128 v[144:147], v1 offset:3072
	global_load_lds_dwordx4 v[2:3], off
	v_lshl_add_u64 v[2:3], v[220:221], 0, s[14:15]
	s_add_i32 m0, s36, 0x2000
	s_nop 0
	global_load_lds_dwordx4 v[2:3], off
	s_barrier
	s_waitcnt lgkmcnt(0)
	s_setprio 1
	s_waitcnt lgkmcnt(0)
	v_mfma_f32_16x16x32_bf16 v[72:75], v[132:135], v[164:167], v[72:75]
	v_mfma_f32_16x16x32_bf16 v[68:71], v[140:143], v[164:167], v[68:71]
	v_mfma_f32_16x16x32_bf16 v[56:59], v[132:135], v[172:175], v[56:59]
	v_mfma_f32_16x16x32_bf16 v[52:55], v[140:143], v[172:175], v[52:55]
	v_mfma_f32_16x16x32_bf16 v[40:43], v[132:135], v[180:183], v[40:43]
	v_mfma_f32_16x16x32_bf16 v[36:39], v[140:143], v[180:183], v[36:39]
	v_mfma_f32_16x16x32_bf16 v[20:23], v[132:135], v[188:191], v[20:23]
	v_mfma_f32_16x16x32_bf16 v[12:15], v[140:143], v[188:191], v[12:15]
	v_mfma_f32_16x16x32_bf16 v[72:75], v[136:139], v[168:171], v[72:75]
	v_mfma_f32_16x16x32_bf16 v[68:71], v[144:147], v[168:171], v[68:71]
	v_mfma_f32_16x16x32_bf16 v[56:59], v[136:139], v[176:179], v[56:59]
	v_mfma_f32_16x16x32_bf16 v[52:55], v[144:147], v[176:179], v[52:55]
	v_mfma_f32_16x16x32_bf16 v[40:43], v[136:139], v[184:187], v[40:43]
	v_mfma_f32_16x16x32_bf16 v[36:39], v[144:147], v[184:187], v[36:39]
	v_mfma_f32_16x16x32_bf16 v[20:23], v[136:139], v[192:195], v[20:23]
	v_mfma_f32_16x16x32_bf16 v[12:15], v[144:147], v[192:195], v[12:15]
	s_setprio 0
	s_mov_b32 m0, s45
	v_lshl_add_u64 v[2:3], v[222:223], 0, s[14:15]
	s_barrier
	ds_read_b128 v[188:191], v230 offset:49152
	ds_read_b128 v[192:195], v230 offset:50176
	ds_read_b128 v[180:183], v230 offset:51200
	ds_read_b128 v[184:187], v230 offset:52224
	ds_read_b128 v[172:175], v230 offset:53248
	ds_read_b128 v[176:179], v230 offset:54272
	ds_read_b128 v[164:167], v230 offset:55296
	ds_read_b128 v[168:171], v230 offset:56320
	global_load_lds_dwordx4 v[2:3], off
	v_lshl_add_u64 v[2:3], v[224:225], 0, s[14:15]
	s_mov_b32 m0, s46
	s_and_b64 vcc, exec, s[12:13]
	global_load_lds_dwordx4 v[2:3], off
	s_barrier
	s_waitcnt lgkmcnt(0)
	s_cbranch_vccnz .LBB0_397
	s_setprio 1
	s_waitcnt lgkmcnt(0)
	v_mfma_f32_16x16x32_bf16 v[128:131], v[148:151], v[188:191], v[128:131]
	v_mfma_f32_16x16x32_bf16 v[124:127], v[156:159], v[188:191], v[124:127]
	v_mfma_f32_16x16x32_bf16 v[112:115], v[148:151], v[180:183], v[112:115]
	v_mfma_f32_16x16x32_bf16 v[108:111], v[156:159], v[180:183], v[108:111]
	v_mfma_f32_16x16x32_bf16 v[96:99], v[148:151], v[172:175], v[96:99]
	v_mfma_f32_16x16x32_bf16 v[92:95], v[156:159], v[172:175], v[92:95]
	v_mfma_f32_16x16x32_bf16 v[28:31], v[148:151], v[164:167], v[28:31]
	v_mfma_f32_16x16x32_bf16 v[16:19], v[156:159], v[164:167], v[16:19]
	v_mfma_f32_16x16x32_bf16 v[128:131], v[152:155], v[192:195], v[128:131]
	v_mfma_f32_16x16x32_bf16 v[124:127], v[160:163], v[192:195], v[124:127]
	v_mfma_f32_16x16x32_bf16 v[112:115], v[152:155], v[184:187], v[112:115]
	v_mfma_f32_16x16x32_bf16 v[108:111], v[160:163], v[184:187], v[108:111]
	v_mfma_f32_16x16x32_bf16 v[96:99], v[152:155], v[176:179], v[96:99]
	v_mfma_f32_16x16x32_bf16 v[92:95], v[160:163], v[176:179], v[92:95]
	v_mfma_f32_16x16x32_bf16 v[28:31], v[152:155], v[168:171], v[28:31]
	v_mfma_f32_16x16x32_bf16 v[16:19], v[160:163], v[168:171], v[16:19]
	s_setprio 0

.LBB0_573:
	ds_read_b128 v[148:151], v222
	ds_read_b128 v[152:155], v222 offset:1024
	ds_read_b128 v[156:159], v222 offset:2048
	ds_read_b128 v[160:163], v222 offset:3072
	s_add_u32 s14, s26, 0xfffc0080
	s_addc_u32 s15, s27, -1
	s_cmp_eq_u32 s50, s53
	s_cselect_b32 s31, s2, s15
	s_cselect_b32 s30, s9, s14
	s_cselect_b32 s29, s11, s52
	s_cselect_b32 s28, s21, s51
	v_lshl_add_u64 v[2:3], s[26:27], 0, v[204:205]
	s_add_i32 m0, s34, 0xc000
	ds_read_b128 v[164:167], v223
	ds_read_b128 v[168:171], v223 offset:1024
	ds_read_b128 v[172:175], v223 offset:2048
	ds_read_b128 v[176:179], v223 offset:3072
	ds_read_b128 v[180:183], v223 offset:4096
	ds_read_b128 v[184:187], v223 offset:5120
	ds_read_b128 v[188:191], v223 offset:6144
	ds_read_b128 v[192:195], v223 offset:7168
	global_load_lds_dwordx4 v[2:3], off
	v_lshl_add_u64 v[2:3], s[26:27], 0, v[206:207]
	s_add_i32 m0, s34, 0xe000
	s_nop 0
	global_load_lds_dwordx4 v[2:3], off
	s_waitcnt lgkmcnt(8)
	s_barrier
	s_waitcnt lgkmcnt(0)
	s_setprio 1
	s_waitcnt lgkmcnt(0)
	v_mfma_f32_16x16x32_bf16 v[124:127], v[148:151], v[164:167], v[124:127]
	v_mfma_f32_16x16x32_bf16 v[116:119], v[156:159], v[164:167], v[116:119]
	v_mfma_f32_16x16x32_bf16 v[108:111], v[148:151], v[172:175], v[108:111]
	v_mfma_f32_16x16x32_bf16 v[100:103], v[156:159], v[172:175], v[100:103]
	v_mfma_f32_16x16x32_bf16 v[92:95], v[148:151], v[180:183], v[92:95]
	v_mfma_f32_16x16x32_bf16 v[84:87], v[156:159], v[180:183], v[84:87]
	v_mfma_f32_16x16x32_bf16 v[76:79], v[148:151], v[188:191], v[76:79]
	v_mfma_f32_16x16x32_bf16 v[72:75], v[156:159], v[188:191], v[72:75]
	v_mfma_f32_16x16x32_bf16 v[124:127], v[152:155], v[168:171], v[124:127]
	v_mfma_f32_16x16x32_bf16 v[116:119], v[160:163], v[168:171], v[116:119]
	v_mfma_f32_16x16x32_bf16 v[108:111], v[152:155], v[176:179], v[108:111]
	v_mfma_f32_16x16x32_bf16 v[100:103], v[160:163], v[176:179], v[100:103]
	v_mfma_f32_16x16x32_bf16 v[92:95], v[152:155], v[184:187], v[92:95]
	v_mfma_f32_16x16x32_bf16 v[84:87], v[160:163], v[184:187], v[84:87]
	v_mfma_f32_16x16x32_bf16 v[76:79], v[152:155], v[192:195], v[76:79]
	v_mfma_f32_16x16x32_bf16 v[72:75], v[160:163], v[192:195], v[72:75]
	s_setprio 0
	s_barrier
	s_add_i32 s14, s47, s23
	v_lshl_add_u64 v[2:3], s[28:29], 0, v[198:199]
	s_mov_b32 m0, s14
	ds_read_b128 v[132:135], v225
	ds_read_b128 v[136:139], v225 offset:1024
	ds_read_b128 v[140:143], v225 offset:2048
	ds_read_b128 v[144:147], v225 offset:3072
	global_load_lds_dwordx4 v[2:3], off
	v_lshl_add_u64 v[212:213], s[28:29], 0, v[202:203]
	s_add_i32 m0, s14, 0x2000
	s_nop 0
	global_load_lds_dwordx4 v[212:213], off
	s_barrier
	s_waitcnt lgkmcnt(0)
	s_setprio 1
	s_waitcnt lgkmcnt(0)
	v_mfma_f32_16x16x32_bf16 v[128:131], v[132:135], v[164:167], v[128:131]
	v_mfma_f32_16x16x32_bf16 v[120:123], v[140:143], v[164:167], v[120:123]
	v_mfma_f32_16x16x32_bf16 v[112:115], v[132:135], v[172:175], v[112:115]
	v_mfma_f32_16x16x32_bf16 v[104:107], v[140:143], v[172:175], v[104:107]
	v_mfma_f32_16x16x32_bf16 v[96:99], v[132:135], v[180:183], v[96:99]
	v_mfma_f32_16x16x32_bf16 v[88:91], v[140:143], v[180:183], v[88:91]
	v_mfma_f32_16x16x32_bf16 v[80:83], v[132:135], v[188:191], v[80:83]
	v_mfma_f32_16x16x32_bf16 v[68:71], v[140:143], v[188:191], v[68:71]
	v_mfma_f32_16x16x32_bf16 v[128:131], v[136:139], v[168:171], v[128:131]
	v_mfma_f32_16x16x32_bf16 v[120:123], v[144:147], v[168:171], v[120:123]
	v_mfma_f32_16x16x32_bf16 v[112:115], v[136:139], v[176:179], v[112:115]
	v_mfma_f32_16x16x32_bf16 v[104:107], v[144:147], v[176:179], v[104:107]
	v_mfma_f32_16x16x32_bf16 v[96:99], v[136:139], v[184:187], v[96:99]
	v_mfma_f32_16x16x32_bf16 v[88:91], v[144:147], v[184:187], v[88:91]
	v_mfma_f32_16x16x32_bf16 v[80:83], v[136:139], v[192:195], v[80:83]
	v_mfma_f32_16x16x32_bf16 v[68:71], v[144:147], v[192:195], v[68:71]
	s_setprio 0
	s_mov_b32 m0, s34
	v_lshl_add_u64 v[214:215], s[30:31], 0, v[196:197]
	s_barrier
	ds_read_b128 v[188:191], v223 offset:16384
	ds_read_b128 v[192:195], v223 offset:17408
	ds_read_b128 v[180:183], v223 offset:18432
	ds_read_b128 v[184:187], v223 offset:19456
	ds_read_b128 v[172:175], v223 offset:20480
	ds_read_b128 v[176:179], v223 offset:21504
	ds_read_b128 v[164:167], v223 offset:22528
	ds_read_b128 v[168:171], v223 offset:23552
	global_load_lds_dwordx4 v[214:215], off
	v_lshl_add_u64 v[216:217], s[30:31], 0, v[200:201]
	s_mov_b32 m0, s35
	v_cmp_ne_u32_e64 s[14:15], 1, v234
	global_load_lds_dwordx4 v[216:217], off
	s_barrier
	s_waitcnt lgkmcnt(0)
	s_andn2_b64 vcc, exec, s[24:25]
	s_cbranch_vccnz .LBB0_575
	s_setprio 1
	s_waitcnt lgkmcnt(0)
	v_mfma_f32_16x16x32_bf16 v[60:63], v[148:151], v[188:191], v[60:63]
	v_mfma_f32_16x16x32_bf16 v[52:55], v[156:159], v[188:191], v[52:55]
	v_mfma_f32_16x16x32_bf16 v[44:47], v[148:151], v[180:183], v[44:47]
	v_mfma_f32_16x16x32_bf16 v[36:39], v[156:159], v[180:183], v[36:39]
	v_mfma_f32_16x16x32_bf16 v[28:31], v[148:151], v[172:175], v[28:31]
	v_mfma_f32_16x16x32_bf16 v[20:23], v[156:159], v[172:175], v[20:23]
	v_mfma_f32_16x16x32_bf16 v[12:15], v[148:151], v[164:167], v[12:15]
	v_mfma_f32_16x16x32_bf16 v[4:7], v[156:159], v[164:167], v[4:7]
	v_mfma_f32_16x16x32_bf16 v[60:63], v[152:155], v[192:195], v[60:63]
	v_mfma_f32_16x16x32_bf16 v[52:55], v[160:163], v[192:195], v[52:55]
	v_mfma_f32_16x16x32_bf16 v[44:47], v[152:155], v[184:187], v[44:47]
	v_mfma_f32_16x16x32_bf16 v[36:39], v[160:163], v[184:187], v[36:39]
	v_mfma_f32_16x16x32_bf16 v[28:31], v[152:155], v[176:179], v[28:31]
	v_mfma_f32_16x16x32_bf16 v[20:23], v[160:163], v[176:179], v[20:23]
	v_mfma_f32_16x16x32_bf16 v[12:15], v[152:155], v[168:171], v[12:15]
	v_mfma_f32_16x16x32_bf16 v[4:7], v[160:163], v[168:171], v[4:7]
	s_setprio 0

.LBB0_577:
	s_add_i32 s54, 0, 0x18000
	v_add_u32_e32 v1, s54, v220
	s_barrier
	ds_read_b128 v[148:151], v1
	ds_read_b128 v[152:155], v1 offset:1024
	ds_read_b128 v[156:159], v1 offset:2048
	ds_read_b128 v[160:163], v1 offset:3072
	s_add_u32 s30, s30, 0x40000
	s_addc_u32 s31, s31, 0
	s_mov_b32 m0, s38
	v_lshl_add_u64 v[132:133], s[30:31], 0, v[196:197]
	ds_read_b128 v[164:167], v223 offset:32768
	ds_read_b128 v[168:171], v223 offset:33792
	ds_read_b128 v[172:175], v223 offset:34816
	ds_read_b128 v[176:179], v223 offset:35840
	ds_read_b128 v[180:183], v223 offset:36864
	ds_read_b128 v[184:187], v223 offset:37888
	ds_read_b128 v[188:191], v223 offset:38912
	ds_read_b128 v[192:195], v223 offset:39936
	global_load_lds_dwordx4 v[132:133], off
	v_lshl_add_u64 v[132:133], s[30:31], 0, v[200:201]
	s_mov_b32 m0, s39
	s_nop 0
	global_load_lds_dwordx4 v[132:133], off
	s_waitcnt lgkmcnt(8)
	s_barrier
	s_waitcnt lgkmcnt(0)
	s_setprio 1
	s_waitcnt lgkmcnt(0)
	v_mfma_f32_16x16x32_bf16 v[124:127], v[148:151], v[164:167], v[124:127]
	v_mfma_f32_16x16x32_bf16 v[116:119], v[156:159], v[164:167], v[116:119]
	v_mfma_f32_16x16x32_bf16 v[108:111], v[148:151], v[172:175], v[108:111]
	v_mfma_f32_16x16x32_bf16 v[100:103], v[156:159], v[172:175], v[100:103]
	v_mfma_f32_16x16x32_bf16 v[92:95], v[148:151], v[180:183], v[92:95]
	v_mfma_f32_16x16x32_bf16 v[84:87], v[156:159], v[180:183], v[84:87]
	v_mfma_f32_16x16x32_bf16 v[76:79], v[148:151], v[188:191], v[76:79]
	v_mfma_f32_16x16x32_bf16 v[72:75], v[156:159], v[188:191], v[72:75]
	v_mfma_f32_16x16x32_bf16 v[124:127], v[152:155], v[168:171], v[124:127]
	v_mfma_f32_16x16x32_bf16 v[116:119], v[160:163], v[168:171], v[116:119]
	v_mfma_f32_16x16x32_bf16 v[108:111], v[152:155], v[176:179], v[108:111]
	v_mfma_f32_16x16x32_bf16 v[100:103], v[160:163], v[176:179], v[100:103]
	v_mfma_f32_16x16x32_bf16 v[92:95], v[152:155], v[184:187], v[92:95]
	v_mfma_f32_16x16x32_bf16 v[84:87], v[160:163], v[184:187], v[84:87]
	v_mfma_f32_16x16x32_bf16 v[76:79], v[152:155], v[192:195], v[76:79]
	v_mfma_f32_16x16x32_bf16 v[72:75], v[160:163], v[192:195], v[72:75]
	s_setprio 0
	s_barrier
	s_add_i32 s30, s54, s23
	v_add_u32_e32 v1, 0x1c000, v224
	v_lshl_add_u64 v[2:3], v[2:3], 0, s[6:7]
	s_mov_b32 m0, s30
	ds_read_b128 v[132:135], v1
	ds_read_b128 v[136:139], v1 offset:1024
	ds_read_b128 v[140:143], v1 offset:2048
	ds_read_b128 v[144:147], v1 offset:3072
	global_load_lds_dwordx4 v[2:3], off
	v_lshl_add_u64 v[2:3], v[212:213], 0, s[6:7]
	s_add_i32 m0, s30, 0x2000
	s_nop 0
	global_load_lds_dwordx4 v[2:3], off
	s_barrier
	s_waitcnt lgkmcnt(0)
	s_setprio 1
	s_waitcnt lgkmcnt(0)
	v_mfma_f32_16x16x32_bf16 v[128:131], v[132:135], v[164:167], v[128:131]
	v_mfma_f32_16x16x32_bf16 v[120:123], v[140:143], v[164:167], v[120:123]
	v_mfma_f32_16x16x32_bf16 v[112:115], v[132:135], v[172:175], v[112:115]
	v_mfma_f32_16x16x32_bf16 v[104:107], v[140:143], v[172:175], v[104:107]
	v_mfma_f32_16x16x32_bf16 v[96:99], v[132:135], v[180:183], v[96:99]
	v_mfma_f32_16x16x32_bf16 v[88:91], v[140:143], v[180:183], v[88:91]
	v_mfma_f32_16x16x32_bf16 v[80:83], v[132:135], v[188:191], v[80:83]
	v_mfma_f32_16x16x32_bf16 v[68:71], v[140:143], v[188:191], v[68:71]
	v_mfma_f32_16x16x32_bf16 v[128:131], v[136:139], v[168:171], v[128:131]
	v_mfma_f32_16x16x32_bf16 v[120:123], v[144:147], v[168:171], v[120:123]
	v_mfma_f32_16x16x32_bf16 v[112:115], v[136:139], v[176:179], v[112:115]
	v_mfma_f32_16x16x32_bf16 v[104:107], v[144:147], v[176:179], v[104:107]
	v_mfma_f32_16x16x32_bf16 v[96:99], v[136:139], v[184:187], v[96:99]
	v_mfma_f32_16x16x32_bf16 v[88:91], v[144:147], v[184:187], v[88:91]
	v_mfma_f32_16x16x32_bf16 v[80:83], v[136:139], v[192:195], v[80:83]
	v_mfma_f32_16x16x32_bf16 v[68:71], v[144:147], v[192:195], v[68:71]
	s_setprio 0
	s_mov_b32 m0, s41
	v_lshl_add_u64 v[2:3], v[214:215], 0, s[6:7]
	s_barrier
	ds_read_b128 v[188:191], v223 offset:49152
	ds_read_b128 v[192:195], v223 offset:50176
	ds_read_b128 v[180:183], v223 offset:51200
	ds_read_b128 v[184:187], v223 offset:52224
	ds_read_b128 v[172:175], v223 offset:53248
	ds_read_b128 v[176:179], v223 offset:54272
	ds_read_b128 v[164:167], v223 offset:55296
	ds_read_b128 v[168:171], v223 offset:56320
	global_load_lds_dwordx4 v[2:3], off
	v_lshl_add_u64 v[2:3], v[216:217], 0, s[6:7]
	s_mov_b32 m0, s42
	s_and_b64 vcc, exec, s[14:15]
	global_load_lds_dwordx4 v[2:3], off
	s_barrier
	s_waitcnt lgkmcnt(0)
	s_cbranch_vccnz .LBB0_579
	s_setprio 1
	s_waitcnt lgkmcnt(0)
	v_mfma_f32_16x16x32_bf16 v[60:63], v[148:151], v[188:191], v[60:63]
	v_mfma_f32_16x16x32_bf16 v[52:55], v[156:159], v[188:191], v[52:55]
	v_mfma_f32_16x16x32_bf16 v[44:47], v[148:151], v[180:183], v[44:47]
	v_mfma_f32_16x16x32_bf16 v[36:39], v[156:159], v[180:183], v[36:39]
	v_mfma_f32_16x16x32_bf16 v[28:31], v[148:151], v[172:175], v[28:31]
	v_mfma_f32_16x16x32_bf16 v[20:23], v[156:159], v[172:175], v[20:23]
	v_mfma_f32_16x16x32_bf16 v[12:15], v[148:151], v[164:167], v[12:15]
	v_mfma_f32_16x16x32_bf16 v[2:5], v[156:159], v[164:167], v[4:7]
	v_mfma_f32_16x16x32_bf16 v[60:63], v[152:155], v[192:195], v[60:63]
	v_mfma_f32_16x16x32_bf16 v[52:55], v[160:163], v[192:195], v[52:55]
	v_mfma_f32_16x16x32_bf16 v[44:47], v[152:155], v[184:187], v[44:47]
	v_mfma_f32_16x16x32_bf16 v[36:39], v[160:163], v[184:187], v[36:39]
	v_mfma_f32_16x16x32_bf16 v[28:31], v[152:155], v[176:179], v[28:31]
	v_mfma_f32_16x16x32_bf16 v[20:23], v[160:163], v[176:179], v[20:23]
	v_mfma_f32_16x16x32_bf16 v[12:15], v[152:155], v[168:171], v[12:15]
	v_mfma_f32_16x16x32_bf16 v[4:7], v[160:163], v[168:171], v[2:5]
	s_setprio 0

.LBB0_688:
	ds_read_b128 v[148:151], v205
	ds_read_b128 v[152:155], v205 offset:1024
	ds_read_b128 v[156:159], v205 offset:2048
	ds_read_b128 v[160:163], v205 offset:3072
	s_mov_b64 s[16:17], s[22:23]
	s_add_u32 s22, s16, 0x100
	s_addc_u32 s23, s17, 0
	s_cmp_eq_u32 s5, s51
	s_cselect_b32 s29, s19, s23
	s_cselect_b32 s28, s18, s22
	s_cselect_b32 s27, s21, s11
	s_cselect_b32 s26, s20, s6
	v_lshl_add_u64 v[2:3], s[16:17], 0, v[214:215]
	s_add_i32 m0, s34, 0xc000
	ds_read_b128 v[164:167], v230
	ds_read_b128 v[168:171], v230 offset:1024
	ds_read_b128 v[172:175], v230 offset:2048
	ds_read_b128 v[176:179], v230 offset:3072
	ds_read_b128 v[180:183], v230 offset:4096
	ds_read_b128 v[184:187], v230 offset:5120
	ds_read_b128 v[188:191], v230 offset:6144
	ds_read_b128 v[192:195], v230 offset:7168
	global_load_lds_dwordx4 v[2:3], off
	v_lshl_add_u64 v[2:3], s[16:17], 0, v[216:217]
	s_add_i32 m0, s34, 0xe000
	s_nop 0
	global_load_lds_dwordx4 v[2:3], off
	s_waitcnt lgkmcnt(8)
	s_barrier
	s_waitcnt lgkmcnt(0)
	s_setprio 1
	s_waitcnt lgkmcnt(0)
	v_mfma_f32_16x16x32_bf16 v[84:87], v[148:151], v[164:167], v[84:87]
	v_mfma_f32_16x16x32_bf16 v[76:79], v[156:159], v[164:167], v[76:79]
	v_mfma_f32_16x16x32_bf16 v[64:67], v[148:151], v[172:175], v[64:67]
	v_mfma_f32_16x16x32_bf16 v[60:63], v[156:159], v[172:175], v[60:63]
	v_mfma_f32_16x16x32_bf16 v[48:51], v[148:151], v[180:183], v[48:51]
	v_mfma_f32_16x16x32_bf16 v[44:47], v[156:159], v[180:183], v[44:47]
	v_mfma_f32_16x16x32_bf16 v[32:35], v[148:151], v[188:191], v[32:35]
	v_mfma_f32_16x16x32_bf16 v[24:27], v[156:159], v[188:191], v[24:27]
	v_mfma_f32_16x16x32_bf16 v[84:87], v[152:155], v[168:171], v[84:87]
	v_mfma_f32_16x16x32_bf16 v[76:79], v[160:163], v[168:171], v[76:79]
	v_mfma_f32_16x16x32_bf16 v[64:67], v[152:155], v[176:179], v[64:67]
	v_mfma_f32_16x16x32_bf16 v[60:63], v[160:163], v[176:179], v[60:63]
	v_mfma_f32_16x16x32_bf16 v[48:51], v[152:155], v[184:187], v[48:51]
	v_mfma_f32_16x16x32_bf16 v[44:47], v[160:163], v[184:187], v[44:47]
	v_mfma_f32_16x16x32_bf16 v[32:35], v[152:155], v[192:195], v[32:35]
	v_mfma_f32_16x16x32_bf16 v[24:27], v[160:163], v[192:195], v[24:27]
	s_setprio 0
	s_barrier
	s_add_i32 s16, s47, s30
	v_lshl_add_u64 v[2:3], s[26:27], 0, v[198:199]
	s_mov_b32 m0, s16
	ds_read_b128 v[132:135], v232
	ds_read_b128 v[136:139], v232 offset:1024
	ds_read_b128 v[140:143], v232 offset:2048
	ds_read_b128 v[144:147], v232 offset:3072
	global_load_lds_dwordx4 v[2:3], off
	v_lshl_add_u64 v[220:221], s[26:27], 0, v[202:203]
	s_add_i32 m0, s16, 0x2000
	s_nop 0
	global_load_lds_dwordx4 v[220:221], off
	s_barrier
	s_waitcnt lgkmcnt(0)
	s_setprio 1
	s_waitcnt lgkmcnt(0)
	v_mfma_f32_16x16x32_bf16 v[72:75], v[132:135], v[164:167], v[72:75]
	v_mfma_f32_16x16x32_bf16 v[68:71], v[140:143], v[164:167], v[68:71]
	v_mfma_f32_16x16x32_bf16 v[56:59], v[132:135], v[172:175], v[56:59]
	v_mfma_f32_16x16x32_bf16 v[52:55], v[140:143], v[172:175], v[52:55]
	v_mfma_f32_16x16x32_bf16 v[40:43], v[132:135], v[180:183], v[40:43]
	v_mfma_f32_16x16x32_bf16 v[36:39], v[140:143], v[180:183], v[36:39]
	v_mfma_f32_16x16x32_bf16 v[20:23], v[132:135], v[188:191], v[20:23]
	v_mfma_f32_16x16x32_bf16 v[12:15], v[140:143], v[188:191], v[12:15]
	v_mfma_f32_16x16x32_bf16 v[72:75], v[136:139], v[168:171], v[72:75]
	v_mfma_f32_16x16x32_bf16 v[68:71], v[144:147], v[168:171], v[68:71]
	v_mfma_f32_16x16x32_bf16 v[56:59], v[136:139], v[176:179], v[56:59]
	v_mfma_f32_16x16x32_bf16 v[52:55], v[144:147], v[176:179], v[52:55]
	v_mfma_f32_16x16x32_bf16 v[40:43], v[136:139], v[184:187], v[40:43]
	v_mfma_f32_16x16x32_bf16 v[36:39], v[144:147], v[184:187], v[36:39]
	v_mfma_f32_16x16x32_bf16 v[20:23], v[136:139], v[192:195], v[20:23]
	v_mfma_f32_16x16x32_bf16 v[12:15], v[144:147], v[192:195], v[12:15]
	s_setprio 0
	s_mov_b32 m0, s34
	v_lshl_add_u64 v[222:223], s[28:29], 0, v[196:197]
	s_barrier
	ds_read_b128 v[188:191], v230 offset:16384
	ds_read_b128 v[192:195], v230 offset:17408
	ds_read_b128 v[180:183], v230 offset:18432
	ds_read_b128 v[184:187], v230 offset:19456
	ds_read_b128 v[172:175], v230 offset:20480
	ds_read_b128 v[176:179], v230 offset:21504
	ds_read_b128 v[164:167], v230 offset:22528
	ds_read_b128 v[168:171], v230 offset:23552
	global_load_lds_dwordx4 v[222:223], off
	v_lshl_add_u64 v[224:225], s[28:29], 0, v[200:201]
	s_mov_b32 m0, s35
	v_cmp_ne_u32_e64 s[16:17], 1, v233
	global_load_lds_dwordx4 v[224:225], off
	s_barrier
	s_waitcnt lgkmcnt(0)
	s_andn2_b64 vcc, exec, s[24:25]
	s_cbranch_vccnz .LBB0_690
	s_setprio 1
	s_waitcnt lgkmcnt(0)
	v_mfma_f32_16x16x32_bf16 v[128:131], v[148:151], v[188:191], v[128:131]
	v_mfma_f32_16x16x32_bf16 v[124:127], v[156:159], v[188:191], v[124:127]
	v_mfma_f32_16x16x32_bf16 v[112:115], v[148:151], v[180:183], v[112:115]
	v_mfma_f32_16x16x32_bf16 v[108:111], v[156:159], v[180:183], v[108:111]
	v_mfma_f32_16x16x32_bf16 v[96:99], v[148:151], v[172:175], v[96:99]
	v_mfma_f32_16x16x32_bf16 v[92:95], v[156:159], v[172:175], v[92:95]
	v_mfma_f32_16x16x32_bf16 v[28:31], v[148:151], v[164:167], v[28:31]
	v_mfma_f32_16x16x32_bf16 v[16:19], v[156:159], v[164:167], v[16:19]
	v_mfma_f32_16x16x32_bf16 v[128:131], v[152:155], v[192:195], v[128:131]
	v_mfma_f32_16x16x32_bf16 v[124:127], v[160:163], v[192:195], v[124:127]
	v_mfma_f32_16x16x32_bf16 v[112:115], v[152:155], v[184:187], v[112:115]
	v_mfma_f32_16x16x32_bf16 v[108:111], v[160:163], v[184:187], v[108:111]
	v_mfma_f32_16x16x32_bf16 v[96:99], v[152:155], v[176:179], v[96:99]
	v_mfma_f32_16x16x32_bf16 v[92:95], v[160:163], v[176:179], v[92:95]
	v_mfma_f32_16x16x32_bf16 v[28:31], v[152:155], v[168:171], v[28:31]
	v_mfma_f32_16x16x32_bf16 v[16:19], v[160:163], v[168:171], v[16:19]
	s_setprio 0

.LBB0_692:
	s_add_i32 s52, 0, 0x18000
	v_add_u32_e32 v1, s52, v226
	s_barrier
	ds_read_b128 v[148:151], v1
	ds_read_b128 v[152:155], v1 offset:1024
	ds_read_b128 v[156:159], v1 offset:2048
	ds_read_b128 v[160:163], v1 offset:3072
	s_add_u32 s28, s28, 0xb0000
	s_addc_u32 s29, s29, 0
	s_mov_b32 m0, s38
	v_lshl_add_u64 v[132:133], s[28:29], 0, v[196:197]
	ds_read_b128 v[164:167], v230 offset:32768
	ds_read_b128 v[168:171], v230 offset:33792
	ds_read_b128 v[172:175], v230 offset:34816
	ds_read_b128 v[176:179], v230 offset:35840
	ds_read_b128 v[180:183], v230 offset:36864
	ds_read_b128 v[184:187], v230 offset:37888
	ds_read_b128 v[188:191], v230 offset:38912
	ds_read_b128 v[192:195], v230 offset:39936
	global_load_lds_dwordx4 v[132:133], off
	v_lshl_add_u64 v[132:133], s[28:29], 0, v[200:201]
	s_mov_b32 m0, s39
	s_nop 0
	global_load_lds_dwordx4 v[132:133], off
	s_waitcnt lgkmcnt(8)
	s_barrier
	s_waitcnt lgkmcnt(0)
	s_setprio 1
	s_waitcnt lgkmcnt(0)
	v_mfma_f32_16x16x32_bf16 v[84:87], v[148:151], v[164:167], v[84:87]
	v_mfma_f32_16x16x32_bf16 v[76:79], v[156:159], v[164:167], v[76:79]
	v_mfma_f32_16x16x32_bf16 v[64:67], v[148:151], v[172:175], v[64:67]
	v_mfma_f32_16x16x32_bf16 v[60:63], v[156:159], v[172:175], v[60:63]
	v_mfma_f32_16x16x32_bf16 v[48:51], v[148:151], v[180:183], v[48:51]
	v_mfma_f32_16x16x32_bf16 v[44:47], v[156:159], v[180:183], v[44:47]
	v_mfma_f32_16x16x32_bf16 v[32:35], v[148:151], v[188:191], v[32:35]
	v_mfma_f32_16x16x32_bf16 v[24:27], v[156:159], v[188:191], v[24:27]
	v_mfma_f32_16x16x32_bf16 v[84:87], v[152:155], v[168:171], v[84:87]
	v_mfma_f32_16x16x32_bf16 v[76:79], v[160:163], v[168:171], v[76:79]
	v_mfma_f32_16x16x32_bf16 v[64:67], v[152:155], v[176:179], v[64:67]
	v_mfma_f32_16x16x32_bf16 v[60:63], v[160:163], v[176:179], v[60:63]
	v_mfma_f32_16x16x32_bf16 v[48:51], v[152:155], v[184:187], v[48:51]
	v_mfma_f32_16x16x32_bf16 v[44:47], v[160:163], v[184:187], v[44:47]
	v_mfma_f32_16x16x32_bf16 v[32:35], v[152:155], v[192:195], v[32:35]
	v_mfma_f32_16x16x32_bf16 v[24:27], v[160:163], v[192:195], v[24:27]
	s_setprio 0
	s_barrier
	s_add_i32 s28, s52, s30
	v_add_u32_e32 v1, 0x1c000, v231
	v_lshl_add_u64 v[2:3], v[2:3], 0, s[8:9]
	s_mov_b32 m0, s28
	ds_read_b128 v[132:135], v1
	ds_read_b128 v[136:139], v1 offset:1024
	ds_read_b128 v[140:143], v1 offset:2048
	ds_read_b128 v[144:147], v1 offset:3072
	global_load_lds_dwordx4 v[2:3], off
	v_lshl_add_u64 v[2:3], v[220:221], 0, s[8:9]
	s_add_i32 m0, s28, 0x2000
	s_nop 0
	global_load_lds_dwordx4 v[2:3], off
	s_barrier
	s_waitcnt lgkmcnt(0)
	s_setprio 1
	s_waitcnt lgkmcnt(0)
	v_mfma_f32_16x16x32_bf16 v[72:75], v[132:135], v[164:167], v[72:75]
	v_mfma_f32_16x16x32_bf16 v[68:71], v[140:143], v[164:167], v[68:71]
	v_mfma_f32_16x16x32_bf16 v[56:59], v[132:135], v[172:175], v[56:59]
	v_mfma_f32_16x16x32_bf16 v[52:55], v[140:143], v[172:175], v[52:55]
	v_mfma_f32_16x16x32_bf16 v[40:43], v[132:135], v[180:183], v[40:43]
	v_mfma_f32_16x16x32_bf16 v[36:39], v[140:143], v[180:183], v[36:39]
	v_mfma_f32_16x16x32_bf16 v[20:23], v[132:135], v[188:191], v[20:23]
	v_mfma_f32_16x16x32_bf16 v[12:15], v[140:143], v[188:191], v[12:15]
	v_mfma_f32_16x16x32_bf16 v[72:75], v[136:139], v[168:171], v[72:75]
	v_mfma_f32_16x16x32_bf16 v[68:71], v[144:147], v[168:171], v[68:71]
	v_mfma_f32_16x16x32_bf16 v[56:59], v[136:139], v[176:179], v[56:59]
	v_mfma_f32_16x16x32_bf16 v[52:55], v[144:147], v[176:179], v[52:55]
	v_mfma_f32_16x16x32_bf16 v[40:43], v[136:139], v[184:187], v[40:43]
	v_mfma_f32_16x16x32_bf16 v[36:39], v[144:147], v[184:187], v[36:39]
	v_mfma_f32_16x16x32_bf16 v[20:23], v[136:139], v[192:195], v[20:23]
	v_mfma_f32_16x16x32_bf16 v[12:15], v[144:147], v[192:195], v[12:15]
	s_setprio 0
	s_mov_b32 m0, s41
	v_lshl_add_u64 v[2:3], v[222:223], 0, s[8:9]
	s_barrier
	ds_read_b128 v[188:191], v230 offset:49152
	ds_read_b128 v[192:195], v230 offset:50176
	ds_read_b128 v[180:183], v230 offset:51200
	ds_read_b128 v[184:187], v230 offset:52224
	ds_read_b128 v[172:175], v230 offset:53248
	ds_read_b128 v[176:179], v230 offset:54272
	ds_read_b128 v[164:167], v230 offset:55296
	ds_read_b128 v[168:171], v230 offset:56320
	global_load_lds_dwordx4 v[2:3], off
	v_lshl_add_u64 v[2:3], v[224:225], 0, s[8:9]
	s_mov_b32 m0, s42
	s_and_b64 vcc, exec, s[16:17]
	global_load_lds_dwordx4 v[2:3], off
	s_barrier
	s_waitcnt lgkmcnt(0)
	s_cbranch_vccnz .LBB0_694
	s_setprio 1
	s_waitcnt lgkmcnt(0)
	v_mfma_f32_16x16x32_bf16 v[128:131], v[148:151], v[188:191], v[128:131]
	v_mfma_f32_16x16x32_bf16 v[124:127], v[156:159], v[188:191], v[124:127]
	v_mfma_f32_16x16x32_bf16 v[112:115], v[148:151], v[180:183], v[112:115]
	v_mfma_f32_16x16x32_bf16 v[108:111], v[156:159], v[180:183], v[108:111]
	v_mfma_f32_16x16x32_bf16 v[96:99], v[148:151], v[172:175], v[96:99]
	v_mfma_f32_16x16x32_bf16 v[92:95], v[156:159], v[172:175], v[92:95]
	v_mfma_f32_16x16x32_bf16 v[28:31], v[148:151], v[164:167], v[28:31]
	v_mfma_f32_16x16x32_bf16 v[16:19], v[156:159], v[164:167], v[16:19]
	v_mfma_f32_16x16x32_bf16 v[128:131], v[152:155], v[192:195], v[128:131]
	v_mfma_f32_16x16x32_bf16 v[124:127], v[160:163], v[192:195], v[124:127]
	v_mfma_f32_16x16x32_bf16 v[112:115], v[152:155], v[184:187], v[112:115]
	v_mfma_f32_16x16x32_bf16 v[108:111], v[160:163], v[184:187], v[108:111]
	v_mfma_f32_16x16x32_bf16 v[96:99], v[152:155], v[176:179], v[96:99]
	v_mfma_f32_16x16x32_bf16 v[92:95], v[160:163], v[176:179], v[92:95]
	v_mfma_f32_16x16x32_bf16 v[28:31], v[152:155], v[168:171], v[28:31]
	v_mfma_f32_16x16x32_bf16 v[16:19], v[160:163], v[168:171], v[16:19]
	s_setprio 0

.LBB0_883:
	ds_read_b128 v[148:151], v234
	ds_read_b128 v[152:155], v234 offset:1024
	ds_read_b128 v[156:159], v234 offset:2048
	ds_read_b128 v[160:163], v234 offset:3072
	s_add_u32 s14, s36, 0xfffc0080
	s_addc_u32 s15, s37, -1
	s_cmp_eq_u32 s29, s61
	s_cselect_b32 s41, s2, s15
	s_cselect_b32 s40, s9, s14
	s_cselect_b32 s39, s19, s60
	s_cselect_b32 s38, s27, s31
	v_lshl_add_u64 v[2:3], s[36:37], 0, v[214:215]
	s_add_i32 m0, s44, 0xc000
	ds_read_b128 v[164:167], v235
	ds_read_b128 v[168:171], v235 offset:1024
	ds_read_b128 v[172:175], v235 offset:2048
	ds_read_b128 v[176:179], v235 offset:3072
	ds_read_b128 v[180:183], v235 offset:4096
	ds_read_b128 v[184:187], v235 offset:5120
	ds_read_b128 v[188:191], v235 offset:6144
	ds_read_b128 v[192:195], v235 offset:7168
	global_load_lds_dwordx4 v[2:3], off
	v_lshl_add_u64 v[2:3], s[36:37], 0, v[216:217]
	s_add_i32 m0, s44, 0xe000
	s_nop 0
	global_load_lds_dwordx4 v[2:3], off
	s_waitcnt lgkmcnt(8)
	s_barrier
	s_waitcnt lgkmcnt(0)
	s_setprio 1
	s_waitcnt lgkmcnt(0)
	v_mfma_f32_16x16x32_bf16 v[72:75], v[148:151], v[164:167], v[72:75]
	v_mfma_f32_16x16x32_bf16 v[68:71], v[156:159], v[164:167], v[68:71]
	v_mfma_f32_16x16x32_bf16 v[56:59], v[148:151], v[172:175], v[56:59]
	v_mfma_f32_16x16x32_bf16 v[52:55], v[156:159], v[172:175], v[52:55]
	v_mfma_f32_16x16x32_bf16 v[40:43], v[148:151], v[180:183], v[40:43]
	v_mfma_f32_16x16x32_bf16 v[36:39], v[156:159], v[180:183], v[36:39]
	v_mfma_f32_16x16x32_bf16 v[24:27], v[148:151], v[188:191], v[24:27]
	v_mfma_f32_16x16x32_bf16 v[20:23], v[156:159], v[188:191], v[20:23]
	v_mfma_f32_16x16x32_bf16 v[72:75], v[152:155], v[168:171], v[72:75]
	v_mfma_f32_16x16x32_bf16 v[68:71], v[160:163], v[168:171], v[68:71]
	v_mfma_f32_16x16x32_bf16 v[56:59], v[152:155], v[176:179], v[56:59]
	v_mfma_f32_16x16x32_bf16 v[52:55], v[160:163], v[176:179], v[52:55]
	v_mfma_f32_16x16x32_bf16 v[40:43], v[152:155], v[184:187], v[40:43]
	v_mfma_f32_16x16x32_bf16 v[36:39], v[160:163], v[184:187], v[36:39]
	v_mfma_f32_16x16x32_bf16 v[24:27], v[152:155], v[192:195], v[24:27]
	v_mfma_f32_16x16x32_bf16 v[20:23], v[160:163], v[192:195], v[20:23]
	s_setprio 0
	s_barrier
	s_add_i32 s14, s57, s21
	v_lshl_add_u64 v[222:223], s[38:39], 0, v[198:199]
	s_mov_b32 m0, s14
	ds_read_b128 v[132:135], v237
	ds_read_b128 v[136:139], v237 offset:1024
	ds_read_b128 v[140:143], v237 offset:2048
	ds_read_b128 v[144:147], v237 offset:3072
	global_load_lds_dwordx4 v[222:223], off
	v_lshl_add_u64 v[224:225], s[38:39], 0, v[202:203]
	s_add_i32 m0, s14, 0x2000
	s_nop 0
	global_load_lds_dwordx4 v[224:225], off
	s_barrier
	s_waitcnt lgkmcnt(0)
	s_setprio 1
	s_waitcnt lgkmcnt(0)
	v_mfma_f32_16x16x32_bf16 v[64:67], v[132:135], v[164:167], v[64:67]
	v_mfma_f32_16x16x32_bf16 v[60:63], v[140:143], v[164:167], v[60:63]
	v_mfma_f32_16x16x32_bf16 v[48:51], v[132:135], v[172:175], v[48:51]
	v_mfma_f32_16x16x32_bf16 v[44:47], v[140:143], v[172:175], v[44:47]
	v_mfma_f32_16x16x32_bf16 v[32:35], v[132:135], v[180:183], v[32:35]
	v_mfma_f32_16x16x32_bf16 v[28:31], v[140:143], v[180:183], v[28:31]
	v_mfma_f32_16x16x32_bf16 v[16:19], v[132:135], v[188:191], v[16:19]
	v_mfma_f32_16x16x32_bf16 v[2:5], v[140:143], v[188:191], v[4:7]
	v_mfma_f32_16x16x32_bf16 v[64:67], v[136:139], v[168:171], v[64:67]
	v_mfma_f32_16x16x32_bf16 v[60:63], v[144:147], v[168:171], v[60:63]
	v_mfma_f32_16x16x32_bf16 v[48:51], v[136:139], v[176:179], v[48:51]
	v_mfma_f32_16x16x32_bf16 v[44:47], v[144:147], v[176:179], v[44:47]
	v_mfma_f32_16x16x32_bf16 v[32:35], v[136:139], v[184:187], v[32:35]
	v_mfma_f32_16x16x32_bf16 v[28:31], v[144:147], v[184:187], v[28:31]
	v_mfma_f32_16x16x32_bf16 v[16:19], v[136:139], v[192:195], v[16:19]
	v_mfma_f32_16x16x32_bf16 v[2:5], v[144:147], v[192:195], v[2:5]
	s_setprio 0
	s_mov_b32 m0, s44
	v_lshl_add_u64 v[226:227], s[40:41], 0, v[196:197]
	s_barrier
	ds_read_b128 v[188:191], v235 offset:16384
	ds_read_b128 v[192:195], v235 offset:17408
	ds_read_b128 v[180:183], v235 offset:18432
	ds_read_b128 v[184:187], v235 offset:19456
	ds_read_b128 v[172:175], v235 offset:20480
	ds_read_b128 v[176:179], v235 offset:21504
	ds_read_b128 v[164:167], v235 offset:22528
	ds_read_b128 v[168:171], v235 offset:23552
	global_load_lds_dwordx4 v[226:227], off
	v_lshl_add_u64 v[228:229], s[40:41], 0, v[200:201]
	s_mov_b32 m0, s45
	v_cmp_ne_u32_e64 s[14:15], 1, v245
	global_load_lds_dwordx4 v[228:229], off
	s_barrier
	s_waitcnt lgkmcnt(0)
	s_andn2_b64 vcc, exec, s[4:5]
	s_cbranch_vccnz .LBB0_885
	s_setprio 1
	s_waitcnt lgkmcnt(0)
	v_mfma_f32_16x16x32_bf16 v[128:131], v[148:151], v[188:191], v[128:131]
	v_mfma_f32_16x16x32_bf16 v[124:127], v[156:159], v[188:191], v[124:127]
	v_mfma_f32_16x16x32_bf16 v[112:115], v[148:151], v[180:183], v[112:115]
	v_mfma_f32_16x16x32_bf16 v[108:111], v[156:159], v[180:183], v[108:111]
	v_mfma_f32_16x16x32_bf16 v[96:99], v[148:151], v[172:175], v[96:99]
	v_mfma_f32_16x16x32_bf16 v[92:95], v[156:159], v[172:175], v[92:95]
	v_mfma_f32_16x16x32_bf16 v[80:83], v[148:151], v[164:167], v[80:83]
	v_mfma_f32_16x16x32_bf16 v[76:79], v[156:159], v[164:167], v[76:79]
	v_mfma_f32_16x16x32_bf16 v[128:131], v[152:155], v[192:195], v[128:131]
	v_mfma_f32_16x16x32_bf16 v[124:127], v[160:163], v[192:195], v[124:127]
	v_mfma_f32_16x16x32_bf16 v[112:115], v[152:155], v[184:187], v[112:115]
	v_mfma_f32_16x16x32_bf16 v[108:111], v[160:163], v[184:187], v[108:111]
	v_mfma_f32_16x16x32_bf16 v[96:99], v[152:155], v[176:179], v[96:99]
	v_mfma_f32_16x16x32_bf16 v[92:95], v[160:163], v[176:179], v[92:95]
	v_mfma_f32_16x16x32_bf16 v[80:83], v[152:155], v[168:171], v[80:83]
	v_mfma_f32_16x16x32_bf16 v[76:79], v[160:163], v[168:171], v[76:79]
	s_setprio 0

.LBB0_887:
	s_add_i32 s62, 0, 0x18000
	v_add_u32_e32 v1, s62, v230
	s_barrier
	ds_read_b128 v[148:151], v1
	ds_read_b128 v[152:155], v1 offset:1024
	ds_read_b128 v[156:159], v1 offset:2048
	ds_read_b128 v[160:163], v1 offset:3072
	s_add_u32 s40, s40, 0x40000
	s_addc_u32 s41, s41, 0
	s_mov_b32 m0, s48
	v_lshl_add_u64 v[6:7], s[40:41], 0, v[196:197]
	ds_read_b128 v[164:167], v235 offset:32768
	ds_read_b128 v[168:171], v235 offset:33792
	ds_read_b128 v[172:175], v235 offset:34816
	ds_read_b128 v[176:179], v235 offset:35840
	ds_read_b128 v[180:183], v235 offset:36864
	ds_read_b128 v[184:187], v235 offset:37888
	ds_read_b128 v[188:191], v235 offset:38912
	ds_read_b128 v[192:195], v235 offset:39936
	global_load_lds_dwordx4 v[6:7], off
	v_lshl_add_u64 v[6:7], s[40:41], 0, v[200:201]
	s_mov_b32 m0, s49
	s_nop 0
	global_load_lds_dwordx4 v[6:7], off
	s_waitcnt lgkmcnt(8)
	s_barrier
	s_waitcnt lgkmcnt(0)
	s_setprio 1
	s_waitcnt lgkmcnt(0)
	v_mfma_f32_16x16x32_bf16 v[72:75], v[148:151], v[164:167], v[72:75]
	v_mfma_f32_16x16x32_bf16 v[68:71], v[156:159], v[164:167], v[68:71]
	v_mfma_f32_16x16x32_bf16 v[56:59], v[148:151], v[172:175], v[56:59]
	v_mfma_f32_16x16x32_bf16 v[52:55], v[156:159], v[172:175], v[52:55]
	v_mfma_f32_16x16x32_bf16 v[40:43], v[148:151], v[180:183], v[40:43]
	v_mfma_f32_16x16x32_bf16 v[36:39], v[156:159], v[180:183], v[36:39]
	v_mfma_f32_16x16x32_bf16 v[24:27], v[148:151], v[188:191], v[24:27]
	v_mfma_f32_16x16x32_bf16 v[20:23], v[156:159], v[188:191], v[20:23]
	v_mfma_f32_16x16x32_bf16 v[72:75], v[152:155], v[168:171], v[72:75]
	v_mfma_f32_16x16x32_bf16 v[68:71], v[160:163], v[168:171], v[68:71]
	v_mfma_f32_16x16x32_bf16 v[56:59], v[152:155], v[176:179], v[56:59]
	v_mfma_f32_16x16x32_bf16 v[52:55], v[160:163], v[176:179], v[52:55]
	v_mfma_f32_16x16x32_bf16 v[40:43], v[152:155], v[184:187], v[40:43]
	v_mfma_f32_16x16x32_bf16 v[36:39], v[160:163], v[184:187], v[36:39]
	v_mfma_f32_16x16x32_bf16 v[24:27], v[152:155], v[192:195], v[24:27]
	v_mfma_f32_16x16x32_bf16 v[20:23], v[160:163], v[192:195], v[20:23]
	s_setprio 0
	s_barrier
	s_add_i32 s40, s62, s21
	v_add_u32_e32 v1, 0x1c000, v236
	v_lshl_add_u64 v[6:7], v[222:223], 0, s[24:25]
	s_mov_b32 m0, s40
	ds_read_b128 v[132:135], v1
	ds_read_b128 v[136:139], v1 offset:1024
	ds_read_b128 v[140:143], v1 offset:2048
	ds_read_b128 v[144:147], v1 offset:3072
	global_load_lds_dwordx4 v[6:7], off
	v_lshl_add_u64 v[6:7], v[224:225], 0, s[24:25]
	s_add_i32 m0, s40, 0x2000
	s_nop 0
	global_load_lds_dwordx4 v[6:7], off
	s_barrier
	s_waitcnt lgkmcnt(0)
	s_setprio 1
	s_waitcnt lgkmcnt(0)
	v_mfma_f32_16x16x32_bf16 v[64:67], v[132:135], v[164:167], v[64:67]
	v_mfma_f32_16x16x32_bf16 v[60:63], v[140:143], v[164:167], v[60:63]
	v_mfma_f32_16x16x32_bf16 v[48:51], v[132:135], v[172:175], v[48:51]
	v_mfma_f32_16x16x32_bf16 v[44:47], v[140:143], v[172:175], v[44:47]
	v_mfma_f32_16x16x32_bf16 v[32:35], v[132:135], v[180:183], v[32:35]
	v_mfma_f32_16x16x32_bf16 v[28:31], v[140:143], v[180:183], v[28:31]
	v_mfma_f32_16x16x32_bf16 v[16:19], v[132:135], v[188:191], v[16:19]
	v_mfma_f32_16x16x32_bf16 v[2:5], v[140:143], v[188:191], v[2:5]
	v_mfma_f32_16x16x32_bf16 v[64:67], v[136:139], v[168:171], v[64:67]
	v_mfma_f32_16x16x32_bf16 v[60:63], v[144:147], v[168:171], v[60:63]
	v_mfma_f32_16x16x32_bf16 v[48:51], v[136:139], v[176:179], v[48:51]
	v_mfma_f32_16x16x32_bf16 v[44:47], v[144:147], v[176:179], v[44:47]
	v_mfma_f32_16x16x32_bf16 v[32:35], v[136:139], v[184:187], v[32:35]
	v_mfma_f32_16x16x32_bf16 v[28:31], v[144:147], v[184:187], v[28:31]
	v_mfma_f32_16x16x32_bf16 v[16:19], v[136:139], v[192:195], v[16:19]
	v_mfma_f32_16x16x32_bf16 v[4:7], v[144:147], v[192:195], v[2:5]
	s_setprio 0
	s_mov_b32 m0, s51
	s_nop 0
	v_lshl_add_u64 v[2:3], v[226:227], 0, s[24:25]
	s_barrier
	ds_read_b128 v[188:191], v235 offset:49152
	ds_read_b128 v[192:195], v235 offset:50176
	ds_read_b128 v[180:183], v235 offset:51200
	ds_read_b128 v[184:187], v235 offset:52224
	ds_read_b128 v[172:175], v235 offset:53248
	ds_read_b128 v[176:179], v235 offset:54272
	ds_read_b128 v[164:167], v235 offset:55296
	ds_read_b128 v[168:171], v235 offset:56320
	global_load_lds_dwordx4 v[2:3], off
	v_lshl_add_u64 v[2:3], v[228:229], 0, s[24:25]
	s_mov_b32 m0, s52
	s_and_b64 vcc, exec, s[14:15]
	global_load_lds_dwordx4 v[2:3], off
	s_barrier
	s_waitcnt lgkmcnt(0)
	s_cbranch_vccnz .LBB0_889
	s_setprio 1
	s_waitcnt lgkmcnt(0)
	v_mfma_f32_16x16x32_bf16 v[128:131], v[148:151], v[188:191], v[128:131]
	v_mfma_f32_16x16x32_bf16 v[124:127], v[156:159], v[188:191], v[124:127]
	v_mfma_f32_16x16x32_bf16 v[112:115], v[148:151], v[180:183], v[112:115]
	v_mfma_f32_16x16x32_bf16 v[108:111], v[156:159], v[180:183], v[108:111]
	v_mfma_f32_16x16x32_bf16 v[96:99], v[148:151], v[172:175], v[96:99]
	v_mfma_f32_16x16x32_bf16 v[92:95], v[156:159], v[172:175], v[92:95]
	v_mfma_f32_16x16x32_bf16 v[80:83], v[148:151], v[164:167], v[80:83]
	v_mfma_f32_16x16x32_bf16 v[76:79], v[156:159], v[164:167], v[76:79]
	v_mfma_f32_16x16x32_bf16 v[128:131], v[152:155], v[192:195], v[128:131]
	v_mfma_f32_16x16x32_bf16 v[124:127], v[160:163], v[192:195], v[124:127]
	v_mfma_f32_16x16x32_bf16 v[112:115], v[152:155], v[184:187], v[112:115]
	v_mfma_f32_16x16x32_bf16 v[108:111], v[160:163], v[184:187], v[108:111]
	v_mfma_f32_16x16x32_bf16 v[96:99], v[152:155], v[176:179], v[96:99]
	v_mfma_f32_16x16x32_bf16 v[92:95], v[160:163], v[176:179], v[92:95]
	v_mfma_f32_16x16x32_bf16 v[80:83], v[152:155], v[168:171], v[80:83]
	v_mfma_f32_16x16x32_bf16 v[76:79], v[160:163], v[168:171], v[76:79]
	s_setprio 0

.LBB0_1147:
	ds_read_b128 v[148:151], v205
	ds_read_b128 v[152:155], v205 offset:1024
	ds_read_b128 v[156:159], v205 offset:2048
	ds_read_b128 v[160:163], v205 offset:3072
	s_add_u32 s12, s30, 0xfff80080
	s_addc_u32 s13, s31, -1
	s_cmp_eq_u32 s21, s57
	s_cselect_b32 s37, s2, s13
	s_cselect_b32 s36, s5, s12
	s_cselect_b32 s35, s17, s56
	s_cselect_b32 s34, s19, s55
	v_lshl_add_u64 v[2:3], s[30:31], 0, v[214:215]
	s_add_i32 m0, s7, 0xc000
	ds_read_b128 v[164:167], v230
	ds_read_b128 v[168:171], v230 offset:1024
	ds_read_b128 v[172:175], v230 offset:2048
	ds_read_b128 v[176:179], v230 offset:3072
	ds_read_b128 v[180:183], v230 offset:4096
	ds_read_b128 v[184:187], v230 offset:5120
	ds_read_b128 v[188:191], v230 offset:6144
	ds_read_b128 v[192:195], v230 offset:7168
	global_load_lds_dwordx4 v[2:3], off
	v_lshl_add_u64 v[2:3], s[30:31], 0, v[216:217]
	s_add_i32 m0, s7, 0xe000
	s_nop 0
	global_load_lds_dwordx4 v[2:3], off
	s_waitcnt lgkmcnt(8)
	s_barrier
	s_waitcnt lgkmcnt(0)
	s_setprio 1
	s_waitcnt lgkmcnt(0)
	v_mfma_f32_16x16x32_bf16 v[84:87], v[148:151], v[164:167], v[84:87]
	v_mfma_f32_16x16x32_bf16 v[76:79], v[156:159], v[164:167], v[76:79]
	v_mfma_f32_16x16x32_bf16 v[64:67], v[148:151], v[172:175], v[64:67]
	v_mfma_f32_16x16x32_bf16 v[60:63], v[156:159], v[172:175], v[60:63]
	v_mfma_f32_16x16x32_bf16 v[48:51], v[148:151], v[180:183], v[48:51]
	v_mfma_f32_16x16x32_bf16 v[44:47], v[156:159], v[180:183], v[44:47]
	v_mfma_f32_16x16x32_bf16 v[32:35], v[148:151], v[188:191], v[32:35]
	v_mfma_f32_16x16x32_bf16 v[24:27], v[156:159], v[188:191], v[24:27]
	v_mfma_f32_16x16x32_bf16 v[84:87], v[152:155], v[168:171], v[84:87]
	v_mfma_f32_16x16x32_bf16 v[76:79], v[160:163], v[168:171], v[76:79]
	v_mfma_f32_16x16x32_bf16 v[64:67], v[152:155], v[176:179], v[64:67]
	v_mfma_f32_16x16x32_bf16 v[60:63], v[160:163], v[176:179], v[60:63]
	v_mfma_f32_16x16x32_bf16 v[48:51], v[152:155], v[184:187], v[48:51]
	v_mfma_f32_16x16x32_bf16 v[44:47], v[160:163], v[184:187], v[44:47]
	v_mfma_f32_16x16x32_bf16 v[32:35], v[152:155], v[192:195], v[32:35]
	v_mfma_f32_16x16x32_bf16 v[24:27], v[160:163], v[192:195], v[24:27]
	s_setprio 0
	s_barrier
	s_add_i32 s12, s53, s40
	v_lshl_add_u64 v[2:3], s[34:35], 0, v[198:199]
	s_mov_b32 m0, s12
	ds_read_b128 v[132:135], v232
	ds_read_b128 v[136:139], v232 offset:1024
	ds_read_b128 v[140:143], v232 offset:2048
	ds_read_b128 v[144:147], v232 offset:3072
	global_load_lds_dwordx4 v[2:3], off
	v_lshl_add_u64 v[220:221], s[34:35], 0, v[202:203]
	s_add_i32 m0, s12, 0x2000
	s_nop 0
	global_load_lds_dwordx4 v[220:221], off
	s_barrier
	s_waitcnt lgkmcnt(0)
	s_setprio 1
	s_waitcnt lgkmcnt(0)
	v_mfma_f32_16x16x32_bf16 v[72:75], v[132:135], v[164:167], v[72:75]
	v_mfma_f32_16x16x32_bf16 v[68:71], v[140:143], v[164:167], v[68:71]
	v_mfma_f32_16x16x32_bf16 v[56:59], v[132:135], v[172:175], v[56:59]
	v_mfma_f32_16x16x32_bf16 v[52:55], v[140:143], v[172:175], v[52:55]
	v_mfma_f32_16x16x32_bf16 v[40:43], v[132:135], v[180:183], v[40:43]
	v_mfma_f32_16x16x32_bf16 v[36:39], v[140:143], v[180:183], v[36:39]
	v_mfma_f32_16x16x32_bf16 v[20:23], v[132:135], v[188:191], v[20:23]
	v_mfma_f32_16x16x32_bf16 v[12:15], v[140:143], v[188:191], v[12:15]
	v_mfma_f32_16x16x32_bf16 v[72:75], v[136:139], v[168:171], v[72:75]
	v_mfma_f32_16x16x32_bf16 v[68:71], v[144:147], v[168:171], v[68:71]
	v_mfma_f32_16x16x32_bf16 v[56:59], v[136:139], v[176:179], v[56:59]
	v_mfma_f32_16x16x32_bf16 v[52:55], v[144:147], v[176:179], v[52:55]
	v_mfma_f32_16x16x32_bf16 v[40:43], v[136:139], v[184:187], v[40:43]
	v_mfma_f32_16x16x32_bf16 v[36:39], v[144:147], v[184:187], v[36:39]
	v_mfma_f32_16x16x32_bf16 v[20:23], v[136:139], v[192:195], v[20:23]
	v_mfma_f32_16x16x32_bf16 v[12:15], v[144:147], v[192:195], v[12:15]
	s_setprio 0
	s_mov_b32 m0, s7
	v_lshl_add_u64 v[222:223], s[36:37], 0, v[196:197]
	s_barrier
	ds_read_b128 v[188:191], v230 offset:16384
	ds_read_b128 v[192:195], v230 offset:17408
	ds_read_b128 v[180:183], v230 offset:18432
	ds_read_b128 v[184:187], v230 offset:19456
	ds_read_b128 v[172:175], v230 offset:20480
	ds_read_b128 v[176:179], v230 offset:21504
	ds_read_b128 v[164:167], v230 offset:22528
	ds_read_b128 v[168:171], v230 offset:23552
	global_load_lds_dwordx4 v[222:223], off
	v_lshl_add_u64 v[224:225], s[36:37], 0, v[200:201]
	s_mov_b32 m0, s41
	v_cmp_ne_u32_e64 s[12:13], 1, v233
	global_load_lds_dwordx4 v[224:225], off
	s_barrier
	s_waitcnt lgkmcnt(0)
	s_andn2_b64 vcc, exec, s[28:29]
	s_cbranch_vccnz .LBB0_1149
	s_setprio 1
	s_waitcnt lgkmcnt(0)
	v_mfma_f32_16x16x32_bf16 v[128:131], v[148:151], v[188:191], v[128:131]
	v_mfma_f32_16x16x32_bf16 v[124:127], v[156:159], v[188:191], v[124:127]
	v_mfma_f32_16x16x32_bf16 v[112:115], v[148:151], v[180:183], v[112:115]
	v_mfma_f32_16x16x32_bf16 v[108:111], v[156:159], v[180:183], v[108:111]
	v_mfma_f32_16x16x32_bf16 v[96:99], v[148:151], v[172:175], v[96:99]
	v_mfma_f32_16x16x32_bf16 v[92:95], v[156:159], v[172:175], v[92:95]
	v_mfma_f32_16x16x32_bf16 v[28:31], v[148:151], v[164:167], v[28:31]
	v_mfma_f32_16x16x32_bf16 v[16:19], v[156:159], v[164:167], v[16:19]
	v_mfma_f32_16x16x32_bf16 v[128:131], v[152:155], v[192:195], v[128:131]
	v_mfma_f32_16x16x32_bf16 v[124:127], v[160:163], v[192:195], v[124:127]
	v_mfma_f32_16x16x32_bf16 v[112:115], v[152:155], v[184:187], v[112:115]
	v_mfma_f32_16x16x32_bf16 v[108:111], v[160:163], v[184:187], v[108:111]
	v_mfma_f32_16x16x32_bf16 v[96:99], v[152:155], v[176:179], v[96:99]
	v_mfma_f32_16x16x32_bf16 v[92:95], v[160:163], v[176:179], v[92:95]
	v_mfma_f32_16x16x32_bf16 v[28:31], v[152:155], v[168:171], v[28:31]
	v_mfma_f32_16x16x32_bf16 v[16:19], v[160:163], v[168:171], v[16:19]
	s_setprio 0

.LBB0_1151:
	s_add_i32 s58, 0, 0x18000
	v_add_u32_e32 v1, s58, v226
	s_barrier
	ds_read_b128 v[148:151], v1
	ds_read_b128 v[152:155], v1 offset:1024
	ds_read_b128 v[156:159], v1 offset:2048
	ds_read_b128 v[160:163], v1 offset:3072
	s_add_u32 s36, s36, 0x80000
	s_addc_u32 s37, s37, 0
	s_mov_b32 m0, s44
	v_lshl_add_u64 v[132:133], s[36:37], 0, v[196:197]
	ds_read_b128 v[164:167], v230 offset:32768
	ds_read_b128 v[168:171], v230 offset:33792
	ds_read_b128 v[172:175], v230 offset:34816
	ds_read_b128 v[176:179], v230 offset:35840
	ds_read_b128 v[180:183], v230 offset:36864
	ds_read_b128 v[184:187], v230 offset:37888
	ds_read_b128 v[188:191], v230 offset:38912
	ds_read_b128 v[192:195], v230 offset:39936
	global_load_lds_dwordx4 v[132:133], off
	v_lshl_add_u64 v[132:133], s[36:37], 0, v[200:201]
	s_mov_b32 m0, s45
	s_nop 0
	global_load_lds_dwordx4 v[132:133], off
	s_waitcnt lgkmcnt(8)
	s_barrier
	s_waitcnt lgkmcnt(0)
	s_setprio 1
	s_waitcnt lgkmcnt(0)
	v_mfma_f32_16x16x32_bf16 v[84:87], v[148:151], v[164:167], v[84:87]
	v_mfma_f32_16x16x32_bf16 v[76:79], v[156:159], v[164:167], v[76:79]
	v_mfma_f32_16x16x32_bf16 v[64:67], v[148:151], v[172:175], v[64:67]
	v_mfma_f32_16x16x32_bf16 v[60:63], v[156:159], v[172:175], v[60:63]
	v_mfma_f32_16x16x32_bf16 v[48:51], v[148:151], v[180:183], v[48:51]
	v_mfma_f32_16x16x32_bf16 v[44:47], v[156:159], v[180:183], v[44:47]
	v_mfma_f32_16x16x32_bf16 v[32:35], v[148:151], v[188:191], v[32:35]
	v_mfma_f32_16x16x32_bf16 v[24:27], v[156:159], v[188:191], v[24:27]
	v_mfma_f32_16x16x32_bf16 v[84:87], v[152:155], v[168:171], v[84:87]
	v_mfma_f32_16x16x32_bf16 v[76:79], v[160:163], v[168:171], v[76:79]
	v_mfma_f32_16x16x32_bf16 v[64:67], v[152:155], v[176:179], v[64:67]
	v_mfma_f32_16x16x32_bf16 v[60:63], v[160:163], v[176:179], v[60:63]
	v_mfma_f32_16x16x32_bf16 v[48:51], v[152:155], v[184:187], v[48:51]
	v_mfma_f32_16x16x32_bf16 v[44:47], v[160:163], v[184:187], v[44:47]
	v_mfma_f32_16x16x32_bf16 v[32:35], v[152:155], v[192:195], v[32:35]
	v_mfma_f32_16x16x32_bf16 v[24:27], v[160:163], v[192:195], v[24:27]
	s_setprio 0
	s_barrier
	s_add_i32 s36, s58, s40
	v_add_u32_e32 v1, 0x1c000, v231
	v_lshl_add_u64 v[2:3], v[2:3], 0, s[14:15]
	s_mov_b32 m0, s36
	ds_read_b128 v[132:135], v1
	ds_read_b128 v[136:139], v1 offset:1024
	ds_read_b128 v[140:143], v1 offset:2048
	ds_read_b128 v[144:147], v1 offset:3072
	global_load_lds_dwordx4 v[2:3], off
	v_lshl_add_u64 v[2:3], v[220:221], 0, s[14:15]
	s_add_i32 m0, s36, 0x2000
	s_nop 0
	global_load_lds_dwordx4 v[2:3], off
	s_barrier
	s_waitcnt lgkmcnt(0)
	s_setprio 1
	s_waitcnt lgkmcnt(0)
	v_mfma_f32_16x16x32_bf16 v[72:75], v[132:135], v[164:167], v[72:75]
	v_mfma_f32_16x16x32_bf16 v[68:71], v[140:143], v[164:167], v[68:71]
	v_mfma_f32_16x16x32_bf16 v[56:59], v[132:135], v[172:175], v[56:59]
	v_mfma_f32_16x16x32_bf16 v[52:55], v[140:143], v[172:175], v[52:55]
	v_mfma_f32_16x16x32_bf16 v[40:43], v[132:135], v[180:183], v[40:43]
	v_mfma_f32_16x16x32_bf16 v[36:39], v[140:143], v[180:183], v[36:39]
	v_mfma_f32_16x16x32_bf16 v[20:23], v[132:135], v[188:191], v[20:23]
	v_mfma_f32_16x16x32_bf16 v[12:15], v[140:143], v[188:191], v[12:15]
	v_mfma_f32_16x16x32_bf16 v[72:75], v[136:139], v[168:171], v[72:75]
	v_mfma_f32_16x16x32_bf16 v[68:71], v[144:147], v[168:171], v[68:71]
	v_mfma_f32_16x16x32_bf16 v[56:59], v[136:139], v[176:179], v[56:59]
	v_mfma_f32_16x16x32_bf16 v[52:55], v[144:147], v[176:179], v[52:55]
	v_mfma_f32_16x16x32_bf16 v[40:43], v[136:139], v[184:187], v[40:43]
	v_mfma_f32_16x16x32_bf16 v[36:39], v[144:147], v[184:187], v[36:39]
	v_mfma_f32_16x16x32_bf16 v[20:23], v[136:139], v[192:195], v[20:23]
	v_mfma_f32_16x16x32_bf16 v[12:15], v[144:147], v[192:195], v[12:15]
	s_setprio 0
	s_mov_b32 m0, s47
	v_lshl_add_u64 v[2:3], v[222:223], 0, s[14:15]
	s_barrier
	ds_read_b128 v[188:191], v230 offset:49152
	ds_read_b128 v[192:195], v230 offset:50176
	ds_read_b128 v[180:183], v230 offset:51200
	ds_read_b128 v[184:187], v230 offset:52224
	ds_read_b128 v[172:175], v230 offset:53248
	ds_read_b128 v[176:179], v230 offset:54272
	ds_read_b128 v[164:167], v230 offset:55296
	ds_read_b128 v[168:171], v230 offset:56320
	global_load_lds_dwordx4 v[2:3], off
	v_lshl_add_u64 v[2:3], v[224:225], 0, s[14:15]
	s_mov_b32 m0, s48
	s_and_b64 vcc, exec, s[12:13]
	global_load_lds_dwordx4 v[2:3], off
	s_barrier
	s_waitcnt lgkmcnt(0)
	s_cbranch_vccnz .LBB0_1153
	s_setprio 1
	s_waitcnt lgkmcnt(0)
	v_mfma_f32_16x16x32_bf16 v[128:131], v[148:151], v[188:191], v[128:131]
	v_mfma_f32_16x16x32_bf16 v[124:127], v[156:159], v[188:191], v[124:127]
	v_mfma_f32_16x16x32_bf16 v[112:115], v[148:151], v[180:183], v[112:115]
	v_mfma_f32_16x16x32_bf16 v[108:111], v[156:159], v[180:183], v[108:111]
	v_mfma_f32_16x16x32_bf16 v[96:99], v[148:151], v[172:175], v[96:99]
	v_mfma_f32_16x16x32_bf16 v[92:95], v[156:159], v[172:175], v[92:95]
	v_mfma_f32_16x16x32_bf16 v[28:31], v[148:151], v[164:167], v[28:31]
	v_mfma_f32_16x16x32_bf16 v[16:19], v[156:159], v[164:167], v[16:19]
	v_mfma_f32_16x16x32_bf16 v[128:131], v[152:155], v[192:195], v[128:131]
	v_mfma_f32_16x16x32_bf16 v[124:127], v[160:163], v[192:195], v[124:127]
	v_mfma_f32_16x16x32_bf16 v[112:115], v[152:155], v[184:187], v[112:115]
	v_mfma_f32_16x16x32_bf16 v[108:111], v[160:163], v[184:187], v[108:111]
	v_mfma_f32_16x16x32_bf16 v[96:99], v[152:155], v[176:179], v[96:99]
	v_mfma_f32_16x16x32_bf16 v[92:95], v[160:163], v[176:179], v[92:95]
	v_mfma_f32_16x16x32_bf16 v[28:31], v[152:155], v[168:171], v[28:31]
	v_mfma_f32_16x16x32_bf16 v[16:19], v[160:163], v[168:171], v[16:19]
	s_setprio 0

.LBB0_1346:
	ds_read_b128 v[148:151], v222
	ds_read_b128 v[152:155], v222 offset:1024
	ds_read_b128 v[156:159], v222 offset:2048
	ds_read_b128 v[160:163], v222 offset:3072
	s_add_u32 s12, s26, 0xfffc0080
	s_addc_u32 s13, s27, -1
	s_cmp_eq_u32 s52, s55
	s_cselect_b32 s31, s2, s13
	s_cselect_b32 s30, s9, s12
	s_cselect_b32 s29, s15, s54
	s_cselect_b32 s28, s21, s53
	v_lshl_add_u64 v[2:3], s[26:27], 0, v[204:205]
	s_add_i32 m0, s36, 0xc000
	ds_read_b128 v[164:167], v223
	ds_read_b128 v[168:171], v223 offset:1024
	ds_read_b128 v[172:175], v223 offset:2048
	ds_read_b128 v[176:179], v223 offset:3072
	ds_read_b128 v[180:183], v223 offset:4096
	ds_read_b128 v[184:187], v223 offset:5120
	ds_read_b128 v[188:191], v223 offset:6144
	ds_read_b128 v[192:195], v223 offset:7168
	global_load_lds_dwordx4 v[2:3], off
	v_lshl_add_u64 v[2:3], s[26:27], 0, v[206:207]
	s_add_i32 m0, s36, 0xe000
	s_nop 0
	global_load_lds_dwordx4 v[2:3], off
	s_waitcnt lgkmcnt(8)
	s_barrier
	s_waitcnt lgkmcnt(0)
	s_setprio 1
	s_waitcnt lgkmcnt(0)
	v_mfma_f32_16x16x32_bf16 v[124:127], v[148:151], v[164:167], v[124:127]
	v_mfma_f32_16x16x32_bf16 v[116:119], v[156:159], v[164:167], v[116:119]
	v_mfma_f32_16x16x32_bf16 v[108:111], v[148:151], v[172:175], v[108:111]
	v_mfma_f32_16x16x32_bf16 v[100:103], v[156:159], v[172:175], v[100:103]
	v_mfma_f32_16x16x32_bf16 v[92:95], v[148:151], v[180:183], v[92:95]
	v_mfma_f32_16x16x32_bf16 v[84:87], v[156:159], v[180:183], v[84:87]
	v_mfma_f32_16x16x32_bf16 v[76:79], v[148:151], v[188:191], v[76:79]
	v_mfma_f32_16x16x32_bf16 v[72:75], v[156:159], v[188:191], v[72:75]
	v_mfma_f32_16x16x32_bf16 v[124:127], v[152:155], v[168:171], v[124:127]
	v_mfma_f32_16x16x32_bf16 v[116:119], v[160:163], v[168:171], v[116:119]
	v_mfma_f32_16x16x32_bf16 v[108:111], v[152:155], v[176:179], v[108:111]
	v_mfma_f32_16x16x32_bf16 v[100:103], v[160:163], v[176:179], v[100:103]
	v_mfma_f32_16x16x32_bf16 v[92:95], v[152:155], v[184:187], v[92:95]
	v_mfma_f32_16x16x32_bf16 v[84:87], v[160:163], v[184:187], v[84:87]
	v_mfma_f32_16x16x32_bf16 v[76:79], v[152:155], v[192:195], v[76:79]
	v_mfma_f32_16x16x32_bf16 v[72:75], v[160:163], v[192:195], v[72:75]
	s_setprio 0
	s_barrier
	s_add_i32 s12, s49, s23
	v_lshl_add_u64 v[2:3], s[28:29], 0, v[198:199]
	s_mov_b32 m0, s12
	ds_read_b128 v[132:135], v225
	ds_read_b128 v[136:139], v225 offset:1024
	ds_read_b128 v[140:143], v225 offset:2048
	ds_read_b128 v[144:147], v225 offset:3072
	global_load_lds_dwordx4 v[2:3], off
	v_lshl_add_u64 v[212:213], s[28:29], 0, v[202:203]
	s_add_i32 m0, s12, 0x2000
	s_nop 0
	global_load_lds_dwordx4 v[212:213], off
	s_barrier
	s_waitcnt lgkmcnt(0)
	s_setprio 1
	s_waitcnt lgkmcnt(0)
	v_mfma_f32_16x16x32_bf16 v[128:131], v[132:135], v[164:167], v[128:131]
	v_mfma_f32_16x16x32_bf16 v[120:123], v[140:143], v[164:167], v[120:123]
	v_mfma_f32_16x16x32_bf16 v[112:115], v[132:135], v[172:175], v[112:115]
	v_mfma_f32_16x16x32_bf16 v[104:107], v[140:143], v[172:175], v[104:107]
	v_mfma_f32_16x16x32_bf16 v[96:99], v[132:135], v[180:183], v[96:99]
	v_mfma_f32_16x16x32_bf16 v[88:91], v[140:143], v[180:183], v[88:91]
	v_mfma_f32_16x16x32_bf16 v[80:83], v[132:135], v[188:191], v[80:83]
	v_mfma_f32_16x16x32_bf16 v[68:71], v[140:143], v[188:191], v[68:71]
	v_mfma_f32_16x16x32_bf16 v[128:131], v[136:139], v[168:171], v[128:131]
	v_mfma_f32_16x16x32_bf16 v[120:123], v[144:147], v[168:171], v[120:123]
	v_mfma_f32_16x16x32_bf16 v[112:115], v[136:139], v[176:179], v[112:115]
	v_mfma_f32_16x16x32_bf16 v[104:107], v[144:147], v[176:179], v[104:107]
	v_mfma_f32_16x16x32_bf16 v[96:99], v[136:139], v[184:187], v[96:99]
	v_mfma_f32_16x16x32_bf16 v[88:91], v[144:147], v[184:187], v[88:91]
	v_mfma_f32_16x16x32_bf16 v[80:83], v[136:139], v[192:195], v[80:83]
	v_mfma_f32_16x16x32_bf16 v[68:71], v[144:147], v[192:195], v[68:71]
	s_setprio 0
	s_mov_b32 m0, s36
	v_lshl_add_u64 v[214:215], s[30:31], 0, v[196:197]
	s_barrier
	ds_read_b128 v[188:191], v223 offset:16384
	ds_read_b128 v[192:195], v223 offset:17408
	ds_read_b128 v[180:183], v223 offset:18432
	ds_read_b128 v[184:187], v223 offset:19456
	ds_read_b128 v[172:175], v223 offset:20480
	ds_read_b128 v[176:179], v223 offset:21504
	ds_read_b128 v[164:167], v223 offset:22528
	ds_read_b128 v[168:171], v223 offset:23552
	global_load_lds_dwordx4 v[214:215], off
	v_lshl_add_u64 v[216:217], s[30:31], 0, v[200:201]
	s_mov_b32 m0, s37
	v_cmp_ne_u32_e64 s[12:13], 1, v234
	global_load_lds_dwordx4 v[216:217], off
	s_barrier
	s_waitcnt lgkmcnt(0)
	s_andn2_b64 vcc, exec, s[24:25]
	s_cbranch_vccnz .LBB0_1348
	s_setprio 1
	s_waitcnt lgkmcnt(0)
	v_mfma_f32_16x16x32_bf16 v[60:63], v[148:151], v[188:191], v[60:63]
	v_mfma_f32_16x16x32_bf16 v[52:55], v[156:159], v[188:191], v[52:55]
	v_mfma_f32_16x16x32_bf16 v[44:47], v[148:151], v[180:183], v[44:47]
	v_mfma_f32_16x16x32_bf16 v[36:39], v[156:159], v[180:183], v[36:39]
	v_mfma_f32_16x16x32_bf16 v[28:31], v[148:151], v[172:175], v[28:31]
	v_mfma_f32_16x16x32_bf16 v[20:23], v[156:159], v[172:175], v[20:23]
	v_mfma_f32_16x16x32_bf16 v[12:15], v[148:151], v[164:167], v[12:15]
	v_mfma_f32_16x16x32_bf16 v[4:7], v[156:159], v[164:167], v[4:7]
	v_mfma_f32_16x16x32_bf16 v[60:63], v[152:155], v[192:195], v[60:63]
	v_mfma_f32_16x16x32_bf16 v[52:55], v[160:163], v[192:195], v[52:55]
	v_mfma_f32_16x16x32_bf16 v[44:47], v[152:155], v[184:187], v[44:47]
	v_mfma_f32_16x16x32_bf16 v[36:39], v[160:163], v[184:187], v[36:39]
	v_mfma_f32_16x16x32_bf16 v[28:31], v[152:155], v[176:179], v[28:31]
	v_mfma_f32_16x16x32_bf16 v[20:23], v[160:163], v[176:179], v[20:23]
	v_mfma_f32_16x16x32_bf16 v[12:15], v[152:155], v[168:171], v[12:15]
	v_mfma_f32_16x16x32_bf16 v[4:7], v[160:163], v[168:171], v[4:7]
	s_setprio 0

.LBB0_1350:
	s_add_i32 s56, 0, 0x18000
	v_add_u32_e32 v1, s56, v220
	s_barrier
	ds_read_b128 v[148:151], v1
	ds_read_b128 v[152:155], v1 offset:1024
	ds_read_b128 v[156:159], v1 offset:2048
	ds_read_b128 v[160:163], v1 offset:3072
	s_add_u32 s30, s30, 0x40000
	s_addc_u32 s31, s31, 0
	s_mov_b32 m0, s40
	v_lshl_add_u64 v[132:133], s[30:31], 0, v[196:197]
	ds_read_b128 v[164:167], v223 offset:32768
	ds_read_b128 v[168:171], v223 offset:33792
	ds_read_b128 v[172:175], v223 offset:34816
	ds_read_b128 v[176:179], v223 offset:35840
	ds_read_b128 v[180:183], v223 offset:36864
	ds_read_b128 v[184:187], v223 offset:37888
	ds_read_b128 v[188:191], v223 offset:38912
	ds_read_b128 v[192:195], v223 offset:39936
	global_load_lds_dwordx4 v[132:133], off
	v_lshl_add_u64 v[132:133], s[30:31], 0, v[200:201]
	s_mov_b32 m0, s41
	s_nop 0
	global_load_lds_dwordx4 v[132:133], off
	s_waitcnt lgkmcnt(8)
	s_barrier
	s_waitcnt lgkmcnt(0)
	s_setprio 1
	s_waitcnt lgkmcnt(0)
	v_mfma_f32_16x16x32_bf16 v[124:127], v[148:151], v[164:167], v[124:127]
	v_mfma_f32_16x16x32_bf16 v[116:119], v[156:159], v[164:167], v[116:119]
	v_mfma_f32_16x16x32_bf16 v[108:111], v[148:151], v[172:175], v[108:111]
	v_mfma_f32_16x16x32_bf16 v[100:103], v[156:159], v[172:175], v[100:103]
	v_mfma_f32_16x16x32_bf16 v[92:95], v[148:151], v[180:183], v[92:95]
	v_mfma_f32_16x16x32_bf16 v[84:87], v[156:159], v[180:183], v[84:87]
	v_mfma_f32_16x16x32_bf16 v[76:79], v[148:151], v[188:191], v[76:79]
	v_mfma_f32_16x16x32_bf16 v[72:75], v[156:159], v[188:191], v[72:75]
	v_mfma_f32_16x16x32_bf16 v[124:127], v[152:155], v[168:171], v[124:127]
	v_mfma_f32_16x16x32_bf16 v[116:119], v[160:163], v[168:171], v[116:119]
	v_mfma_f32_16x16x32_bf16 v[108:111], v[152:155], v[176:179], v[108:111]
	v_mfma_f32_16x16x32_bf16 v[100:103], v[160:163], v[176:179], v[100:103]
	v_mfma_f32_16x16x32_bf16 v[92:95], v[152:155], v[184:187], v[92:95]
	v_mfma_f32_16x16x32_bf16 v[84:87], v[160:163], v[184:187], v[84:87]
	v_mfma_f32_16x16x32_bf16 v[76:79], v[152:155], v[192:195], v[76:79]
	v_mfma_f32_16x16x32_bf16 v[72:75], v[160:163], v[192:195], v[72:75]
	s_setprio 0
	s_barrier
	s_add_i32 s30, s56, s23
	v_add_u32_e32 v1, 0x1c000, v224
	v_lshl_add_u64 v[2:3], v[2:3], 0, s[6:7]
	s_mov_b32 m0, s30
	ds_read_b128 v[132:135], v1
	ds_read_b128 v[136:139], v1 offset:1024
	ds_read_b128 v[140:143], v1 offset:2048
	ds_read_b128 v[144:147], v1 offset:3072
	global_load_lds_dwordx4 v[2:3], off
	v_lshl_add_u64 v[2:3], v[212:213], 0, s[6:7]
	s_add_i32 m0, s30, 0x2000
	s_nop 0
	global_load_lds_dwordx4 v[2:3], off
	s_barrier
	s_waitcnt lgkmcnt(0)
	s_setprio 1
	s_waitcnt lgkmcnt(0)
	v_mfma_f32_16x16x32_bf16 v[128:131], v[132:135], v[164:167], v[128:131]
	v_mfma_f32_16x16x32_bf16 v[120:123], v[140:143], v[164:167], v[120:123]
	v_mfma_f32_16x16x32_bf16 v[112:115], v[132:135], v[172:175], v[112:115]
	v_mfma_f32_16x16x32_bf16 v[104:107], v[140:143], v[172:175], v[104:107]
	v_mfma_f32_16x16x32_bf16 v[96:99], v[132:135], v[180:183], v[96:99]
	v_mfma_f32_16x16x32_bf16 v[88:91], v[140:143], v[180:183], v[88:91]
	v_mfma_f32_16x16x32_bf16 v[80:83], v[132:135], v[188:191], v[80:83]
	v_mfma_f32_16x16x32_bf16 v[68:71], v[140:143], v[188:191], v[68:71]
	v_mfma_f32_16x16x32_bf16 v[128:131], v[136:139], v[168:171], v[128:131]
	v_mfma_f32_16x16x32_bf16 v[120:123], v[144:147], v[168:171], v[120:123]
	v_mfma_f32_16x16x32_bf16 v[112:115], v[136:139], v[176:179], v[112:115]
	v_mfma_f32_16x16x32_bf16 v[104:107], v[144:147], v[176:179], v[104:107]
	v_mfma_f32_16x16x32_bf16 v[96:99], v[136:139], v[184:187], v[96:99]
	v_mfma_f32_16x16x32_bf16 v[88:91], v[144:147], v[184:187], v[88:91]
	v_mfma_f32_16x16x32_bf16 v[80:83], v[136:139], v[192:195], v[80:83]
	v_mfma_f32_16x16x32_bf16 v[68:71], v[144:147], v[192:195], v[68:71]
	s_setprio 0
	s_mov_b32 m0, s43
	v_lshl_add_u64 v[2:3], v[214:215], 0, s[6:7]
	s_barrier
	ds_read_b128 v[188:191], v223 offset:49152
	ds_read_b128 v[192:195], v223 offset:50176
	ds_read_b128 v[180:183], v223 offset:51200
	ds_read_b128 v[184:187], v223 offset:52224
	ds_read_b128 v[172:175], v223 offset:53248
	ds_read_b128 v[176:179], v223 offset:54272
	ds_read_b128 v[164:167], v223 offset:55296
	ds_read_b128 v[168:171], v223 offset:56320
	global_load_lds_dwordx4 v[2:3], off
	v_lshl_add_u64 v[2:3], v[216:217], 0, s[6:7]
	s_mov_b32 m0, s44
	s_and_b64 vcc, exec, s[12:13]
	global_load_lds_dwordx4 v[2:3], off
	s_barrier
	s_waitcnt lgkmcnt(0)
	s_cbranch_vccnz .LBB0_1352
	s_setprio 1
	s_waitcnt lgkmcnt(0)
	v_mfma_f32_16x16x32_bf16 v[60:63], v[148:151], v[188:191], v[60:63]
	v_mfma_f32_16x16x32_bf16 v[52:55], v[156:159], v[188:191], v[52:55]
	v_mfma_f32_16x16x32_bf16 v[44:47], v[148:151], v[180:183], v[44:47]
	v_mfma_f32_16x16x32_bf16 v[36:39], v[156:159], v[180:183], v[36:39]
	v_mfma_f32_16x16x32_bf16 v[28:31], v[148:151], v[172:175], v[28:31]
	v_mfma_f32_16x16x32_bf16 v[20:23], v[156:159], v[172:175], v[20:23]
	v_mfma_f32_16x16x32_bf16 v[12:15], v[148:151], v[164:167], v[12:15]
	v_mfma_f32_16x16x32_bf16 v[2:5], v[156:159], v[164:167], v[4:7]
	v_mfma_f32_16x16x32_bf16 v[60:63], v[152:155], v[192:195], v[60:63]
	v_mfma_f32_16x16x32_bf16 v[52:55], v[160:163], v[192:195], v[52:55]
	v_mfma_f32_16x16x32_bf16 v[44:47], v[152:155], v[184:187], v[44:47]
	v_mfma_f32_16x16x32_bf16 v[36:39], v[160:163], v[184:187], v[36:39]
	v_mfma_f32_16x16x32_bf16 v[28:31], v[152:155], v[176:179], v[28:31]
	v_mfma_f32_16x16x32_bf16 v[20:23], v[160:163], v[176:179], v[20:23]
	v_mfma_f32_16x16x32_bf16 v[12:15], v[152:155], v[168:171], v[12:15]
	v_mfma_f32_16x16x32_bf16 v[4:7], v[160:163], v[168:171], v[2:5]
	s_setprio 0

.LBB0_1461:
	ds_read_b128 v[148:151], v205
	ds_read_b128 v[152:155], v205 offset:1024
	ds_read_b128 v[156:159], v205 offset:2048
	ds_read_b128 v[160:163], v205 offset:3072
	s_mov_b64 s[16:17], s[24:25]
	s_add_u32 s24, s16, 0x100
	s_addc_u32 s25, s17, 0
	s_cmp_eq_u32 s5, s53
	s_cselect_b32 s31, s21, s25
	s_cselect_b32 s30, s20, s24
	s_cselect_b32 s29, s23, s19
	s_cselect_b32 s28, s22, s6
	v_lshl_add_u64 v[2:3], s[16:17], 0, v[214:215]
	s_add_i32 m0, s36, 0xc000
	ds_read_b128 v[164:167], v230
	ds_read_b128 v[168:171], v230 offset:1024
	ds_read_b128 v[172:175], v230 offset:2048
	ds_read_b128 v[176:179], v230 offset:3072
	ds_read_b128 v[180:183], v230 offset:4096
	ds_read_b128 v[184:187], v230 offset:5120
	ds_read_b128 v[188:191], v230 offset:6144
	ds_read_b128 v[192:195], v230 offset:7168
	global_load_lds_dwordx4 v[2:3], off
	v_lshl_add_u64 v[2:3], s[16:17], 0, v[216:217]
	s_add_i32 m0, s36, 0xe000
	s_nop 0
	global_load_lds_dwordx4 v[2:3], off
	s_waitcnt lgkmcnt(8)
	s_barrier
	s_waitcnt lgkmcnt(0)
	s_setprio 1
	s_waitcnt lgkmcnt(0)
	v_mfma_f32_16x16x32_bf16 v[84:87], v[148:151], v[164:167], v[84:87]
	v_mfma_f32_16x16x32_bf16 v[76:79], v[156:159], v[164:167], v[76:79]
	v_mfma_f32_16x16x32_bf16 v[64:67], v[148:151], v[172:175], v[64:67]
	v_mfma_f32_16x16x32_bf16 v[60:63], v[156:159], v[172:175], v[60:63]
	v_mfma_f32_16x16x32_bf16 v[48:51], v[148:151], v[180:183], v[48:51]
	v_mfma_f32_16x16x32_bf16 v[44:47], v[156:159], v[180:183], v[44:47]
	v_mfma_f32_16x16x32_bf16 v[32:35], v[148:151], v[188:191], v[32:35]
	v_mfma_f32_16x16x32_bf16 v[24:27], v[156:159], v[188:191], v[24:27]
	v_mfma_f32_16x16x32_bf16 v[84:87], v[152:155], v[168:171], v[84:87]
	v_mfma_f32_16x16x32_bf16 v[76:79], v[160:163], v[168:171], v[76:79]
	v_mfma_f32_16x16x32_bf16 v[64:67], v[152:155], v[176:179], v[64:67]
	v_mfma_f32_16x16x32_bf16 v[60:63], v[160:163], v[176:179], v[60:63]
	v_mfma_f32_16x16x32_bf16 v[48:51], v[152:155], v[184:187], v[48:51]
	v_mfma_f32_16x16x32_bf16 v[44:47], v[160:163], v[184:187], v[44:47]
	v_mfma_f32_16x16x32_bf16 v[32:35], v[152:155], v[192:195], v[32:35]
	v_mfma_f32_16x16x32_bf16 v[24:27], v[160:163], v[192:195], v[24:27]
	s_setprio 0
	s_barrier
	s_add_i32 s16, s49, s34
	v_lshl_add_u64 v[2:3], s[28:29], 0, v[198:199]
	s_mov_b32 m0, s16
	ds_read_b128 v[132:135], v232
	ds_read_b128 v[136:139], v232 offset:1024
	ds_read_b128 v[140:143], v232 offset:2048
	ds_read_b128 v[144:147], v232 offset:3072
	global_load_lds_dwordx4 v[2:3], off
	v_lshl_add_u64 v[220:221], s[28:29], 0, v[202:203]
	s_add_i32 m0, s16, 0x2000
	s_nop 0
	global_load_lds_dwordx4 v[220:221], off
	s_barrier
	s_waitcnt lgkmcnt(0)
	s_setprio 1
	s_waitcnt lgkmcnt(0)
	v_mfma_f32_16x16x32_bf16 v[72:75], v[132:135], v[164:167], v[72:75]
	v_mfma_f32_16x16x32_bf16 v[68:71], v[140:143], v[164:167], v[68:71]
	v_mfma_f32_16x16x32_bf16 v[56:59], v[132:135], v[172:175], v[56:59]
	v_mfma_f32_16x16x32_bf16 v[52:55], v[140:143], v[172:175], v[52:55]
	v_mfma_f32_16x16x32_bf16 v[40:43], v[132:135], v[180:183], v[40:43]
	v_mfma_f32_16x16x32_bf16 v[36:39], v[140:143], v[180:183], v[36:39]
	v_mfma_f32_16x16x32_bf16 v[20:23], v[132:135], v[188:191], v[20:23]
	v_mfma_f32_16x16x32_bf16 v[12:15], v[140:143], v[188:191], v[12:15]
	v_mfma_f32_16x16x32_bf16 v[72:75], v[136:139], v[168:171], v[72:75]
	v_mfma_f32_16x16x32_bf16 v[68:71], v[144:147], v[168:171], v[68:71]
	v_mfma_f32_16x16x32_bf16 v[56:59], v[136:139], v[176:179], v[56:59]
	v_mfma_f32_16x16x32_bf16 v[52:55], v[144:147], v[176:179], v[52:55]
	v_mfma_f32_16x16x32_bf16 v[40:43], v[136:139], v[184:187], v[40:43]
	v_mfma_f32_16x16x32_bf16 v[36:39], v[144:147], v[184:187], v[36:39]
	v_mfma_f32_16x16x32_bf16 v[20:23], v[136:139], v[192:195], v[20:23]
	v_mfma_f32_16x16x32_bf16 v[12:15], v[144:147], v[192:195], v[12:15]
	s_setprio 0
	s_mov_b32 m0, s36
	v_lshl_add_u64 v[222:223], s[30:31], 0, v[196:197]
	s_barrier
	ds_read_b128 v[188:191], v230 offset:16384
	ds_read_b128 v[192:195], v230 offset:17408
	ds_read_b128 v[180:183], v230 offset:18432
	ds_read_b128 v[184:187], v230 offset:19456
	ds_read_b128 v[172:175], v230 offset:20480
	ds_read_b128 v[176:179], v230 offset:21504
	ds_read_b128 v[164:167], v230 offset:22528
	ds_read_b128 v[168:171], v230 offset:23552
	global_load_lds_dwordx4 v[222:223], off
	v_lshl_add_u64 v[224:225], s[30:31], 0, v[200:201]
	s_mov_b32 m0, s37
	v_cmp_ne_u32_e64 s[16:17], 1, v233
	global_load_lds_dwordx4 v[224:225], off
	s_barrier
	s_waitcnt lgkmcnt(0)
	s_andn2_b64 vcc, exec, s[26:27]
	s_cbranch_vccnz .LBB0_1463
	s_setprio 1
	s_waitcnt lgkmcnt(0)
	v_mfma_f32_16x16x32_bf16 v[128:131], v[148:151], v[188:191], v[128:131]
	v_mfma_f32_16x16x32_bf16 v[124:127], v[156:159], v[188:191], v[124:127]
	v_mfma_f32_16x16x32_bf16 v[112:115], v[148:151], v[180:183], v[112:115]
	v_mfma_f32_16x16x32_bf16 v[108:111], v[156:159], v[180:183], v[108:111]
	v_mfma_f32_16x16x32_bf16 v[96:99], v[148:151], v[172:175], v[96:99]
	v_mfma_f32_16x16x32_bf16 v[92:95], v[156:159], v[172:175], v[92:95]
	v_mfma_f32_16x16x32_bf16 v[28:31], v[148:151], v[164:167], v[28:31]
	v_mfma_f32_16x16x32_bf16 v[16:19], v[156:159], v[164:167], v[16:19]
	v_mfma_f32_16x16x32_bf16 v[128:131], v[152:155], v[192:195], v[128:131]
	v_mfma_f32_16x16x32_bf16 v[124:127], v[160:163], v[192:195], v[124:127]
	v_mfma_f32_16x16x32_bf16 v[112:115], v[152:155], v[184:187], v[112:115]
	v_mfma_f32_16x16x32_bf16 v[108:111], v[160:163], v[184:187], v[108:111]
	v_mfma_f32_16x16x32_bf16 v[96:99], v[152:155], v[176:179], v[96:99]
	v_mfma_f32_16x16x32_bf16 v[92:95], v[160:163], v[176:179], v[92:95]
	v_mfma_f32_16x16x32_bf16 v[28:31], v[152:155], v[168:171], v[28:31]
	v_mfma_f32_16x16x32_bf16 v[16:19], v[160:163], v[168:171], v[16:19]
	s_setprio 0

.LBB0_1465:
	s_add_i32 s54, 0, 0x18000
	v_add_u32_e32 v1, s54, v226
	s_barrier
	ds_read_b128 v[148:151], v1
	ds_read_b128 v[152:155], v1 offset:1024
	ds_read_b128 v[156:159], v1 offset:2048
	ds_read_b128 v[160:163], v1 offset:3072
	s_add_u32 s30, s30, 0xb0000
	s_addc_u32 s31, s31, 0
	s_mov_b32 m0, s40
	v_lshl_add_u64 v[132:133], s[30:31], 0, v[196:197]
	ds_read_b128 v[164:167], v230 offset:32768
	ds_read_b128 v[168:171], v230 offset:33792
	ds_read_b128 v[172:175], v230 offset:34816
	ds_read_b128 v[176:179], v230 offset:35840
	ds_read_b128 v[180:183], v230 offset:36864
	ds_read_b128 v[184:187], v230 offset:37888
	ds_read_b128 v[188:191], v230 offset:38912
	ds_read_b128 v[192:195], v230 offset:39936
	global_load_lds_dwordx4 v[132:133], off
	v_lshl_add_u64 v[132:133], s[30:31], 0, v[200:201]
	s_mov_b32 m0, s41
	s_nop 0
	global_load_lds_dwordx4 v[132:133], off
	s_waitcnt lgkmcnt(8)
	s_barrier
	s_waitcnt lgkmcnt(0)
	s_setprio 1
	s_waitcnt lgkmcnt(0)
	v_mfma_f32_16x16x32_bf16 v[84:87], v[148:151], v[164:167], v[84:87]
	v_mfma_f32_16x16x32_bf16 v[76:79], v[156:159], v[164:167], v[76:79]
	v_mfma_f32_16x16x32_bf16 v[64:67], v[148:151], v[172:175], v[64:67]
	v_mfma_f32_16x16x32_bf16 v[60:63], v[156:159], v[172:175], v[60:63]
	v_mfma_f32_16x16x32_bf16 v[48:51], v[148:151], v[180:183], v[48:51]
	v_mfma_f32_16x16x32_bf16 v[44:47], v[156:159], v[180:183], v[44:47]
	v_mfma_f32_16x16x32_bf16 v[32:35], v[148:151], v[188:191], v[32:35]
	v_mfma_f32_16x16x32_bf16 v[24:27], v[156:159], v[188:191], v[24:27]
	v_mfma_f32_16x16x32_bf16 v[84:87], v[152:155], v[168:171], v[84:87]
	v_mfma_f32_16x16x32_bf16 v[76:79], v[160:163], v[168:171], v[76:79]
	v_mfma_f32_16x16x32_bf16 v[64:67], v[152:155], v[176:179], v[64:67]
	v_mfma_f32_16x16x32_bf16 v[60:63], v[160:163], v[176:179], v[60:63]
	v_mfma_f32_16x16x32_bf16 v[48:51], v[152:155], v[184:187], v[48:51]
	v_mfma_f32_16x16x32_bf16 v[44:47], v[160:163], v[184:187], v[44:47]
	v_mfma_f32_16x16x32_bf16 v[32:35], v[152:155], v[192:195], v[32:35]
	v_mfma_f32_16x16x32_bf16 v[24:27], v[160:163], v[192:195], v[24:27]
	s_setprio 0
	s_barrier
	s_add_i32 s30, s54, s34
	v_add_u32_e32 v1, 0x1c000, v231
	v_lshl_add_u64 v[2:3], v[2:3], 0, s[8:9]
	s_mov_b32 m0, s30
	ds_read_b128 v[132:135], v1
	ds_read_b128 v[136:139], v1 offset:1024
	ds_read_b128 v[140:143], v1 offset:2048
	ds_read_b128 v[144:147], v1 offset:3072
	global_load_lds_dwordx4 v[2:3], off
	v_lshl_add_u64 v[2:3], v[220:221], 0, s[8:9]
	s_add_i32 m0, s30, 0x2000
	s_nop 0
	global_load_lds_dwordx4 v[2:3], off
	s_barrier
	s_waitcnt lgkmcnt(0)
	s_setprio 1
	s_waitcnt lgkmcnt(0)
	v_mfma_f32_16x16x32_bf16 v[72:75], v[132:135], v[164:167], v[72:75]
	v_mfma_f32_16x16x32_bf16 v[68:71], v[140:143], v[164:167], v[68:71]
	v_mfma_f32_16x16x32_bf16 v[56:59], v[132:135], v[172:175], v[56:59]
	v_mfma_f32_16x16x32_bf16 v[52:55], v[140:143], v[172:175], v[52:55]
	v_mfma_f32_16x16x32_bf16 v[40:43], v[132:135], v[180:183], v[40:43]
	v_mfma_f32_16x16x32_bf16 v[36:39], v[140:143], v[180:183], v[36:39]
	v_mfma_f32_16x16x32_bf16 v[20:23], v[132:135], v[188:191], v[20:23]
	v_mfma_f32_16x16x32_bf16 v[12:15], v[140:143], v[188:191], v[12:15]
	v_mfma_f32_16x16x32_bf16 v[72:75], v[136:139], v[168:171], v[72:75]
	v_mfma_f32_16x16x32_bf16 v[68:71], v[144:147], v[168:171], v[68:71]
	v_mfma_f32_16x16x32_bf16 v[56:59], v[136:139], v[176:179], v[56:59]
	v_mfma_f32_16x16x32_bf16 v[52:55], v[144:147], v[176:179], v[52:55]
	v_mfma_f32_16x16x32_bf16 v[40:43], v[136:139], v[184:187], v[40:43]
	v_mfma_f32_16x16x32_bf16 v[36:39], v[144:147], v[184:187], v[36:39]
	v_mfma_f32_16x16x32_bf16 v[20:23], v[136:139], v[192:195], v[20:23]
	v_mfma_f32_16x16x32_bf16 v[12:15], v[144:147], v[192:195], v[12:15]
	s_setprio 0
	s_mov_b32 m0, s43
	v_lshl_add_u64 v[2:3], v[222:223], 0, s[8:9]
	s_barrier
	ds_read_b128 v[188:191], v230 offset:49152
	ds_read_b128 v[192:195], v230 offset:50176
	ds_read_b128 v[180:183], v230 offset:51200
	ds_read_b128 v[184:187], v230 offset:52224
	ds_read_b128 v[172:175], v230 offset:53248
	ds_read_b128 v[176:179], v230 offset:54272
	ds_read_b128 v[164:167], v230 offset:55296
	ds_read_b128 v[168:171], v230 offset:56320
	global_load_lds_dwordx4 v[2:3], off
	v_lshl_add_u64 v[2:3], v[224:225], 0, s[8:9]
	s_mov_b32 m0, s44
	s_and_b64 vcc, exec, s[16:17]
	global_load_lds_dwordx4 v[2:3], off
	s_barrier
	s_waitcnt lgkmcnt(0)
	s_cbranch_vccnz .LBB0_1467
	s_setprio 1
	s_waitcnt lgkmcnt(0)
	v_mfma_f32_16x16x32_bf16 v[128:131], v[148:151], v[188:191], v[128:131]
	v_mfma_f32_16x16x32_bf16 v[124:127], v[156:159], v[188:191], v[124:127]
	v_mfma_f32_16x16x32_bf16 v[112:115], v[148:151], v[180:183], v[112:115]
	v_mfma_f32_16x16x32_bf16 v[108:111], v[156:159], v[180:183], v[108:111]
	v_mfma_f32_16x16x32_bf16 v[96:99], v[148:151], v[172:175], v[96:99]
	v_mfma_f32_16x16x32_bf16 v[92:95], v[156:159], v[172:175], v[92:95]
	v_mfma_f32_16x16x32_bf16 v[28:31], v[148:151], v[164:167], v[28:31]
	v_mfma_f32_16x16x32_bf16 v[16:19], v[156:159], v[164:167], v[16:19]
	v_mfma_f32_16x16x32_bf16 v[128:131], v[152:155], v[192:195], v[128:131]
	v_mfma_f32_16x16x32_bf16 v[124:127], v[160:163], v[192:195], v[124:127]
	v_mfma_f32_16x16x32_bf16 v[112:115], v[152:155], v[184:187], v[112:115]
	v_mfma_f32_16x16x32_bf16 v[108:111], v[160:163], v[184:187], v[108:111]
	v_mfma_f32_16x16x32_bf16 v[96:99], v[152:155], v[176:179], v[96:99]
	v_mfma_f32_16x16x32_bf16 v[92:95], v[160:163], v[176:179], v[92:95]
	v_mfma_f32_16x16x32_bf16 v[28:31], v[152:155], v[168:171], v[28:31]
	v_mfma_f32_16x16x32_bf16 v[16:19], v[160:163], v[168:171], v[16:19]
	s_setprio 0

.LBB0_1682:
	ds_read_b128 v[148:151], v223
	ds_read_b128 v[152:155], v223 offset:1024
	ds_read_b128 v[156:159], v223 offset:2048
	ds_read_b128 v[160:163], v223 offset:3072
	s_add_u32 s16, s20, 0xfffc0080
	s_addc_u32 s17, s21, -1
	s_cmp_eq_u32 s35, s48
	s_cselect_b32 s41, s2, s17
	s_cselect_b32 s40, s5, s16
	s_cselect_b32 s23, s24, s43
	s_cselect_b32 s22, s31, s42
	v_lshl_add_u64 v[2:3], s[20:21], 0, v[204:205]
	s_add_i32 m0, s44, 0xc000
	ds_read_b128 v[164:167], v224
	ds_read_b128 v[168:171], v224 offset:1024
	ds_read_b128 v[172:175], v224 offset:2048
	ds_read_b128 v[176:179], v224 offset:3072
	ds_read_b128 v[180:183], v224 offset:4096
	ds_read_b128 v[184:187], v224 offset:5120
	ds_read_b128 v[188:191], v224 offset:6144
	ds_read_b128 v[192:195], v224 offset:7168
	global_load_lds_dwordx4 v[2:3], off
	v_lshl_add_u64 v[2:3], s[20:21], 0, v[206:207]
	s_add_i32 m0, s44, 0xe000
	s_nop 0
	global_load_lds_dwordx4 v[2:3], off
	s_waitcnt lgkmcnt(8)
	s_barrier
	s_waitcnt lgkmcnt(0)
	s_setprio 1
	s_waitcnt lgkmcnt(0)
	v_mfma_f32_16x16x32_bf16 v[128:131], v[148:151], v[164:167], v[128:131]
	v_mfma_f32_16x16x32_bf16 v[124:127], v[156:159], v[164:167], v[124:127]
	v_mfma_f32_16x16x32_bf16 v[112:115], v[148:151], v[172:175], v[112:115]
	v_mfma_f32_16x16x32_bf16 v[108:111], v[156:159], v[172:175], v[108:111]
	v_mfma_f32_16x16x32_bf16 v[96:99], v[148:151], v[180:183], v[96:99]
	v_mfma_f32_16x16x32_bf16 v[92:95], v[156:159], v[180:183], v[92:95]
	v_mfma_f32_16x16x32_bf16 v[80:83], v[148:151], v[188:191], v[80:83]
	v_mfma_f32_16x16x32_bf16 v[76:79], v[156:159], v[188:191], v[76:79]
	v_mfma_f32_16x16x32_bf16 v[128:131], v[152:155], v[168:171], v[128:131]
	v_mfma_f32_16x16x32_bf16 v[124:127], v[160:163], v[168:171], v[124:127]
	v_mfma_f32_16x16x32_bf16 v[112:115], v[152:155], v[176:179], v[112:115]
	v_mfma_f32_16x16x32_bf16 v[108:111], v[160:163], v[176:179], v[108:111]
	v_mfma_f32_16x16x32_bf16 v[96:99], v[152:155], v[184:187], v[96:99]
	v_mfma_f32_16x16x32_bf16 v[92:95], v[160:163], v[184:187], v[92:95]
	v_mfma_f32_16x16x32_bf16 v[80:83], v[152:155], v[192:195], v[80:83]
	v_mfma_f32_16x16x32_bf16 v[76:79], v[160:163], v[192:195], v[76:79]
	s_setprio 0
	s_barrier
	s_add_i32 s16, s61, s9
	v_lshl_add_u64 v[2:3], s[22:23], 0, v[198:199]
	s_mov_b32 m0, s16
	ds_read_b128 v[132:135], v226
	ds_read_b128 v[136:139], v226 offset:1024
	ds_read_b128 v[140:143], v226 offset:2048
	ds_read_b128 v[144:147], v226 offset:3072
	global_load_lds_dwordx4 v[2:3], off
	v_lshl_add_u64 v[212:213], s[22:23], 0, v[202:203]
	s_add_i32 m0, s16, 0x2000
	s_nop 0
	global_load_lds_dwordx4 v[212:213], off
	s_barrier
	s_waitcnt lgkmcnt(0)
	s_setprio 1
	s_waitcnt lgkmcnt(0)
	v_mfma_f32_16x16x32_bf16 v[120:123], v[132:135], v[164:167], v[120:123]
	v_mfma_f32_16x16x32_bf16 v[116:119], v[140:143], v[164:167], v[116:119]
	v_mfma_f32_16x16x32_bf16 v[104:107], v[132:135], v[172:175], v[104:107]
	v_mfma_f32_16x16x32_bf16 v[100:103], v[140:143], v[172:175], v[100:103]
	v_mfma_f32_16x16x32_bf16 v[88:91], v[132:135], v[180:183], v[88:91]
	v_mfma_f32_16x16x32_bf16 v[84:87], v[140:143], v[180:183], v[84:87]
	v_mfma_f32_16x16x32_bf16 v[72:75], v[132:135], v[188:191], v[72:75]
	v_mfma_f32_16x16x32_bf16 v[68:71], v[140:143], v[188:191], v[68:71]
	v_mfma_f32_16x16x32_bf16 v[120:123], v[136:139], v[168:171], v[120:123]
	v_mfma_f32_16x16x32_bf16 v[116:119], v[144:147], v[168:171], v[116:119]
	v_mfma_f32_16x16x32_bf16 v[104:107], v[136:139], v[176:179], v[104:107]
	v_mfma_f32_16x16x32_bf16 v[100:103], v[144:147], v[176:179], v[100:103]
	v_mfma_f32_16x16x32_bf16 v[88:91], v[136:139], v[184:187], v[88:91]
	v_mfma_f32_16x16x32_bf16 v[84:87], v[144:147], v[184:187], v[84:87]
	v_mfma_f32_16x16x32_bf16 v[72:75], v[136:139], v[192:195], v[72:75]
	v_mfma_f32_16x16x32_bf16 v[68:71], v[144:147], v[192:195], v[68:71]
	s_setprio 0
	s_mov_b32 m0, s44
	v_lshl_add_u64 v[214:215], s[40:41], 0, v[196:197]
	s_barrier
	ds_read_b128 v[188:191], v224 offset:16384
	ds_read_b128 v[192:195], v224 offset:17408
	ds_read_b128 v[180:183], v224 offset:18432
	ds_read_b128 v[184:187], v224 offset:19456
	ds_read_b128 v[172:175], v224 offset:20480
	ds_read_b128 v[176:179], v224 offset:21504
	ds_read_b128 v[164:167], v224 offset:22528
	ds_read_b128 v[168:171], v224 offset:23552
	global_load_lds_dwordx4 v[214:215], off
	v_lshl_add_u64 v[216:217], s[40:41], 0, v[200:201]
	s_mov_b32 m0, s45
	v_cmp_ne_u32_e64 s[16:17], 1, v236
	global_load_lds_dwordx4 v[216:217], off
	s_barrier
	s_waitcnt lgkmcnt(0)
	s_andn2_b64 vcc, exec, s[18:19]
	s_cbranch_vccnz .LBB0_1684
	s_setprio 1
	s_waitcnt lgkmcnt(0)
	v_mfma_f32_16x16x32_bf16 v[64:67], v[148:151], v[188:191], v[64:67]
	v_mfma_f32_16x16x32_bf16 v[60:63], v[156:159], v[188:191], v[60:63]
	v_mfma_f32_16x16x32_bf16 v[48:51], v[148:151], v[180:183], v[48:51]
	v_mfma_f32_16x16x32_bf16 v[44:47], v[156:159], v[180:183], v[44:47]
	v_mfma_f32_16x16x32_bf16 v[32:35], v[148:151], v[172:175], v[32:35]
	v_mfma_f32_16x16x32_bf16 v[28:31], v[156:159], v[172:175], v[28:31]
	v_mfma_f32_16x16x32_bf16 v[16:19], v[148:151], v[164:167], v[16:19]
	v_mfma_f32_16x16x32_bf16 v[12:15], v[156:159], v[164:167], v[12:15]
	v_mfma_f32_16x16x32_bf16 v[64:67], v[152:155], v[192:195], v[64:67]
	v_mfma_f32_16x16x32_bf16 v[60:63], v[160:163], v[192:195], v[60:63]
	v_mfma_f32_16x16x32_bf16 v[48:51], v[152:155], v[184:187], v[48:51]
	v_mfma_f32_16x16x32_bf16 v[44:47], v[160:163], v[184:187], v[44:47]
	v_mfma_f32_16x16x32_bf16 v[32:35], v[152:155], v[176:179], v[32:35]
	v_mfma_f32_16x16x32_bf16 v[28:31], v[160:163], v[176:179], v[28:31]
	v_mfma_f32_16x16x32_bf16 v[16:19], v[152:155], v[168:171], v[16:19]
	v_mfma_f32_16x16x32_bf16 v[12:15], v[160:163], v[168:171], v[12:15]
	s_setprio 0

.LBB0_1686:
	s_add_i32 s49, 0, 0x18000
	v_add_u32_e32 v1, s49, v219
	s_barrier
	ds_read_b128 v[148:151], v1
	ds_read_b128 v[152:155], v1 offset:1024
	ds_read_b128 v[156:159], v1 offset:2048
	ds_read_b128 v[160:163], v1 offset:3072
	s_add_u32 s40, s40, 0x40000
	s_addc_u32 s41, s41, 0
	s_mov_b32 m0, s52
	v_lshl_add_u64 v[132:133], s[40:41], 0, v[196:197]
	ds_read_b128 v[164:167], v224 offset:32768
	ds_read_b128 v[168:171], v224 offset:33792
	ds_read_b128 v[172:175], v224 offset:34816
	ds_read_b128 v[176:179], v224 offset:35840
	ds_read_b128 v[180:183], v224 offset:36864
	ds_read_b128 v[184:187], v224 offset:37888
	ds_read_b128 v[188:191], v224 offset:38912
	ds_read_b128 v[192:195], v224 offset:39936
	global_load_lds_dwordx4 v[132:133], off
	v_lshl_add_u64 v[132:133], s[40:41], 0, v[200:201]
	s_mov_b32 m0, s53
	s_nop 0
	global_load_lds_dwordx4 v[132:133], off
	s_waitcnt lgkmcnt(8)
	s_barrier
	s_waitcnt lgkmcnt(0)
	s_setprio 1
	s_waitcnt lgkmcnt(0)
	v_mfma_f32_16x16x32_bf16 v[128:131], v[148:151], v[164:167], v[128:131]
	v_mfma_f32_16x16x32_bf16 v[124:127], v[156:159], v[164:167], v[124:127]
	v_mfma_f32_16x16x32_bf16 v[112:115], v[148:151], v[172:175], v[112:115]
	v_mfma_f32_16x16x32_bf16 v[108:111], v[156:159], v[172:175], v[108:111]
	v_mfma_f32_16x16x32_bf16 v[96:99], v[148:151], v[180:183], v[96:99]
	v_mfma_f32_16x16x32_bf16 v[92:95], v[156:159], v[180:183], v[92:95]
	v_mfma_f32_16x16x32_bf16 v[80:83], v[148:151], v[188:191], v[80:83]
	v_mfma_f32_16x16x32_bf16 v[76:79], v[156:159], v[188:191], v[76:79]
	v_mfma_f32_16x16x32_bf16 v[128:131], v[152:155], v[168:171], v[128:131]
	v_mfma_f32_16x16x32_bf16 v[124:127], v[160:163], v[168:171], v[124:127]
	v_mfma_f32_16x16x32_bf16 v[112:115], v[152:155], v[176:179], v[112:115]
	v_mfma_f32_16x16x32_bf16 v[108:111], v[160:163], v[176:179], v[108:111]
	v_mfma_f32_16x16x32_bf16 v[96:99], v[152:155], v[184:187], v[96:99]
	v_mfma_f32_16x16x32_bf16 v[92:95], v[160:163], v[184:187], v[92:95]
	v_mfma_f32_16x16x32_bf16 v[80:83], v[152:155], v[192:195], v[80:83]
	v_mfma_f32_16x16x32_bf16 v[76:79], v[160:163], v[192:195], v[76:79]
	s_setprio 0
	s_barrier
	s_add_i32 s40, s49, s9
	v_add_u32_e32 v1, 0x1c000, v225
	v_lshl_add_u64 v[2:3], v[2:3], 0, s[26:27]
	s_mov_b32 m0, s40
	ds_read_b128 v[132:135], v1
	ds_read_b128 v[136:139], v1 offset:1024
	ds_read_b128 v[140:143], v1 offset:2048
	ds_read_b128 v[144:147], v1 offset:3072
	global_load_lds_dwordx4 v[2:3], off
	v_lshl_add_u64 v[2:3], v[212:213], 0, s[26:27]
	s_add_i32 m0, s40, 0x2000
	s_nop 0
	global_load_lds_dwordx4 v[2:3], off
	s_barrier
	s_waitcnt lgkmcnt(0)
	s_setprio 1
	s_waitcnt lgkmcnt(0)
	v_mfma_f32_16x16x32_bf16 v[120:123], v[132:135], v[164:167], v[120:123]
	v_mfma_f32_16x16x32_bf16 v[116:119], v[140:143], v[164:167], v[116:119]
	v_mfma_f32_16x16x32_bf16 v[104:107], v[132:135], v[172:175], v[104:107]
	v_mfma_f32_16x16x32_bf16 v[100:103], v[140:143], v[172:175], v[100:103]
	v_mfma_f32_16x16x32_bf16 v[88:91], v[132:135], v[180:183], v[88:91]
	v_mfma_f32_16x16x32_bf16 v[84:87], v[140:143], v[180:183], v[84:87]
	v_mfma_f32_16x16x32_bf16 v[72:75], v[132:135], v[188:191], v[72:75]
	v_mfma_f32_16x16x32_bf16 v[68:71], v[140:143], v[188:191], v[68:71]
	v_mfma_f32_16x16x32_bf16 v[120:123], v[136:139], v[168:171], v[120:123]
	v_mfma_f32_16x16x32_bf16 v[116:119], v[144:147], v[168:171], v[116:119]
	v_mfma_f32_16x16x32_bf16 v[104:107], v[136:139], v[176:179], v[104:107]
	v_mfma_f32_16x16x32_bf16 v[100:103], v[144:147], v[176:179], v[100:103]
	v_mfma_f32_16x16x32_bf16 v[88:91], v[136:139], v[184:187], v[88:91]
	v_mfma_f32_16x16x32_bf16 v[84:87], v[144:147], v[184:187], v[84:87]
	v_mfma_f32_16x16x32_bf16 v[72:75], v[136:139], v[192:195], v[72:75]
	v_mfma_f32_16x16x32_bf16 v[68:71], v[144:147], v[192:195], v[68:71]
	s_setprio 0
	s_mov_b32 m0, s55
	v_lshl_add_u64 v[2:3], v[214:215], 0, s[26:27]
	s_barrier
	ds_read_b128 v[188:191], v224 offset:49152
	ds_read_b128 v[192:195], v224 offset:50176
	ds_read_b128 v[180:183], v224 offset:51200
	ds_read_b128 v[184:187], v224 offset:52224
	ds_read_b128 v[172:175], v224 offset:53248
	ds_read_b128 v[176:179], v224 offset:54272
	ds_read_b128 v[164:167], v224 offset:55296
	ds_read_b128 v[168:171], v224 offset:56320
	global_load_lds_dwordx4 v[2:3], off
	v_lshl_add_u64 v[2:3], v[216:217], 0, s[26:27]
	s_mov_b32 m0, s56
	s_and_b64 vcc, exec, s[16:17]
	global_load_lds_dwordx4 v[2:3], off
	s_barrier
	s_waitcnt lgkmcnt(0)
	s_cbranch_vccnz .LBB0_1688
	s_setprio 1
	s_waitcnt lgkmcnt(0)
	v_mfma_f32_16x16x32_bf16 v[64:67], v[148:151], v[188:191], v[64:67]
	v_mfma_f32_16x16x32_bf16 v[60:63], v[156:159], v[188:191], v[60:63]
	v_mfma_f32_16x16x32_bf16 v[48:51], v[148:151], v[180:183], v[48:51]
	v_mfma_f32_16x16x32_bf16 v[44:47], v[156:159], v[180:183], v[44:47]
	v_mfma_f32_16x16x32_bf16 v[32:35], v[148:151], v[172:175], v[32:35]
	v_mfma_f32_16x16x32_bf16 v[28:31], v[156:159], v[172:175], v[28:31]
	v_mfma_f32_16x16x32_bf16 v[16:19], v[148:151], v[164:167], v[16:19]
	v_mfma_f32_16x16x32_bf16 v[12:15], v[156:159], v[164:167], v[12:15]
	v_mfma_f32_16x16x32_bf16 v[64:67], v[152:155], v[192:195], v[64:67]
	v_mfma_f32_16x16x32_bf16 v[60:63], v[160:163], v[192:195], v[60:63]
	v_mfma_f32_16x16x32_bf16 v[48:51], v[152:155], v[184:187], v[48:51]
	v_mfma_f32_16x16x32_bf16 v[44:47], v[160:163], v[184:187], v[44:47]
	v_mfma_f32_16x16x32_bf16 v[32:35], v[152:155], v[176:179], v[32:35]
	v_mfma_f32_16x16x32_bf16 v[28:31], v[160:163], v[176:179], v[28:31]
	v_mfma_f32_16x16x32_bf16 v[16:19], v[152:155], v[168:171], v[16:19]
	v_mfma_f32_16x16x32_bf16 v[12:15], v[160:163], v[168:171], v[12:15]
	s_setprio 0

.LBB0_1888:
	ds_read_b128 v[148:151], v232
	ds_read_b128 v[152:155], v232 offset:1024
	ds_read_b128 v[156:159], v232 offset:2048
	ds_read_b128 v[160:163], v232 offset:3072
	s_add_u32 s12, s20, 0xffff0080
	s_addc_u32 s13, s21, -1
	s_cmp_eq_u32 s52, s55
	s_cselect_b32 s25, s17, s13
	s_cselect_b32 s24, s49, s12
	s_cselect_b32 s23, s50, s54
	s_cselect_b32 s22, s51, s53
	v_lshl_add_u64 v[2:3], s[20:21], 0, v[220:221]
	s_add_i32 m0, s30, 0xc000
	ds_read_b128 v[164:167], v233
	ds_read_b128 v[168:171], v233 offset:1024
	ds_read_b128 v[172:175], v233 offset:2048
	ds_read_b128 v[176:179], v233 offset:3072
	ds_read_b128 v[180:183], v233 offset:4096
	ds_read_b128 v[184:187], v233 offset:5120
	ds_read_b128 v[188:191], v233 offset:6144
	ds_read_b128 v[192:195], v233 offset:7168
	global_load_lds_dwordx4 v[2:3], off
	v_lshl_add_u64 v[2:3], s[20:21], 0, v[222:223]
	s_add_i32 m0, s30, 0xe000
	s_nop 0
	global_load_lds_dwordx4 v[2:3], off
	s_waitcnt lgkmcnt(8)
	s_barrier
	s_waitcnt lgkmcnt(0)
	s_setprio 1
	s_waitcnt lgkmcnt(0)
	v_mfma_f32_16x16x32_bf16 v[128:131], v[148:151], v[164:167], v[128:131]
	v_mfma_f32_16x16x32_bf16 v[124:127], v[156:159], v[164:167], v[124:127]
	v_mfma_f32_16x16x32_bf16 v[112:115], v[148:151], v[172:175], v[112:115]
	v_mfma_f32_16x16x32_bf16 v[108:111], v[156:159], v[172:175], v[108:111]
	v_mfma_f32_16x16x32_bf16 v[96:99], v[148:151], v[180:183], v[96:99]
	v_mfma_f32_16x16x32_bf16 v[92:95], v[156:159], v[180:183], v[92:95]
	v_mfma_f32_16x16x32_bf16 v[80:83], v[148:151], v[188:191], v[80:83]
	v_mfma_f32_16x16x32_bf16 v[76:79], v[156:159], v[188:191], v[76:79]
	v_mfma_f32_16x16x32_bf16 v[128:131], v[152:155], v[168:171], v[128:131]
	v_mfma_f32_16x16x32_bf16 v[124:127], v[160:163], v[168:171], v[124:127]
	v_mfma_f32_16x16x32_bf16 v[112:115], v[152:155], v[176:179], v[112:115]
	v_mfma_f32_16x16x32_bf16 v[108:111], v[160:163], v[176:179], v[108:111]
	v_mfma_f32_16x16x32_bf16 v[96:99], v[152:155], v[184:187], v[96:99]
	v_mfma_f32_16x16x32_bf16 v[92:95], v[160:163], v[184:187], v[92:95]
	v_mfma_f32_16x16x32_bf16 v[80:83], v[152:155], v[192:195], v[80:83]
	v_mfma_f32_16x16x32_bf16 v[76:79], v[160:163], v[192:195], v[76:79]
	s_setprio 0
	s_barrier
	s_add_i32 s12, s43, s29
	v_add_u32_e32 v0, 0x14000, v234
	v_lshl_add_u64 v[2:3], s[22:23], 0, v[196:197]
	s_mov_b32 m0, s12
	ds_read_b128 v[132:135], v0
	ds_read_b128 v[136:139], v0 offset:1024
	ds_read_b128 v[140:143], v0 offset:2048
	ds_read_b128 v[144:147], v0 offset:3072
	global_load_lds_dwordx4 v[2:3], off
	v_lshl_add_u64 v[224:225], s[22:23], 0, v[198:199]
	s_add_i32 m0, s12, 0x2000
	s_nop 0
	global_load_lds_dwordx4 v[224:225], off
	s_barrier
	s_waitcnt lgkmcnt(0)
	s_setprio 1
	s_waitcnt lgkmcnt(0)
	v_mfma_f32_16x16x32_bf16 v[120:123], v[132:135], v[164:167], v[120:123]
	v_mfma_f32_16x16x32_bf16 v[116:119], v[140:143], v[164:167], v[116:119]
	v_mfma_f32_16x16x32_bf16 v[104:107], v[132:135], v[172:175], v[104:107]
	v_mfma_f32_16x16x32_bf16 v[100:103], v[140:143], v[172:175], v[100:103]
	v_mfma_f32_16x16x32_bf16 v[88:91], v[132:135], v[180:183], v[88:91]
	v_mfma_f32_16x16x32_bf16 v[84:87], v[140:143], v[180:183], v[84:87]
	v_mfma_f32_16x16x32_bf16 v[72:75], v[132:135], v[188:191], v[72:75]
	v_mfma_f32_16x16x32_bf16 v[68:71], v[140:143], v[188:191], v[68:71]
	v_mfma_f32_16x16x32_bf16 v[120:123], v[136:139], v[168:171], v[120:123]
	v_mfma_f32_16x16x32_bf16 v[116:119], v[144:147], v[168:171], v[116:119]
	v_mfma_f32_16x16x32_bf16 v[104:107], v[136:139], v[176:179], v[104:107]
	v_mfma_f32_16x16x32_bf16 v[100:103], v[144:147], v[176:179], v[100:103]
	v_mfma_f32_16x16x32_bf16 v[88:91], v[136:139], v[184:187], v[88:91]
	v_mfma_f32_16x16x32_bf16 v[84:87], v[144:147], v[184:187], v[84:87]
	v_mfma_f32_16x16x32_bf16 v[72:75], v[136:139], v[192:195], v[72:75]
	v_mfma_f32_16x16x32_bf16 v[68:71], v[144:147], v[192:195], v[68:71]
	s_setprio 0
	s_mov_b32 m0, s30
	v_lshl_add_u64 v[226:227], s[24:25], 0, v[202:203]
	s_barrier
	ds_read_b128 v[188:191], v233 offset:16384
	ds_read_b128 v[192:195], v233 offset:17408
	ds_read_b128 v[180:183], v233 offset:18432
	ds_read_b128 v[184:187], v233 offset:19456
	ds_read_b128 v[172:175], v233 offset:20480
	ds_read_b128 v[176:179], v233 offset:21504
	ds_read_b128 v[164:167], v233 offset:22528
	ds_read_b128 v[168:171], v233 offset:23552
	global_load_lds_dwordx4 v[226:227], off
	v_lshl_add_u64 v[228:229], s[24:25], 0, v[200:201]
	s_mov_b32 m0, s31
	v_cndmask_b32_e64 v0, 0, 1, s[18:19]
	global_load_lds_dwordx4 v[228:229], off
	s_barrier
	s_waitcnt lgkmcnt(0)
	v_cmp_ne_u32_e64 s[12:13], 1, v0
	s_andn2_b64 vcc, exec, s[18:19]
	s_cbranch_vccnz .LBB0_1890
	s_setprio 1
	s_waitcnt lgkmcnt(0)
	v_mfma_f32_16x16x32_bf16 v[64:67], v[148:151], v[188:191], v[64:67]
	v_mfma_f32_16x16x32_bf16 v[60:63], v[156:159], v[188:191], v[60:63]
	v_mfma_f32_16x16x32_bf16 v[48:51], v[148:151], v[180:183], v[48:51]
	v_mfma_f32_16x16x32_bf16 v[44:47], v[156:159], v[180:183], v[44:47]
	v_mfma_f32_16x16x32_bf16 v[32:35], v[148:151], v[172:175], v[32:35]
	v_mfma_f32_16x16x32_bf16 v[28:31], v[156:159], v[172:175], v[28:31]
	v_mfma_f32_16x16x32_bf16 v[16:19], v[148:151], v[164:167], v[16:19]
	v_mfma_f32_16x16x32_bf16 v[12:15], v[156:159], v[164:167], v[12:15]
	v_mfma_f32_16x16x32_bf16 v[64:67], v[152:155], v[192:195], v[64:67]
	v_mfma_f32_16x16x32_bf16 v[60:63], v[160:163], v[192:195], v[60:63]
	v_mfma_f32_16x16x32_bf16 v[48:51], v[152:155], v[184:187], v[48:51]
	v_mfma_f32_16x16x32_bf16 v[44:47], v[160:163], v[184:187], v[44:47]
	v_mfma_f32_16x16x32_bf16 v[32:35], v[152:155], v[176:179], v[32:35]
	v_mfma_f32_16x16x32_bf16 v[28:31], v[160:163], v[176:179], v[28:31]
	v_mfma_f32_16x16x32_bf16 v[16:19], v[152:155], v[168:171], v[16:19]
	v_mfma_f32_16x16x32_bf16 v[12:15], v[160:163], v[168:171], v[12:15]
	s_setprio 0

.LBB0_1892:
	s_add_i32 s56, 0, 0x18000
	v_add_u32_e32 v0, s56, v230
	s_barrier
	ds_read_b128 v[148:151], v0
	ds_read_b128 v[152:155], v0 offset:1024
	ds_read_b128 v[156:159], v0 offset:2048
	ds_read_b128 v[160:163], v0 offset:3072
	s_add_u32 s24, s24, 0x10000
	s_addc_u32 s25, s25, 0
	s_mov_b32 m0, s36
	v_lshl_add_u64 v[132:133], s[24:25], 0, v[202:203]
	ds_read_b128 v[164:167], v233 offset:32768
	ds_read_b128 v[168:171], v233 offset:33792
	ds_read_b128 v[172:175], v233 offset:34816
	ds_read_b128 v[176:179], v233 offset:35840
	ds_read_b128 v[180:183], v233 offset:36864
	ds_read_b128 v[184:187], v233 offset:37888
	ds_read_b128 v[188:191], v233 offset:38912
	ds_read_b128 v[192:195], v233 offset:39936
	global_load_lds_dwordx4 v[132:133], off
	v_lshl_add_u64 v[132:133], s[24:25], 0, v[200:201]
	s_mov_b32 m0, s37
	s_nop 0
	global_load_lds_dwordx4 v[132:133], off
	s_waitcnt lgkmcnt(8)
	s_barrier
	s_waitcnt lgkmcnt(0)
	s_setprio 1
	s_waitcnt lgkmcnt(0)
	v_mfma_f32_16x16x32_bf16 v[128:131], v[148:151], v[164:167], v[128:131]
	v_mfma_f32_16x16x32_bf16 v[124:127], v[156:159], v[164:167], v[124:127]
	v_mfma_f32_16x16x32_bf16 v[112:115], v[148:151], v[172:175], v[112:115]
	v_mfma_f32_16x16x32_bf16 v[108:111], v[156:159], v[172:175], v[108:111]
	v_mfma_f32_16x16x32_bf16 v[96:99], v[148:151], v[180:183], v[96:99]
	v_mfma_f32_16x16x32_bf16 v[92:95], v[156:159], v[180:183], v[92:95]
	v_mfma_f32_16x16x32_bf16 v[80:83], v[148:151], v[188:191], v[80:83]
	v_mfma_f32_16x16x32_bf16 v[76:79], v[156:159], v[188:191], v[76:79]
	v_mfma_f32_16x16x32_bf16 v[128:131], v[152:155], v[168:171], v[128:131]
	v_mfma_f32_16x16x32_bf16 v[124:127], v[160:163], v[168:171], v[124:127]
	v_mfma_f32_16x16x32_bf16 v[112:115], v[152:155], v[176:179], v[112:115]
	v_mfma_f32_16x16x32_bf16 v[108:111], v[160:163], v[176:179], v[108:111]
	v_mfma_f32_16x16x32_bf16 v[96:99], v[152:155], v[184:187], v[96:99]
	v_mfma_f32_16x16x32_bf16 v[92:95], v[160:163], v[184:187], v[92:95]
	v_mfma_f32_16x16x32_bf16 v[80:83], v[152:155], v[192:195], v[80:83]
	v_mfma_f32_16x16x32_bf16 v[76:79], v[160:163], v[192:195], v[76:79]
	s_setprio 0
	s_barrier
	s_add_i32 s24, s56, s29
	v_add_u32_e32 v0, 0x1c000, v234
	v_lshl_add_u64 v[2:3], v[2:3], 0, s[4:5]
	s_mov_b32 m0, s24
	ds_read_b128 v[132:135], v0
	ds_read_b128 v[136:139], v0 offset:1024
	ds_read_b128 v[140:143], v0 offset:2048
	ds_read_b128 v[144:147], v0 offset:3072
	global_load_lds_dwordx4 v[2:3], off
	v_lshl_add_u64 v[2:3], v[224:225], 0, s[4:5]
	s_add_i32 m0, s24, 0x2000
	s_nop 0
	global_load_lds_dwordx4 v[2:3], off
	s_barrier
	s_waitcnt lgkmcnt(0)
	s_setprio 1
	s_waitcnt lgkmcnt(0)
	v_mfma_f32_16x16x32_bf16 v[120:123], v[132:135], v[164:167], v[120:123]
	v_mfma_f32_16x16x32_bf16 v[116:119], v[140:143], v[164:167], v[116:119]
	v_mfma_f32_16x16x32_bf16 v[104:107], v[132:135], v[172:175], v[104:107]
	v_mfma_f32_16x16x32_bf16 v[100:103], v[140:143], v[172:175], v[100:103]
	v_mfma_f32_16x16x32_bf16 v[88:91], v[132:135], v[180:183], v[88:91]
	v_mfma_f32_16x16x32_bf16 v[84:87], v[140:143], v[180:183], v[84:87]
	v_mfma_f32_16x16x32_bf16 v[72:75], v[132:135], v[188:191], v[72:75]
	v_mfma_f32_16x16x32_bf16 v[68:71], v[140:143], v[188:191], v[68:71]
	v_mfma_f32_16x16x32_bf16 v[120:123], v[136:139], v[168:171], v[120:123]
	v_mfma_f32_16x16x32_bf16 v[116:119], v[144:147], v[168:171], v[116:119]
	v_mfma_f32_16x16x32_bf16 v[104:107], v[136:139], v[176:179], v[104:107]
	v_mfma_f32_16x16x32_bf16 v[100:103], v[144:147], v[176:179], v[100:103]
	v_mfma_f32_16x16x32_bf16 v[88:91], v[136:139], v[184:187], v[88:91]
	v_mfma_f32_16x16x32_bf16 v[84:87], v[144:147], v[184:187], v[84:87]
	v_mfma_f32_16x16x32_bf16 v[72:75], v[136:139], v[192:195], v[72:75]
	v_mfma_f32_16x16x32_bf16 v[68:71], v[144:147], v[192:195], v[68:71]
	s_setprio 0
	s_mov_b32 m0, s39
	v_lshl_add_u64 v[2:3], v[226:227], 0, s[4:5]
	s_barrier
	ds_read_b128 v[188:191], v233 offset:49152
	ds_read_b128 v[192:195], v233 offset:50176
	ds_read_b128 v[180:183], v233 offset:51200
	ds_read_b128 v[184:187], v233 offset:52224
	ds_read_b128 v[172:175], v233 offset:53248
	ds_read_b128 v[176:179], v233 offset:54272
	ds_read_b128 v[164:167], v233 offset:55296
	ds_read_b128 v[168:171], v233 offset:56320
	global_load_lds_dwordx4 v[2:3], off
	v_lshl_add_u64 v[2:3], v[228:229], 0, s[4:5]
	s_mov_b32 m0, s40
	s_and_b64 vcc, exec, s[12:13]
	global_load_lds_dwordx4 v[2:3], off
	s_barrier
	s_waitcnt lgkmcnt(0)
	s_cbranch_vccnz .LBB0_1894
	s_setprio 1
	s_waitcnt lgkmcnt(0)
	v_mfma_f32_16x16x32_bf16 v[64:67], v[148:151], v[188:191], v[64:67]
	v_mfma_f32_16x16x32_bf16 v[60:63], v[156:159], v[188:191], v[60:63]
	v_mfma_f32_16x16x32_bf16 v[48:51], v[148:151], v[180:183], v[48:51]
	v_mfma_f32_16x16x32_bf16 v[44:47], v[156:159], v[180:183], v[44:47]
	v_mfma_f32_16x16x32_bf16 v[32:35], v[148:151], v[172:175], v[32:35]
	v_mfma_f32_16x16x32_bf16 v[28:31], v[156:159], v[172:175], v[28:31]
	v_mfma_f32_16x16x32_bf16 v[16:19], v[148:151], v[164:167], v[16:19]
	v_mfma_f32_16x16x32_bf16 v[12:15], v[156:159], v[164:167], v[12:15]
	v_mfma_f32_16x16x32_bf16 v[64:67], v[152:155], v[192:195], v[64:67]
	v_mfma_f32_16x16x32_bf16 v[60:63], v[160:163], v[192:195], v[60:63]
	v_mfma_f32_16x16x32_bf16 v[48:51], v[152:155], v[184:187], v[48:51]
	v_mfma_f32_16x16x32_bf16 v[44:47], v[160:163], v[184:187], v[44:47]
	v_mfma_f32_16x16x32_bf16 v[32:35], v[152:155], v[176:179], v[32:35]
	v_mfma_f32_16x16x32_bf16 v[28:31], v[160:163], v[176:179], v[28:31]
	v_mfma_f32_16x16x32_bf16 v[16:19], v[152:155], v[168:171], v[16:19]
	v_mfma_f32_16x16x32_bf16 v[12:15], v[160:163], v[168:171], v[12:15]
	s_setprio 0

.LBB0_1996:
	ds_read_b128 v[156:159], v219
	ds_read_b128 v[160:163], v219 offset:1024
	ds_read_b128 v[164:167], v219 offset:2048
	ds_read_b128 v[168:171], v219 offset:3072
	s_mov_b64 s[14:15], s[4:5]
	s_add_u32 s4, s14, 0x100
	s_addc_u32 s5, s15, 0
	s_cmp_eq_u32 s47, s50
	s_cselect_b32 s25, s19, s5
	s_cselect_b32 s24, s18, s4
	s_cselect_b32 s23, s21, s49
	s_cselect_b32 s22, s20, s48
	v_lshl_add_u64 v[2:3], s[14:15], 0, v[204:205]
	s_add_i32 m0, s29, 0xc000
	ds_read_b128 v[104:107], v220
	ds_read_b128 v[172:175], v220 offset:1024
	ds_read_b128 v[176:179], v220 offset:2048
	ds_read_b128 v[180:183], v220 offset:3072
	ds_read_b128 v[184:187], v220 offset:4096
	ds_read_b128 v[188:191], v220 offset:5120
	ds_read_b128 v[192:195], v220 offset:6144
	ds_read_b128 v[212:215], v220 offset:7168
	global_load_lds_dwordx4 v[2:3], off
	v_lshl_add_u64 v[2:3], s[14:15], 0, v[206:207]
	s_add_i32 m0, s29, 0xe000
	s_nop 0
	global_load_lds_dwordx4 v[2:3], off
	s_waitcnt lgkmcnt(8)
	s_barrier
	s_waitcnt lgkmcnt(0)
	s_setprio 1
	s_waitcnt lgkmcnt(0)
	v_mfma_f32_16x16x32_bf16 v[100:103], v[156:159], v[104:107], v[152:155]
	v_mfma_f32_16x16x32_bf16 v[124:127], v[160:163], v[172:175], v[100:103]
	v_mfma_f32_16x16x32_bf16 v[100:103], v[164:167], v[104:107], v[148:151]
	v_mfma_f32_16x16x32_bf16 v[128:131], v[168:171], v[172:175], v[100:103]
	v_mfma_f32_16x16x32_bf16 v[100:103], v[156:159], v[176:179], v[120:123]
	v_mfma_f32_16x16x32_bf16 v[120:123], v[160:163], v[180:183], v[100:103]
	v_mfma_f32_16x16x32_bf16 v[100:103], v[164:167], v[176:179], v[116:119]
	v_mfma_f32_16x16x32_bf16 v[96:99], v[156:159], v[184:187], v[96:99]
	v_mfma_f32_16x16x32_bf16 v[92:95], v[164:167], v[184:187], v[92:95]
	v_mfma_f32_16x16x32_bf16 v[80:83], v[156:159], v[192:195], v[80:83]
	v_mfma_f32_16x16x32_bf16 v[76:79], v[164:167], v[192:195], v[76:79]
	v_mfma_f32_16x16x32_bf16 v[116:119], v[168:171], v[180:183], v[100:103]
	v_mfma_f32_16x16x32_bf16 v[96:99], v[160:163], v[188:191], v[96:99]
	v_mfma_f32_16x16x32_bf16 v[92:95], v[168:171], v[188:191], v[92:95]
	v_mfma_f32_16x16x32_bf16 v[80:83], v[160:163], v[212:215], v[80:83]
	v_mfma_f32_16x16x32_bf16 v[76:79], v[168:171], v[212:215], v[76:79]
	s_setprio 0
	s_barrier
	s_add_i32 s14, s55, s28
	v_lshl_add_u64 v[2:3], s[22:23], 0, v[198:199]
	s_mov_b32 m0, s14
	ds_read_b128 v[140:143], v222
	ds_read_b128 v[144:147], v222 offset:1024
	ds_read_b128 v[148:151], v222 offset:2048
	ds_read_b128 v[152:155], v222 offset:3072
	global_load_lds_dwordx4 v[2:3], off
	v_lshl_add_u64 v[210:211], s[22:23], 0, v[202:203]
	s_add_i32 m0, s14, 0x2000
	s_nop 0
	global_load_lds_dwordx4 v[210:211], off
	s_barrier
	s_waitcnt lgkmcnt(0)
	s_setprio 1
	s_waitcnt lgkmcnt(0)
	v_mfma_f32_16x16x32_bf16 v[100:103], v[140:143], v[104:107], v[136:139]
	v_mfma_f32_16x16x32_bf16 v[104:107], v[148:151], v[104:107], v[132:135]
	v_mfma_f32_16x16x32_bf16 v[112:115], v[140:143], v[176:179], v[112:115]
	v_mfma_f32_16x16x32_bf16 v[108:111], v[148:151], v[176:179], v[108:111]
	v_mfma_f32_16x16x32_bf16 v[88:91], v[140:143], v[184:187], v[88:91]
	v_mfma_f32_16x16x32_bf16 v[84:87], v[148:151], v[184:187], v[84:87]
	v_mfma_f32_16x16x32_bf16 v[72:75], v[140:143], v[192:195], v[72:75]
	v_mfma_f32_16x16x32_bf16 v[68:71], v[148:151], v[192:195], v[68:71]
	v_mfma_f32_16x16x32_bf16 v[100:103], v[144:147], v[172:175], v[100:103]
	v_mfma_f32_16x16x32_bf16 v[104:107], v[152:155], v[172:175], v[104:107]
	v_mfma_f32_16x16x32_bf16 v[112:115], v[144:147], v[180:183], v[112:115]
	v_mfma_f32_16x16x32_bf16 v[108:111], v[152:155], v[180:183], v[108:111]
	v_mfma_f32_16x16x32_bf16 v[88:91], v[144:147], v[188:191], v[88:91]
	v_mfma_f32_16x16x32_bf16 v[84:87], v[152:155], v[188:191], v[84:87]
	v_mfma_f32_16x16x32_bf16 v[72:75], v[144:147], v[212:215], v[72:75]
	v_mfma_f32_16x16x32_bf16 v[68:71], v[152:155], v[212:215], v[68:71]
	s_setprio 0
	s_mov_b32 m0, s29
	v_lshl_add_u64 v[212:213], s[24:25], 0, v[196:197]
	s_barrier
	ds_read_b128 v[188:191], v220 offset:16384
	ds_read_b128 v[192:195], v220 offset:17408
	ds_read_b128 v[180:183], v220 offset:18432
	ds_read_b128 v[184:187], v220 offset:19456
	ds_read_b128 v[172:175], v220 offset:20480
	ds_read_b128 v[176:179], v220 offset:21504
	ds_read_b128 v[132:135], v220 offset:22528
	ds_read_b128 v[136:139], v220 offset:23552
	global_load_lds_dwordx4 v[212:213], off
	v_lshl_add_u64 v[214:215], s[24:25], 0, v[200:201]
	s_mov_b32 m0, s30
	v_cmp_ne_u32_e64 s[14:15], 1, v224
	global_load_lds_dwordx4 v[214:215], off
	s_barrier
	s_waitcnt lgkmcnt(0)
	s_andn2_b64 vcc, exec, s[16:17]
	s_cbranch_vccnz .LBB0_1998
	s_setprio 1
	s_waitcnt lgkmcnt(0)
	v_mfma_f32_16x16x32_bf16 v[64:67], v[156:159], v[188:191], v[64:67]
	v_mfma_f32_16x16x32_bf16 v[60:63], v[164:167], v[188:191], v[60:63]
	v_mfma_f32_16x16x32_bf16 v[48:51], v[156:159], v[180:183], v[48:51]
	v_mfma_f32_16x16x32_bf16 v[44:47], v[164:167], v[180:183], v[44:47]
	v_mfma_f32_16x16x32_bf16 v[32:35], v[156:159], v[172:175], v[32:35]
	v_mfma_f32_16x16x32_bf16 v[28:31], v[164:167], v[172:175], v[28:31]
	v_mfma_f32_16x16x32_bf16 v[16:19], v[156:159], v[132:135], v[16:19]
	v_mfma_f32_16x16x32_bf16 v[12:15], v[164:167], v[132:135], v[12:15]
	v_mfma_f32_16x16x32_bf16 v[64:67], v[160:163], v[192:195], v[64:67]
	v_mfma_f32_16x16x32_bf16 v[60:63], v[168:171], v[192:195], v[60:63]
	v_mfma_f32_16x16x32_bf16 v[48:51], v[160:163], v[184:187], v[48:51]
	v_mfma_f32_16x16x32_bf16 v[44:47], v[168:171], v[184:187], v[44:47]
	v_mfma_f32_16x16x32_bf16 v[32:35], v[160:163], v[176:179], v[32:35]
	v_mfma_f32_16x16x32_bf16 v[28:31], v[168:171], v[176:179], v[28:31]
	v_mfma_f32_16x16x32_bf16 v[16:19], v[160:163], v[136:139], v[16:19]
	v_mfma_f32_16x16x32_bf16 v[12:15], v[168:171], v[136:139], v[12:15]
	s_setprio 0

.LBB0_2191:
	ds_read_b128 v[148:151], v222
	ds_read_b128 v[152:155], v222 offset:1024
	ds_read_b128 v[156:159], v222 offset:2048
	ds_read_b128 v[160:163], v222 offset:3072
	s_mov_b64 s[12:13], s[24:25]
	s_add_u32 s24, s12, 0x100
	s_addc_u32 s25, s13, 0
	s_cmp_eq_u32 s57, s60
	s_cselect_b32 s31, s21, s25
	s_cselect_b32 s30, s20, s24
	s_cselect_b32 s29, s19, s59
	s_cselect_b32 s28, s56, s58
	v_lshl_add_u64 v[2:3], s[12:13], 0, v[204:205]
	s_add_i32 m0, s36, 0xc000
	ds_read_b128 v[164:167], v223
	ds_read_b128 v[168:171], v223 offset:1024
	ds_read_b128 v[172:175], v223 offset:2048
	ds_read_b128 v[176:179], v223 offset:3072
	ds_read_b128 v[180:183], v223 offset:4096
	ds_read_b128 v[184:187], v223 offset:5120
	ds_read_b128 v[188:191], v223 offset:6144
	ds_read_b128 v[192:195], v223 offset:7168
	global_load_lds_dwordx4 v[2:3], off
	v_lshl_add_u64 v[2:3], s[12:13], 0, v[206:207]
	s_add_i32 m0, s36, 0xe000
	s_nop 0
	global_load_lds_dwordx4 v[2:3], off
	s_waitcnt lgkmcnt(8)
	s_barrier
	s_waitcnt lgkmcnt(0)
	s_setprio 1
	s_waitcnt lgkmcnt(0)
	v_mfma_f32_16x16x32_bf16 v[128:131], v[148:151], v[164:167], v[128:131]
	v_mfma_f32_16x16x32_bf16 v[124:127], v[156:159], v[164:167], v[124:127]
	v_mfma_f32_16x16x32_bf16 v[112:115], v[148:151], v[172:175], v[112:115]
	v_mfma_f32_16x16x32_bf16 v[108:111], v[156:159], v[172:175], v[108:111]
	v_mfma_f32_16x16x32_bf16 v[96:99], v[148:151], v[180:183], v[96:99]
	v_mfma_f32_16x16x32_bf16 v[92:95], v[156:159], v[180:183], v[92:95]
	v_mfma_f32_16x16x32_bf16 v[80:83], v[148:151], v[188:191], v[80:83]
	v_mfma_f32_16x16x32_bf16 v[76:79], v[156:159], v[188:191], v[76:79]
	v_mfma_f32_16x16x32_bf16 v[128:131], v[152:155], v[168:171], v[128:131]
	v_mfma_f32_16x16x32_bf16 v[124:127], v[160:163], v[168:171], v[124:127]
	v_mfma_f32_16x16x32_bf16 v[112:115], v[152:155], v[176:179], v[112:115]
	v_mfma_f32_16x16x32_bf16 v[108:111], v[160:163], v[176:179], v[108:111]
	v_mfma_f32_16x16x32_bf16 v[96:99], v[152:155], v[184:187], v[96:99]
	v_mfma_f32_16x16x32_bf16 v[92:95], v[160:163], v[184:187], v[92:95]
	v_mfma_f32_16x16x32_bf16 v[80:83], v[152:155], v[192:195], v[80:83]
	v_mfma_f32_16x16x32_bf16 v[76:79], v[160:163], v[192:195], v[76:79]
	s_setprio 0
	s_barrier
	s_add_i32 s12, s50, s11
	v_lshl_add_u64 v[2:3], s[28:29], 0, v[198:199]
	s_mov_b32 m0, s12
	ds_read_b128 v[132:135], v225
	ds_read_b128 v[136:139], v225 offset:1024
	ds_read_b128 v[140:143], v225 offset:2048
	ds_read_b128 v[144:147], v225 offset:3072
	global_load_lds_dwordx4 v[2:3], off
	v_lshl_add_u64 v[214:215], s[28:29], 0, v[202:203]
	s_add_i32 m0, s12, 0x2000
	s_nop 0
	global_load_lds_dwordx4 v[214:215], off
	s_barrier
	s_waitcnt lgkmcnt(0)
	s_setprio 1
	s_waitcnt lgkmcnt(0)
	v_mfma_f32_16x16x32_bf16 v[120:123], v[132:135], v[164:167], v[120:123]
	v_mfma_f32_16x16x32_bf16 v[116:119], v[140:143], v[164:167], v[116:119]
	v_mfma_f32_16x16x32_bf16 v[104:107], v[132:135], v[172:175], v[104:107]
	v_mfma_f32_16x16x32_bf16 v[100:103], v[140:143], v[172:175], v[100:103]
	v_mfma_f32_16x16x32_bf16 v[88:91], v[132:135], v[180:183], v[88:91]
	v_mfma_f32_16x16x32_bf16 v[84:87], v[140:143], v[180:183], v[84:87]
	v_mfma_f32_16x16x32_bf16 v[72:75], v[132:135], v[188:191], v[72:75]
	v_mfma_f32_16x16x32_bf16 v[68:71], v[140:143], v[188:191], v[68:71]
	v_mfma_f32_16x16x32_bf16 v[120:123], v[136:139], v[168:171], v[120:123]
	v_mfma_f32_16x16x32_bf16 v[116:119], v[144:147], v[168:171], v[116:119]
	v_mfma_f32_16x16x32_bf16 v[104:107], v[136:139], v[176:179], v[104:107]
	v_mfma_f32_16x16x32_bf16 v[100:103], v[144:147], v[176:179], v[100:103]
	v_mfma_f32_16x16x32_bf16 v[88:91], v[136:139], v[184:187], v[88:91]
	v_mfma_f32_16x16x32_bf16 v[84:87], v[144:147], v[184:187], v[84:87]
	v_mfma_f32_16x16x32_bf16 v[72:75], v[136:139], v[192:195], v[72:75]
	v_mfma_f32_16x16x32_bf16 v[68:71], v[144:147], v[192:195], v[68:71]
	s_setprio 0
	s_mov_b32 m0, s36
	v_lshl_add_u64 v[216:217], s[30:31], 0, v[196:197]
	s_barrier
	ds_read_b128 v[188:191], v223 offset:16384
	ds_read_b128 v[192:195], v223 offset:17408
	ds_read_b128 v[180:183], v223 offset:18432
	ds_read_b128 v[184:187], v223 offset:19456
	ds_read_b128 v[172:175], v223 offset:20480
	ds_read_b128 v[176:179], v223 offset:21504
	ds_read_b128 v[164:167], v223 offset:22528
	ds_read_b128 v[168:171], v223 offset:23552
	global_load_lds_dwordx4 v[216:217], off
	v_lshl_add_u64 v[218:219], s[30:31], 0, v[200:201]
	s_mov_b32 m0, s37
	v_cmp_ne_u32_e64 s[12:13], 1, v213
	global_load_lds_dwordx4 v[218:219], off
	s_barrier
	s_waitcnt lgkmcnt(0)
	s_andn2_b64 vcc, exec, s[26:27]
	s_cbranch_vccnz .LBB0_2193
	s_setprio 1
	s_waitcnt lgkmcnt(0)
	v_mfma_f32_16x16x32_bf16 v[64:67], v[148:151], v[188:191], v[64:67]
	v_mfma_f32_16x16x32_bf16 v[60:63], v[156:159], v[188:191], v[60:63]
	v_mfma_f32_16x16x32_bf16 v[48:51], v[148:151], v[180:183], v[48:51]
	v_mfma_f32_16x16x32_bf16 v[44:47], v[156:159], v[180:183], v[44:47]
	v_mfma_f32_16x16x32_bf16 v[32:35], v[148:151], v[172:175], v[32:35]
	v_mfma_f32_16x16x32_bf16 v[28:31], v[156:159], v[172:175], v[28:31]
	v_mfma_f32_16x16x32_bf16 v[16:19], v[148:151], v[164:167], v[16:19]
	v_mfma_f32_16x16x32_bf16 v[12:15], v[156:159], v[164:167], v[12:15]
	v_mfma_f32_16x16x32_bf16 v[64:67], v[152:155], v[192:195], v[64:67]
	v_mfma_f32_16x16x32_bf16 v[60:63], v[160:163], v[192:195], v[60:63]
	v_mfma_f32_16x16x32_bf16 v[48:51], v[152:155], v[184:187], v[48:51]
	v_mfma_f32_16x16x32_bf16 v[44:47], v[160:163], v[184:187], v[44:47]
	v_mfma_f32_16x16x32_bf16 v[32:35], v[152:155], v[176:179], v[32:35]
	v_mfma_f32_16x16x32_bf16 v[28:31], v[160:163], v[176:179], v[28:31]
	v_mfma_f32_16x16x32_bf16 v[16:19], v[152:155], v[168:171], v[16:19]
	v_mfma_f32_16x16x32_bf16 v[12:15], v[160:163], v[168:171], v[12:15]
	s_setprio 0

.LBB0_2195:
	s_add_i32 s61, 0, 0x18000
	v_add_u32_e32 v0, s61, v221
	s_barrier
	ds_read_b128 v[148:151], v0
	ds_read_b128 v[152:155], v0 offset:1024
	ds_read_b128 v[156:159], v0 offset:2048
	ds_read_b128 v[160:163], v0 offset:3072
	s_add_u32 s30, s30, 0x14000
	s_addc_u32 s31, s31, 0
	s_mov_b32 m0, s40
	v_lshl_add_u64 v[132:133], s[30:31], 0, v[196:197]
	ds_read_b128 v[164:167], v223 offset:32768
	ds_read_b128 v[168:171], v223 offset:33792
	ds_read_b128 v[172:175], v223 offset:34816
	ds_read_b128 v[176:179], v223 offset:35840
	ds_read_b128 v[180:183], v223 offset:36864
	ds_read_b128 v[184:187], v223 offset:37888
	ds_read_b128 v[188:191], v223 offset:38912
	ds_read_b128 v[192:195], v223 offset:39936
	global_load_lds_dwordx4 v[132:133], off
	v_lshl_add_u64 v[132:133], s[30:31], 0, v[200:201]
	s_mov_b32 m0, s41
	s_nop 0
	global_load_lds_dwordx4 v[132:133], off
	s_waitcnt lgkmcnt(8)
	s_barrier
	s_waitcnt lgkmcnt(0)
	s_setprio 1
	s_waitcnt lgkmcnt(0)
	v_mfma_f32_16x16x32_bf16 v[128:131], v[148:151], v[164:167], v[128:131]
	v_mfma_f32_16x16x32_bf16 v[124:127], v[156:159], v[164:167], v[124:127]
	v_mfma_f32_16x16x32_bf16 v[112:115], v[148:151], v[172:175], v[112:115]
	v_mfma_f32_16x16x32_bf16 v[108:111], v[156:159], v[172:175], v[108:111]
	v_mfma_f32_16x16x32_bf16 v[96:99], v[148:151], v[180:183], v[96:99]
	v_mfma_f32_16x16x32_bf16 v[92:95], v[156:159], v[180:183], v[92:95]
	v_mfma_f32_16x16x32_bf16 v[80:83], v[148:151], v[188:191], v[80:83]
	v_mfma_f32_16x16x32_bf16 v[76:79], v[156:159], v[188:191], v[76:79]
	v_mfma_f32_16x16x32_bf16 v[128:131], v[152:155], v[168:171], v[128:131]
	v_mfma_f32_16x16x32_bf16 v[124:127], v[160:163], v[168:171], v[124:127]
	v_mfma_f32_16x16x32_bf16 v[112:115], v[152:155], v[176:179], v[112:115]
	v_mfma_f32_16x16x32_bf16 v[108:111], v[160:163], v[176:179], v[108:111]
	v_mfma_f32_16x16x32_bf16 v[96:99], v[152:155], v[184:187], v[96:99]
	v_mfma_f32_16x16x32_bf16 v[92:95], v[160:163], v[184:187], v[92:95]
	v_mfma_f32_16x16x32_bf16 v[80:83], v[152:155], v[192:195], v[80:83]
	v_mfma_f32_16x16x32_bf16 v[76:79], v[160:163], v[192:195], v[76:79]
	s_setprio 0
	s_barrier
	s_add_i32 s30, s61, s11
	v_add_u32_e32 v0, 0x1c000, v224
	v_lshl_add_u64 v[2:3], v[2:3], 0, s[16:17]
	s_mov_b32 m0, s30
	ds_read_b128 v[132:135], v0
	ds_read_b128 v[136:139], v0 offset:1024
	ds_read_b128 v[140:143], v0 offset:2048
	ds_read_b128 v[144:147], v0 offset:3072
	global_load_lds_dwordx4 v[2:3], off
	v_lshl_add_u64 v[2:3], v[214:215], 0, s[16:17]
	s_add_i32 m0, s30, 0x2000
	s_nop 0
	global_load_lds_dwordx4 v[2:3], off
	s_barrier
	s_waitcnt lgkmcnt(0)
	s_setprio 1
	s_waitcnt lgkmcnt(0)
	v_mfma_f32_16x16x32_bf16 v[120:123], v[132:135], v[164:167], v[120:123]
	v_mfma_f32_16x16x32_bf16 v[116:119], v[140:143], v[164:167], v[116:119]
	v_mfma_f32_16x16x32_bf16 v[104:107], v[132:135], v[172:175], v[104:107]
	v_mfma_f32_16x16x32_bf16 v[100:103], v[140:143], v[172:175], v[100:103]
	v_mfma_f32_16x16x32_bf16 v[88:91], v[132:135], v[180:183], v[88:91]
	v_mfma_f32_16x16x32_bf16 v[84:87], v[140:143], v[180:183], v[84:87]
	v_mfma_f32_16x16x32_bf16 v[72:75], v[132:135], v[188:191], v[72:75]
	v_mfma_f32_16x16x32_bf16 v[68:71], v[140:143], v[188:191], v[68:71]
	v_mfma_f32_16x16x32_bf16 v[120:123], v[136:139], v[168:171], v[120:123]
	v_mfma_f32_16x16x32_bf16 v[116:119], v[144:147], v[168:171], v[116:119]
	v_mfma_f32_16x16x32_bf16 v[104:107], v[136:139], v[176:179], v[104:107]
	v_mfma_f32_16x16x32_bf16 v[100:103], v[144:147], v[176:179], v[100:103]
	v_mfma_f32_16x16x32_bf16 v[88:91], v[136:139], v[184:187], v[88:91]
	v_mfma_f32_16x16x32_bf16 v[84:87], v[144:147], v[184:187], v[84:87]
	v_mfma_f32_16x16x32_bf16 v[72:75], v[136:139], v[192:195], v[72:75]
	v_mfma_f32_16x16x32_bf16 v[68:71], v[144:147], v[192:195], v[68:71]
	s_setprio 0
	s_mov_b32 m0, s43
	v_lshl_add_u64 v[2:3], v[216:217], 0, s[16:17]
	s_barrier
	ds_read_b128 v[188:191], v223 offset:49152
	ds_read_b128 v[192:195], v223 offset:50176
	ds_read_b128 v[180:183], v223 offset:51200
	ds_read_b128 v[184:187], v223 offset:52224
	ds_read_b128 v[172:175], v223 offset:53248
	ds_read_b128 v[176:179], v223 offset:54272
	ds_read_b128 v[164:167], v223 offset:55296
	ds_read_b128 v[168:171], v223 offset:56320
	global_load_lds_dwordx4 v[2:3], off
	v_lshl_add_u64 v[2:3], v[218:219], 0, s[16:17]
	s_mov_b32 m0, s46
	s_and_b64 vcc, exec, s[12:13]
	global_load_lds_dwordx4 v[2:3], off
	s_barrier
	s_waitcnt lgkmcnt(0)
	s_cbranch_vccnz .LBB0_2197
	s_setprio 1
	s_waitcnt lgkmcnt(0)
	v_mfma_f32_16x16x32_bf16 v[64:67], v[148:151], v[188:191], v[64:67]
	v_mfma_f32_16x16x32_bf16 v[60:63], v[156:159], v[188:191], v[60:63]
	v_mfma_f32_16x16x32_bf16 v[48:51], v[148:151], v[180:183], v[48:51]
	v_mfma_f32_16x16x32_bf16 v[44:47], v[156:159], v[180:183], v[44:47]
	v_mfma_f32_16x16x32_bf16 v[32:35], v[148:151], v[172:175], v[32:35]
	v_mfma_f32_16x16x32_bf16 v[28:31], v[156:159], v[172:175], v[28:31]
	v_mfma_f32_16x16x32_bf16 v[16:19], v[148:151], v[164:167], v[16:19]
	v_mfma_f32_16x16x32_bf16 v[12:15], v[156:159], v[164:167], v[12:15]
	v_mfma_f32_16x16x32_bf16 v[64:67], v[152:155], v[192:195], v[64:67]
	v_mfma_f32_16x16x32_bf16 v[60:63], v[160:163], v[192:195], v[60:63]
	v_mfma_f32_16x16x32_bf16 v[48:51], v[152:155], v[184:187], v[48:51]
	v_mfma_f32_16x16x32_bf16 v[44:47], v[160:163], v[184:187], v[44:47]
	v_mfma_f32_16x16x32_bf16 v[32:35], v[152:155], v[176:179], v[32:35]
	v_mfma_f32_16x16x32_bf16 v[28:31], v[160:163], v[176:179], v[28:31]
	v_mfma_f32_16x16x32_bf16 v[16:19], v[152:155], v[168:171], v[16:19]
	v_mfma_f32_16x16x32_bf16 v[12:15], v[160:163], v[168:171], v[12:15]
	s_setprio 0

.LBB0_2717:
	ds_read_b128 v[148:151], v205
	ds_read_b128 v[152:155], v205 offset:1024
	ds_read_b128 v[156:159], v205 offset:2048
	ds_read_b128 v[160:163], v205 offset:3072
	s_add_u32 s12, s34, 0xfff80080
	s_addc_u32 s13, s35, -1
	s_cmp_eq_u32 s23, s48
	s_cselect_b32 s39, s2, s13
	s_cselect_b32 s38, s5, s12
	s_cselect_b32 s37, s19, s47
	s_cselect_b32 s36, s21, s46
	v_lshl_add_u64 v[2:3], s[34:35], 0, v[214:215]
	s_add_i32 m0, s7, 0xc000
	ds_read_b128 v[164:167], v230
	ds_read_b128 v[168:171], v230 offset:1024
	ds_read_b128 v[172:175], v230 offset:2048
	ds_read_b128 v[176:179], v230 offset:3072
	ds_read_b128 v[180:183], v230 offset:4096
	ds_read_b128 v[184:187], v230 offset:5120
	ds_read_b128 v[188:191], v230 offset:6144
	ds_read_b128 v[192:195], v230 offset:7168
	global_load_lds_dwordx4 v[2:3], off
	v_lshl_add_u64 v[2:3], s[34:35], 0, v[216:217]
	s_add_i32 m0, s7, 0xe000
	s_nop 0
	global_load_lds_dwordx4 v[2:3], off
	s_waitcnt lgkmcnt(8)
	s_barrier
	s_waitcnt lgkmcnt(0)
	s_setprio 1
	s_waitcnt lgkmcnt(0)
	v_mfma_f32_16x16x32_bf16 v[84:87], v[148:151], v[164:167], v[84:87]
	v_mfma_f32_16x16x32_bf16 v[76:79], v[156:159], v[164:167], v[76:79]
	v_mfma_f32_16x16x32_bf16 v[64:67], v[148:151], v[172:175], v[64:67]
	v_mfma_f32_16x16x32_bf16 v[60:63], v[156:159], v[172:175], v[60:63]
	v_mfma_f32_16x16x32_bf16 v[48:51], v[148:151], v[180:183], v[48:51]
	v_mfma_f32_16x16x32_bf16 v[44:47], v[156:159], v[180:183], v[44:47]
	v_mfma_f32_16x16x32_bf16 v[32:35], v[148:151], v[188:191], v[32:35]
	v_mfma_f32_16x16x32_bf16 v[24:27], v[156:159], v[188:191], v[24:27]
	v_mfma_f32_16x16x32_bf16 v[84:87], v[152:155], v[168:171], v[84:87]
	v_mfma_f32_16x16x32_bf16 v[76:79], v[160:163], v[168:171], v[76:79]
	v_mfma_f32_16x16x32_bf16 v[64:67], v[152:155], v[176:179], v[64:67]
	v_mfma_f32_16x16x32_bf16 v[60:63], v[160:163], v[176:179], v[60:63]
	v_mfma_f32_16x16x32_bf16 v[48:51], v[152:155], v[184:187], v[48:51]
	v_mfma_f32_16x16x32_bf16 v[44:47], v[160:163], v[184:187], v[44:47]
	v_mfma_f32_16x16x32_bf16 v[32:35], v[152:155], v[192:195], v[32:35]
	v_mfma_f32_16x16x32_bf16 v[24:27], v[160:163], v[192:195], v[24:27]
	s_setprio 0
	s_barrier
	s_add_i32 s12, s63, s40
	v_lshl_add_u64 v[2:3], s[36:37], 0, v[198:199]
	s_mov_b32 m0, s12
	ds_read_b128 v[132:135], v232
	ds_read_b128 v[136:139], v232 offset:1024
	ds_read_b128 v[140:143], v232 offset:2048
	ds_read_b128 v[144:147], v232 offset:3072
	global_load_lds_dwordx4 v[2:3], off
	v_lshl_add_u64 v[220:221], s[36:37], 0, v[202:203]
	s_add_i32 m0, s12, 0x2000
	s_nop 0
	global_load_lds_dwordx4 v[220:221], off
	s_barrier
	s_waitcnt lgkmcnt(0)
	s_setprio 1
	s_waitcnt lgkmcnt(0)
	v_mfma_f32_16x16x32_bf16 v[72:75], v[132:135], v[164:167], v[72:75]
	v_mfma_f32_16x16x32_bf16 v[68:71], v[140:143], v[164:167], v[68:71]
	v_mfma_f32_16x16x32_bf16 v[56:59], v[132:135], v[172:175], v[56:59]
	v_mfma_f32_16x16x32_bf16 v[52:55], v[140:143], v[172:175], v[52:55]
	v_mfma_f32_16x16x32_bf16 v[40:43], v[132:135], v[180:183], v[40:43]
	v_mfma_f32_16x16x32_bf16 v[36:39], v[140:143], v[180:183], v[36:39]
	v_mfma_f32_16x16x32_bf16 v[20:23], v[132:135], v[188:191], v[20:23]
	v_mfma_f32_16x16x32_bf16 v[12:15], v[140:143], v[188:191], v[12:15]
	v_mfma_f32_16x16x32_bf16 v[72:75], v[136:139], v[168:171], v[72:75]
	v_mfma_f32_16x16x32_bf16 v[68:71], v[144:147], v[168:171], v[68:71]
	v_mfma_f32_16x16x32_bf16 v[56:59], v[136:139], v[176:179], v[56:59]
	v_mfma_f32_16x16x32_bf16 v[52:55], v[144:147], v[176:179], v[52:55]
	v_mfma_f32_16x16x32_bf16 v[40:43], v[136:139], v[184:187], v[40:43]
	v_mfma_f32_16x16x32_bf16 v[36:39], v[144:147], v[184:187], v[36:39]
	v_mfma_f32_16x16x32_bf16 v[20:23], v[136:139], v[192:195], v[20:23]
	v_mfma_f32_16x16x32_bf16 v[12:15], v[144:147], v[192:195], v[12:15]
	s_setprio 0
	s_mov_b32 m0, s7
	v_lshl_add_u64 v[222:223], s[38:39], 0, v[196:197]
	s_barrier
	ds_read_b128 v[188:191], v230 offset:16384
	ds_read_b128 v[192:195], v230 offset:17408
	ds_read_b128 v[180:183], v230 offset:18432
	ds_read_b128 v[184:187], v230 offset:19456
	ds_read_b128 v[172:175], v230 offset:20480
	ds_read_b128 v[176:179], v230 offset:21504
	ds_read_b128 v[164:167], v230 offset:22528
	ds_read_b128 v[168:171], v230 offset:23552
	global_load_lds_dwordx4 v[222:223], off
	v_lshl_add_u64 v[224:225], s[38:39], 0, v[200:201]
	s_mov_b32 m0, s41
	v_cmp_ne_u32_e64 s[12:13], 1, v233
	global_load_lds_dwordx4 v[224:225], off
	s_barrier
	s_waitcnt lgkmcnt(0)
	s_andn2_b64 vcc, exec, s[30:31]
	s_cbranch_vccnz .LBB0_2719
	s_setprio 1
	s_waitcnt lgkmcnt(0)
	v_mfma_f32_16x16x32_bf16 v[128:131], v[148:151], v[188:191], v[128:131]
	v_mfma_f32_16x16x32_bf16 v[124:127], v[156:159], v[188:191], v[124:127]
	v_mfma_f32_16x16x32_bf16 v[112:115], v[148:151], v[180:183], v[112:115]
	v_mfma_f32_16x16x32_bf16 v[108:111], v[156:159], v[180:183], v[108:111]
	v_mfma_f32_16x16x32_bf16 v[96:99], v[148:151], v[172:175], v[96:99]
	v_mfma_f32_16x16x32_bf16 v[92:95], v[156:159], v[172:175], v[92:95]
	v_mfma_f32_16x16x32_bf16 v[28:31], v[148:151], v[164:167], v[28:31]
	v_mfma_f32_16x16x32_bf16 v[16:19], v[156:159], v[164:167], v[16:19]
	v_mfma_f32_16x16x32_bf16 v[128:131], v[152:155], v[192:195], v[128:131]
	v_mfma_f32_16x16x32_bf16 v[124:127], v[160:163], v[192:195], v[124:127]
	v_mfma_f32_16x16x32_bf16 v[112:115], v[152:155], v[184:187], v[112:115]
	v_mfma_f32_16x16x32_bf16 v[108:111], v[160:163], v[184:187], v[108:111]
	v_mfma_f32_16x16x32_bf16 v[96:99], v[152:155], v[176:179], v[96:99]
	v_mfma_f32_16x16x32_bf16 v[92:95], v[160:163], v[176:179], v[92:95]
	v_mfma_f32_16x16x32_bf16 v[28:31], v[152:155], v[168:171], v[28:31]
	v_mfma_f32_16x16x32_bf16 v[16:19], v[160:163], v[168:171], v[16:19]
	s_setprio 0

.LBB0_2721:
	s_add_i32 s49, 0, 0x18000
	v_add_u32_e32 v1, s49, v226
	s_barrier
	ds_read_b128 v[148:151], v1
	ds_read_b128 v[152:155], v1 offset:1024
	ds_read_b128 v[156:159], v1 offset:2048
	ds_read_b128 v[160:163], v1 offset:3072
	s_add_u32 s38, s38, 0x80000
	s_addc_u32 s39, s39, 0
	s_mov_b32 m0, s54
	v_lshl_add_u64 v[132:133], s[38:39], 0, v[196:197]
	ds_read_b128 v[164:167], v230 offset:32768
	ds_read_b128 v[168:171], v230 offset:33792
	ds_read_b128 v[172:175], v230 offset:34816
	ds_read_b128 v[176:179], v230 offset:35840
	ds_read_b128 v[180:183], v230 offset:36864
	ds_read_b128 v[184:187], v230 offset:37888
	ds_read_b128 v[188:191], v230 offset:38912
	ds_read_b128 v[192:195], v230 offset:39936
	global_load_lds_dwordx4 v[132:133], off
	v_lshl_add_u64 v[132:133], s[38:39], 0, v[200:201]
	s_mov_b32 m0, s55
	s_nop 0
	global_load_lds_dwordx4 v[132:133], off
	s_waitcnt lgkmcnt(8)
	s_barrier
	s_waitcnt lgkmcnt(0)
	s_setprio 1
	s_waitcnt lgkmcnt(0)
	v_mfma_f32_16x16x32_bf16 v[84:87], v[148:151], v[164:167], v[84:87]
	v_mfma_f32_16x16x32_bf16 v[76:79], v[156:159], v[164:167], v[76:79]
	v_mfma_f32_16x16x32_bf16 v[64:67], v[148:151], v[172:175], v[64:67]
	v_mfma_f32_16x16x32_bf16 v[60:63], v[156:159], v[172:175], v[60:63]
	v_mfma_f32_16x16x32_bf16 v[48:51], v[148:151], v[180:183], v[48:51]
	v_mfma_f32_16x16x32_bf16 v[44:47], v[156:159], v[180:183], v[44:47]
	v_mfma_f32_16x16x32_bf16 v[32:35], v[148:151], v[188:191], v[32:35]
	v_mfma_f32_16x16x32_bf16 v[24:27], v[156:159], v[188:191], v[24:27]
	v_mfma_f32_16x16x32_bf16 v[84:87], v[152:155], v[168:171], v[84:87]
	v_mfma_f32_16x16x32_bf16 v[76:79], v[160:163], v[168:171], v[76:79]
	v_mfma_f32_16x16x32_bf16 v[64:67], v[152:155], v[176:179], v[64:67]
	v_mfma_f32_16x16x32_bf16 v[60:63], v[160:163], v[176:179], v[60:63]
	v_mfma_f32_16x16x32_bf16 v[48:51], v[152:155], v[184:187], v[48:51]
	v_mfma_f32_16x16x32_bf16 v[44:47], v[160:163], v[184:187], v[44:47]
	v_mfma_f32_16x16x32_bf16 v[32:35], v[152:155], v[192:195], v[32:35]
	v_mfma_f32_16x16x32_bf16 v[24:27], v[160:163], v[192:195], v[24:27]
	s_setprio 0
	s_barrier
	s_add_i32 s38, s49, s40
	v_add_u32_e32 v1, 0x1c000, v231
	v_lshl_add_u64 v[2:3], v[2:3], 0, s[16:17]
	s_mov_b32 m0, s38
	ds_read_b128 v[132:135], v1
	ds_read_b128 v[136:139], v1 offset:1024
	ds_read_b128 v[140:143], v1 offset:2048
	ds_read_b128 v[144:147], v1 offset:3072
	global_load_lds_dwordx4 v[2:3], off
	v_lshl_add_u64 v[2:3], v[220:221], 0, s[16:17]
	s_add_i32 m0, s38, 0x2000
	s_nop 0
	global_load_lds_dwordx4 v[2:3], off
	s_barrier
	s_waitcnt lgkmcnt(0)
	s_setprio 1
	s_waitcnt lgkmcnt(0)
	v_mfma_f32_16x16x32_bf16 v[72:75], v[132:135], v[164:167], v[72:75]
	v_mfma_f32_16x16x32_bf16 v[68:71], v[140:143], v[164:167], v[68:71]
	v_mfma_f32_16x16x32_bf16 v[56:59], v[132:135], v[172:175], v[56:59]
	v_mfma_f32_16x16x32_bf16 v[52:55], v[140:143], v[172:175], v[52:55]
	v_mfma_f32_16x16x32_bf16 v[40:43], v[132:135], v[180:183], v[40:43]
	v_mfma_f32_16x16x32_bf16 v[36:39], v[140:143], v[180:183], v[36:39]
	v_mfma_f32_16x16x32_bf16 v[20:23], v[132:135], v[188:191], v[20:23]
	v_mfma_f32_16x16x32_bf16 v[12:15], v[140:143], v[188:191], v[12:15]
	v_mfma_f32_16x16x32_bf16 v[72:75], v[136:139], v[168:171], v[72:75]
	v_mfma_f32_16x16x32_bf16 v[68:71], v[144:147], v[168:171], v[68:71]
	v_mfma_f32_16x16x32_bf16 v[56:59], v[136:139], v[176:179], v[56:59]
	v_mfma_f32_16x16x32_bf16 v[52:55], v[144:147], v[176:179], v[52:55]
	v_mfma_f32_16x16x32_bf16 v[40:43], v[136:139], v[184:187], v[40:43]
	v_mfma_f32_16x16x32_bf16 v[36:39], v[144:147], v[184:187], v[36:39]
	v_mfma_f32_16x16x32_bf16 v[20:23], v[136:139], v[192:195], v[20:23]
	v_mfma_f32_16x16x32_bf16 v[12:15], v[144:147], v[192:195], v[12:15]
	s_setprio 0
	s_mov_b32 m0, s57
	v_lshl_add_u64 v[2:3], v[222:223], 0, s[16:17]
	s_barrier
	ds_read_b128 v[188:191], v230 offset:49152
	ds_read_b128 v[192:195], v230 offset:50176
	ds_read_b128 v[180:183], v230 offset:51200
	ds_read_b128 v[184:187], v230 offset:52224
	ds_read_b128 v[172:175], v230 offset:53248
	ds_read_b128 v[176:179], v230 offset:54272
	ds_read_b128 v[164:167], v230 offset:55296
	ds_read_b128 v[168:171], v230 offset:56320
	global_load_lds_dwordx4 v[2:3], off
	v_lshl_add_u64 v[2:3], v[224:225], 0, s[16:17]
	s_mov_b32 m0, s58
	s_and_b64 vcc, exec, s[12:13]
	global_load_lds_dwordx4 v[2:3], off
	s_barrier
	s_waitcnt lgkmcnt(0)
	s_cbranch_vccnz .LBB0_2723
	s_setprio 1
	s_waitcnt lgkmcnt(0)
	v_mfma_f32_16x16x32_bf16 v[128:131], v[148:151], v[188:191], v[128:131]
	v_mfma_f32_16x16x32_bf16 v[124:127], v[156:159], v[188:191], v[124:127]
	v_mfma_f32_16x16x32_bf16 v[112:115], v[148:151], v[180:183], v[112:115]
	v_mfma_f32_16x16x32_bf16 v[108:111], v[156:159], v[180:183], v[108:111]
	v_mfma_f32_16x16x32_bf16 v[96:99], v[148:151], v[172:175], v[96:99]
	v_mfma_f32_16x16x32_bf16 v[92:95], v[156:159], v[172:175], v[92:95]
	v_mfma_f32_16x16x32_bf16 v[28:31], v[148:151], v[164:167], v[28:31]
	v_mfma_f32_16x16x32_bf16 v[16:19], v[156:159], v[164:167], v[16:19]
	v_mfma_f32_16x16x32_bf16 v[128:131], v[152:155], v[192:195], v[128:131]
	v_mfma_f32_16x16x32_bf16 v[124:127], v[160:163], v[192:195], v[124:127]
	v_mfma_f32_16x16x32_bf16 v[112:115], v[152:155], v[184:187], v[112:115]
	v_mfma_f32_16x16x32_bf16 v[108:111], v[160:163], v[184:187], v[108:111]
	v_mfma_f32_16x16x32_bf16 v[96:99], v[152:155], v[176:179], v[96:99]
	v_mfma_f32_16x16x32_bf16 v[92:95], v[160:163], v[176:179], v[92:95]
	v_mfma_f32_16x16x32_bf16 v[28:31], v[152:155], v[168:171], v[28:31]
	v_mfma_f32_16x16x32_bf16 v[16:19], v[160:163], v[168:171], v[16:19]
	s_setprio 0

.LBB0_2892:
	ds_read_b128 v[148:151], v222
	ds_read_b128 v[152:155], v222 offset:1024
	ds_read_b128 v[156:159], v222 offset:2048
	ds_read_b128 v[160:163], v222 offset:3072
	s_add_u32 s12, s28, 0xfffc0080
	s_addc_u32 s13, s29, -1
	s_cmp_eq_u32 s56, s59
	s_cselect_b32 s35, s2, s13
	s_cselect_b32 s34, s15, s12
	s_cselect_b32 s31, s17, s58
	s_cselect_b32 s30, s23, s57
	v_lshl_add_u64 v[2:3], s[28:29], 0, v[204:205]
	s_add_i32 m0, s36, 0xc000
	ds_read_b128 v[164:167], v223
	ds_read_b128 v[168:171], v223 offset:1024
	ds_read_b128 v[172:175], v223 offset:2048
	ds_read_b128 v[176:179], v223 offset:3072
	ds_read_b128 v[180:183], v223 offset:4096
	ds_read_b128 v[184:187], v223 offset:5120
	ds_read_b128 v[188:191], v223 offset:6144
	ds_read_b128 v[192:195], v223 offset:7168
	global_load_lds_dwordx4 v[2:3], off
	v_lshl_add_u64 v[2:3], s[28:29], 0, v[206:207]
	s_add_i32 m0, s36, 0xe000
	s_nop 0
	global_load_lds_dwordx4 v[2:3], off
	s_waitcnt lgkmcnt(8)
	s_barrier
	s_waitcnt lgkmcnt(0)
	s_setprio 1
	s_waitcnt lgkmcnt(0)
	v_mfma_f32_16x16x32_bf16 v[124:127], v[148:151], v[164:167], v[124:127]
	v_mfma_f32_16x16x32_bf16 v[116:119], v[156:159], v[164:167], v[116:119]
	v_mfma_f32_16x16x32_bf16 v[108:111], v[148:151], v[172:175], v[108:111]
	v_mfma_f32_16x16x32_bf16 v[100:103], v[156:159], v[172:175], v[100:103]
	v_mfma_f32_16x16x32_bf16 v[92:95], v[148:151], v[180:183], v[92:95]
	v_mfma_f32_16x16x32_bf16 v[84:87], v[156:159], v[180:183], v[84:87]
	v_mfma_f32_16x16x32_bf16 v[76:79], v[148:151], v[188:191], v[76:79]
	v_mfma_f32_16x16x32_bf16 v[72:75], v[156:159], v[188:191], v[72:75]
	v_mfma_f32_16x16x32_bf16 v[124:127], v[152:155], v[168:171], v[124:127]
	v_mfma_f32_16x16x32_bf16 v[116:119], v[160:163], v[168:171], v[116:119]
	v_mfma_f32_16x16x32_bf16 v[108:111], v[152:155], v[176:179], v[108:111]
	v_mfma_f32_16x16x32_bf16 v[100:103], v[160:163], v[176:179], v[100:103]
	v_mfma_f32_16x16x32_bf16 v[92:95], v[152:155], v[184:187], v[92:95]
	v_mfma_f32_16x16x32_bf16 v[84:87], v[160:163], v[184:187], v[84:87]
	v_mfma_f32_16x16x32_bf16 v[76:79], v[152:155], v[192:195], v[76:79]
	v_mfma_f32_16x16x32_bf16 v[72:75], v[160:163], v[192:195], v[72:75]
	s_setprio 0
	s_barrier
	s_add_i32 s12, s46, s25
	v_lshl_add_u64 v[2:3], s[30:31], 0, v[198:199]
	s_mov_b32 m0, s12
	ds_read_b128 v[132:135], v225
	ds_read_b128 v[136:139], v225 offset:1024
	ds_read_b128 v[140:143], v225 offset:2048
	ds_read_b128 v[144:147], v225 offset:3072
	global_load_lds_dwordx4 v[2:3], off
	v_lshl_add_u64 v[212:213], s[30:31], 0, v[202:203]
	s_add_i32 m0, s12, 0x2000
	s_nop 0
	global_load_lds_dwordx4 v[212:213], off
	s_barrier
	s_waitcnt lgkmcnt(0)
	s_setprio 1
	s_waitcnt lgkmcnt(0)
	v_mfma_f32_16x16x32_bf16 v[128:131], v[132:135], v[164:167], v[128:131]
	v_mfma_f32_16x16x32_bf16 v[120:123], v[140:143], v[164:167], v[120:123]
	v_mfma_f32_16x16x32_bf16 v[112:115], v[132:135], v[172:175], v[112:115]
	v_mfma_f32_16x16x32_bf16 v[104:107], v[140:143], v[172:175], v[104:107]
	v_mfma_f32_16x16x32_bf16 v[96:99], v[132:135], v[180:183], v[96:99]
	v_mfma_f32_16x16x32_bf16 v[88:91], v[140:143], v[180:183], v[88:91]
	v_mfma_f32_16x16x32_bf16 v[80:83], v[132:135], v[188:191], v[80:83]
	v_mfma_f32_16x16x32_bf16 v[68:71], v[140:143], v[188:191], v[68:71]
	v_mfma_f32_16x16x32_bf16 v[128:131], v[136:139], v[168:171], v[128:131]
	v_mfma_f32_16x16x32_bf16 v[120:123], v[144:147], v[168:171], v[120:123]
	v_mfma_f32_16x16x32_bf16 v[112:115], v[136:139], v[176:179], v[112:115]
	v_mfma_f32_16x16x32_bf16 v[104:107], v[144:147], v[176:179], v[104:107]
	v_mfma_f32_16x16x32_bf16 v[96:99], v[136:139], v[184:187], v[96:99]
	v_mfma_f32_16x16x32_bf16 v[88:91], v[144:147], v[184:187], v[88:91]
	v_mfma_f32_16x16x32_bf16 v[80:83], v[136:139], v[192:195], v[80:83]
	v_mfma_f32_16x16x32_bf16 v[68:71], v[144:147], v[192:195], v[68:71]
	s_setprio 0
	s_mov_b32 m0, s36
	v_lshl_add_u64 v[214:215], s[34:35], 0, v[196:197]
	s_barrier
	ds_read_b128 v[188:191], v223 offset:16384
	ds_read_b128 v[192:195], v223 offset:17408
	ds_read_b128 v[180:183], v223 offset:18432
	ds_read_b128 v[184:187], v223 offset:19456
	ds_read_b128 v[172:175], v223 offset:20480
	ds_read_b128 v[176:179], v223 offset:21504
	ds_read_b128 v[164:167], v223 offset:22528
	ds_read_b128 v[168:171], v223 offset:23552
	global_load_lds_dwordx4 v[214:215], off
	v_lshl_add_u64 v[216:217], s[34:35], 0, v[200:201]
	s_mov_b32 m0, s37
	v_cmp_ne_u32_e64 s[12:13], 1, v234
	global_load_lds_dwordx4 v[216:217], off
	s_barrier
	s_waitcnt lgkmcnt(0)
	s_andn2_b64 vcc, exec, s[26:27]
	s_cbranch_vccnz .LBB0_2894
	s_setprio 1
	s_waitcnt lgkmcnt(0)
	v_mfma_f32_16x16x32_bf16 v[60:63], v[148:151], v[188:191], v[60:63]
	v_mfma_f32_16x16x32_bf16 v[52:55], v[156:159], v[188:191], v[52:55]
	v_mfma_f32_16x16x32_bf16 v[44:47], v[148:151], v[180:183], v[44:47]
	v_mfma_f32_16x16x32_bf16 v[36:39], v[156:159], v[180:183], v[36:39]
	v_mfma_f32_16x16x32_bf16 v[28:31], v[148:151], v[172:175], v[28:31]
	v_mfma_f32_16x16x32_bf16 v[20:23], v[156:159], v[172:175], v[20:23]
	v_mfma_f32_16x16x32_bf16 v[12:15], v[148:151], v[164:167], v[12:15]
	v_mfma_f32_16x16x32_bf16 v[4:7], v[156:159], v[164:167], v[4:7]
	v_mfma_f32_16x16x32_bf16 v[60:63], v[152:155], v[192:195], v[60:63]
	v_mfma_f32_16x16x32_bf16 v[52:55], v[160:163], v[192:195], v[52:55]
	v_mfma_f32_16x16x32_bf16 v[44:47], v[152:155], v[184:187], v[44:47]
	v_mfma_f32_16x16x32_bf16 v[36:39], v[160:163], v[184:187], v[36:39]
	v_mfma_f32_16x16x32_bf16 v[28:31], v[152:155], v[176:179], v[28:31]
	v_mfma_f32_16x16x32_bf16 v[20:23], v[160:163], v[176:179], v[20:23]
	v_mfma_f32_16x16x32_bf16 v[12:15], v[152:155], v[168:171], v[12:15]
	v_mfma_f32_16x16x32_bf16 v[4:7], v[160:163], v[168:171], v[4:7]
	s_setprio 0

.LBB0_2896:
	s_add_i32 s60, 0, 0x18000
	v_add_u32_e32 v1, s60, v220
	s_barrier
	ds_read_b128 v[148:151], v1
	ds_read_b128 v[152:155], v1 offset:1024
	ds_read_b128 v[156:159], v1 offset:2048
	ds_read_b128 v[160:163], v1 offset:3072
	s_add_u32 s34, s34, 0x40000
	s_addc_u32 s35, s35, 0
	s_mov_b32 m0, s40
	v_lshl_add_u64 v[132:133], s[34:35], 0, v[196:197]
	ds_read_b128 v[164:167], v223 offset:32768
	ds_read_b128 v[168:171], v223 offset:33792
	ds_read_b128 v[172:175], v223 offset:34816
	ds_read_b128 v[176:179], v223 offset:35840
	ds_read_b128 v[180:183], v223 offset:36864
	ds_read_b128 v[184:187], v223 offset:37888
	ds_read_b128 v[188:191], v223 offset:38912
	ds_read_b128 v[192:195], v223 offset:39936
	global_load_lds_dwordx4 v[132:133], off
	v_lshl_add_u64 v[132:133], s[34:35], 0, v[200:201]
	s_mov_b32 m0, s41
	s_nop 0
	global_load_lds_dwordx4 v[132:133], off
	s_waitcnt lgkmcnt(8)
	s_barrier
	s_waitcnt lgkmcnt(0)
	s_setprio 1
	s_waitcnt lgkmcnt(0)
	v_mfma_f32_16x16x32_bf16 v[124:127], v[148:151], v[164:167], v[124:127]
	v_mfma_f32_16x16x32_bf16 v[116:119], v[156:159], v[164:167], v[116:119]
	v_mfma_f32_16x16x32_bf16 v[108:111], v[148:151], v[172:175], v[108:111]
	v_mfma_f32_16x16x32_bf16 v[100:103], v[156:159], v[172:175], v[100:103]
	v_mfma_f32_16x16x32_bf16 v[92:95], v[148:151], v[180:183], v[92:95]
	v_mfma_f32_16x16x32_bf16 v[84:87], v[156:159], v[180:183], v[84:87]
	v_mfma_f32_16x16x32_bf16 v[76:79], v[148:151], v[188:191], v[76:79]
	v_mfma_f32_16x16x32_bf16 v[72:75], v[156:159], v[188:191], v[72:75]
	v_mfma_f32_16x16x32_bf16 v[124:127], v[152:155], v[168:171], v[124:127]
	v_mfma_f32_16x16x32_bf16 v[116:119], v[160:163], v[168:171], v[116:119]
	v_mfma_f32_16x16x32_bf16 v[108:111], v[152:155], v[176:179], v[108:111]
	v_mfma_f32_16x16x32_bf16 v[100:103], v[160:163], v[176:179], v[100:103]
	v_mfma_f32_16x16x32_bf16 v[92:95], v[152:155], v[184:187], v[92:95]
	v_mfma_f32_16x16x32_bf16 v[84:87], v[160:163], v[184:187], v[84:87]
	v_mfma_f32_16x16x32_bf16 v[76:79], v[152:155], v[192:195], v[76:79]
	v_mfma_f32_16x16x32_bf16 v[72:75], v[160:163], v[192:195], v[72:75]
	s_setprio 0
	s_barrier
	s_add_i32 s34, s60, s25
	v_add_u32_e32 v1, 0x1c000, v224
	v_lshl_add_u64 v[2:3], v[2:3], 0, s[6:7]
	s_mov_b32 m0, s34
	ds_read_b128 v[132:135], v1
	ds_read_b128 v[136:139], v1 offset:1024
	ds_read_b128 v[140:143], v1 offset:2048
	ds_read_b128 v[144:147], v1 offset:3072
	global_load_lds_dwordx4 v[2:3], off
	v_lshl_add_u64 v[2:3], v[212:213], 0, s[6:7]
	s_add_i32 m0, s34, 0x2000
	s_nop 0
	global_load_lds_dwordx4 v[2:3], off
	s_barrier
	s_waitcnt lgkmcnt(0)
	s_setprio 1
	s_waitcnt lgkmcnt(0)
	v_mfma_f32_16x16x32_bf16 v[128:131], v[132:135], v[164:167], v[128:131]
	v_mfma_f32_16x16x32_bf16 v[120:123], v[140:143], v[164:167], v[120:123]
	v_mfma_f32_16x16x32_bf16 v[112:115], v[132:135], v[172:175], v[112:115]
	v_mfma_f32_16x16x32_bf16 v[104:107], v[140:143], v[172:175], v[104:107]
	v_mfma_f32_16x16x32_bf16 v[96:99], v[132:135], v[180:183], v[96:99]
	v_mfma_f32_16x16x32_bf16 v[88:91], v[140:143], v[180:183], v[88:91]
	v_mfma_f32_16x16x32_bf16 v[80:83], v[132:135], v[188:191], v[80:83]
	v_mfma_f32_16x16x32_bf16 v[68:71], v[140:143], v[188:191], v[68:71]
	v_mfma_f32_16x16x32_bf16 v[128:131], v[136:139], v[168:171], v[128:131]
	v_mfma_f32_16x16x32_bf16 v[120:123], v[144:147], v[168:171], v[120:123]
	v_mfma_f32_16x16x32_bf16 v[112:115], v[136:139], v[176:179], v[112:115]
	v_mfma_f32_16x16x32_bf16 v[104:107], v[144:147], v[176:179], v[104:107]
	v_mfma_f32_16x16x32_bf16 v[96:99], v[136:139], v[184:187], v[96:99]
	v_mfma_f32_16x16x32_bf16 v[88:91], v[144:147], v[184:187], v[88:91]
	v_mfma_f32_16x16x32_bf16 v[80:83], v[136:139], v[192:195], v[80:83]
	v_mfma_f32_16x16x32_bf16 v[68:71], v[144:147], v[192:195], v[68:71]
	s_setprio 0
	s_mov_b32 m0, s48
	v_lshl_add_u64 v[2:3], v[214:215], 0, s[6:7]
	s_barrier
	ds_read_b128 v[188:191], v223 offset:49152
	ds_read_b128 v[192:195], v223 offset:50176
	ds_read_b128 v[180:183], v223 offset:51200
	ds_read_b128 v[184:187], v223 offset:52224
	ds_read_b128 v[172:175], v223 offset:53248
	ds_read_b128 v[176:179], v223 offset:54272
	ds_read_b128 v[164:167], v223 offset:55296
	ds_read_b128 v[168:171], v223 offset:56320
	global_load_lds_dwordx4 v[2:3], off
	v_lshl_add_u64 v[2:3], v[216:217], 0, s[6:7]
	s_mov_b32 m0, s49
	s_and_b64 vcc, exec, s[12:13]
	global_load_lds_dwordx4 v[2:3], off
	s_barrier
	s_waitcnt lgkmcnt(0)
	s_cbranch_vccnz .LBB0_2898
	s_setprio 1
	s_waitcnt lgkmcnt(0)
	v_mfma_f32_16x16x32_bf16 v[60:63], v[148:151], v[188:191], v[60:63]
	v_mfma_f32_16x16x32_bf16 v[52:55], v[156:159], v[188:191], v[52:55]
	v_mfma_f32_16x16x32_bf16 v[44:47], v[148:151], v[180:183], v[44:47]
	v_mfma_f32_16x16x32_bf16 v[36:39], v[156:159], v[180:183], v[36:39]
	v_mfma_f32_16x16x32_bf16 v[28:31], v[148:151], v[172:175], v[28:31]
	v_mfma_f32_16x16x32_bf16 v[20:23], v[156:159], v[172:175], v[20:23]
	v_mfma_f32_16x16x32_bf16 v[12:15], v[148:151], v[164:167], v[12:15]
	v_mfma_f32_16x16x32_bf16 v[2:5], v[156:159], v[164:167], v[4:7]
	v_mfma_f32_16x16x32_bf16 v[60:63], v[152:155], v[192:195], v[60:63]
	v_mfma_f32_16x16x32_bf16 v[52:55], v[160:163], v[192:195], v[52:55]
	v_mfma_f32_16x16x32_bf16 v[44:47], v[152:155], v[184:187], v[44:47]
	v_mfma_f32_16x16x32_bf16 v[36:39], v[160:163], v[184:187], v[36:39]
	v_mfma_f32_16x16x32_bf16 v[28:31], v[152:155], v[176:179], v[28:31]
	v_mfma_f32_16x16x32_bf16 v[20:23], v[160:163], v[176:179], v[20:23]
	v_mfma_f32_16x16x32_bf16 v[12:15], v[152:155], v[168:171], v[12:15]
	v_mfma_f32_16x16x32_bf16 v[4:7], v[160:163], v[168:171], v[2:5]
	s_setprio 0

.LBB0_3007:
	ds_read_b128 v[148:151], v205
	ds_read_b128 v[152:155], v205 offset:1024
	ds_read_b128 v[156:159], v205 offset:2048
	ds_read_b128 v[160:163], v205 offset:3072
	s_mov_b64 s[12:13], s[22:23]
	s_add_u32 s22, s12, 0x100
	s_addc_u32 s23, s13, 0
	s_cmp_eq_u32 s5, s46
	s_cselect_b32 s29, s19, s23
	s_cselect_b32 s28, s18, s22
	s_cselect_b32 s27, s21, s17
	s_cselect_b32 s26, s20, s6
	v_lshl_add_u64 v[2:3], s[12:13], 0, v[214:215]
	s_add_i32 m0, s36, 0xc000
	ds_read_b128 v[164:167], v230
	ds_read_b128 v[168:171], v230 offset:1024
	ds_read_b128 v[172:175], v230 offset:2048
	ds_read_b128 v[176:179], v230 offset:3072
	ds_read_b128 v[180:183], v230 offset:4096
	ds_read_b128 v[184:187], v230 offset:5120
	ds_read_b128 v[188:191], v230 offset:6144
	ds_read_b128 v[192:195], v230 offset:7168
	global_load_lds_dwordx4 v[2:3], off
	v_lshl_add_u64 v[2:3], s[12:13], 0, v[216:217]
	s_add_i32 m0, s36, 0xe000
	s_nop 0
	global_load_lds_dwordx4 v[2:3], off
	s_waitcnt lgkmcnt(8)
	s_barrier
	s_waitcnt lgkmcnt(0)
	s_setprio 1
	s_waitcnt lgkmcnt(0)
	v_mfma_f32_16x16x32_bf16 v[84:87], v[148:151], v[164:167], v[84:87]
	v_mfma_f32_16x16x32_bf16 v[76:79], v[156:159], v[164:167], v[76:79]
	v_mfma_f32_16x16x32_bf16 v[64:67], v[148:151], v[172:175], v[64:67]
	v_mfma_f32_16x16x32_bf16 v[60:63], v[156:159], v[172:175], v[60:63]
	v_mfma_f32_16x16x32_bf16 v[48:51], v[148:151], v[180:183], v[48:51]
	v_mfma_f32_16x16x32_bf16 v[44:47], v[156:159], v[180:183], v[44:47]
	v_mfma_f32_16x16x32_bf16 v[32:35], v[148:151], v[188:191], v[32:35]
	v_mfma_f32_16x16x32_bf16 v[24:27], v[156:159], v[188:191], v[24:27]
	v_mfma_f32_16x16x32_bf16 v[84:87], v[152:155], v[168:171], v[84:87]
	v_mfma_f32_16x16x32_bf16 v[76:79], v[160:163], v[168:171], v[76:79]
	v_mfma_f32_16x16x32_bf16 v[64:67], v[152:155], v[176:179], v[64:67]
	v_mfma_f32_16x16x32_bf16 v[60:63], v[160:163], v[176:179], v[60:63]
	v_mfma_f32_16x16x32_bf16 v[48:51], v[152:155], v[184:187], v[48:51]
	v_mfma_f32_16x16x32_bf16 v[44:47], v[160:163], v[184:187], v[44:47]
	v_mfma_f32_16x16x32_bf16 v[32:35], v[152:155], v[192:195], v[32:35]
	v_mfma_f32_16x16x32_bf16 v[24:27], v[160:163], v[192:195], v[24:27]
	s_setprio 0
	s_barrier
	s_add_i32 s12, s59, s34
	v_lshl_add_u64 v[2:3], s[26:27], 0, v[198:199]
	s_mov_b32 m0, s12
	ds_read_b128 v[132:135], v232
	ds_read_b128 v[136:139], v232 offset:1024
	ds_read_b128 v[140:143], v232 offset:2048
	ds_read_b128 v[144:147], v232 offset:3072
	global_load_lds_dwordx4 v[2:3], off
	v_lshl_add_u64 v[220:221], s[26:27], 0, v[202:203]
	s_add_i32 m0, s12, 0x2000
	s_nop 0
	global_load_lds_dwordx4 v[220:221], off
	s_barrier
	s_waitcnt lgkmcnt(0)
	s_setprio 1
	s_waitcnt lgkmcnt(0)
	v_mfma_f32_16x16x32_bf16 v[72:75], v[132:135], v[164:167], v[72:75]
	v_mfma_f32_16x16x32_bf16 v[68:71], v[140:143], v[164:167], v[68:71]
	v_mfma_f32_16x16x32_bf16 v[56:59], v[132:135], v[172:175], v[56:59]
	v_mfma_f32_16x16x32_bf16 v[52:55], v[140:143], v[172:175], v[52:55]
	v_mfma_f32_16x16x32_bf16 v[40:43], v[132:135], v[180:183], v[40:43]
	v_mfma_f32_16x16x32_bf16 v[36:39], v[140:143], v[180:183], v[36:39]
	v_mfma_f32_16x16x32_bf16 v[20:23], v[132:135], v[188:191], v[20:23]
	v_mfma_f32_16x16x32_bf16 v[12:15], v[140:143], v[188:191], v[12:15]
	v_mfma_f32_16x16x32_bf16 v[72:75], v[136:139], v[168:171], v[72:75]
	v_mfma_f32_16x16x32_bf16 v[68:71], v[144:147], v[168:171], v[68:71]
	v_mfma_f32_16x16x32_bf16 v[56:59], v[136:139], v[176:179], v[56:59]
	v_mfma_f32_16x16x32_bf16 v[52:55], v[144:147], v[176:179], v[52:55]
	v_mfma_f32_16x16x32_bf16 v[40:43], v[136:139], v[184:187], v[40:43]
	v_mfma_f32_16x16x32_bf16 v[36:39], v[144:147], v[184:187], v[36:39]
	v_mfma_f32_16x16x32_bf16 v[20:23], v[136:139], v[192:195], v[20:23]
	v_mfma_f32_16x16x32_bf16 v[12:15], v[144:147], v[192:195], v[12:15]
	s_setprio 0
	s_mov_b32 m0, s36
	v_lshl_add_u64 v[222:223], s[28:29], 0, v[196:197]
	s_barrier
	ds_read_b128 v[188:191], v230 offset:16384
	ds_read_b128 v[192:195], v230 offset:17408
	ds_read_b128 v[180:183], v230 offset:18432
	ds_read_b128 v[184:187], v230 offset:19456
	ds_read_b128 v[172:175], v230 offset:20480
	ds_read_b128 v[176:179], v230 offset:21504
	ds_read_b128 v[164:167], v230 offset:22528
	ds_read_b128 v[168:171], v230 offset:23552
	global_load_lds_dwordx4 v[222:223], off
	v_lshl_add_u64 v[224:225], s[28:29], 0, v[200:201]
	s_mov_b32 m0, s37
	v_cmp_ne_u32_e64 s[12:13], 1, v233
	global_load_lds_dwordx4 v[224:225], off
	s_barrier
	s_waitcnt lgkmcnt(0)
	s_andn2_b64 vcc, exec, s[24:25]
	s_cbranch_vccnz .LBB0_3009
	s_setprio 1
	s_waitcnt lgkmcnt(0)
	v_mfma_f32_16x16x32_bf16 v[128:131], v[148:151], v[188:191], v[128:131]
	v_mfma_f32_16x16x32_bf16 v[124:127], v[156:159], v[188:191], v[124:127]
	v_mfma_f32_16x16x32_bf16 v[112:115], v[148:151], v[180:183], v[112:115]
	v_mfma_f32_16x16x32_bf16 v[108:111], v[156:159], v[180:183], v[108:111]
	v_mfma_f32_16x16x32_bf16 v[96:99], v[148:151], v[172:175], v[96:99]
	v_mfma_f32_16x16x32_bf16 v[92:95], v[156:159], v[172:175], v[92:95]
	v_mfma_f32_16x16x32_bf16 v[28:31], v[148:151], v[164:167], v[28:31]
	v_mfma_f32_16x16x32_bf16 v[16:19], v[156:159], v[164:167], v[16:19]
	v_mfma_f32_16x16x32_bf16 v[128:131], v[152:155], v[192:195], v[128:131]
	v_mfma_f32_16x16x32_bf16 v[124:127], v[160:163], v[192:195], v[124:127]
	v_mfma_f32_16x16x32_bf16 v[112:115], v[152:155], v[184:187], v[112:115]
	v_mfma_f32_16x16x32_bf16 v[108:111], v[160:163], v[184:187], v[108:111]
	v_mfma_f32_16x16x32_bf16 v[96:99], v[152:155], v[176:179], v[96:99]
	v_mfma_f32_16x16x32_bf16 v[92:95], v[160:163], v[176:179], v[92:95]
	v_mfma_f32_16x16x32_bf16 v[28:31], v[152:155], v[168:171], v[28:31]
	v_mfma_f32_16x16x32_bf16 v[16:19], v[160:163], v[168:171], v[16:19]
	s_setprio 0

.LBB0_3011:
	s_add_i32 s47, 0, 0x18000
	v_add_u32_e32 v1, s47, v226
	s_barrier
	ds_read_b128 v[148:151], v1
	ds_read_b128 v[152:155], v1 offset:1024
	ds_read_b128 v[156:159], v1 offset:2048
	ds_read_b128 v[160:163], v1 offset:3072
	s_add_u32 s28, s28, 0xb0000
	s_addc_u32 s29, s29, 0
	s_mov_b32 m0, s40
	v_lshl_add_u64 v[132:133], s[28:29], 0, v[196:197]
	ds_read_b128 v[164:167], v230 offset:32768
	ds_read_b128 v[168:171], v230 offset:33792
	ds_read_b128 v[172:175], v230 offset:34816
	ds_read_b128 v[176:179], v230 offset:35840
	ds_read_b128 v[180:183], v230 offset:36864
	ds_read_b128 v[184:187], v230 offset:37888
	ds_read_b128 v[188:191], v230 offset:38912
	ds_read_b128 v[192:195], v230 offset:39936
	global_load_lds_dwordx4 v[132:133], off
	v_lshl_add_u64 v[132:133], s[28:29], 0, v[200:201]
	s_mov_b32 m0, s41
	s_nop 0
	global_load_lds_dwordx4 v[132:133], off
	s_waitcnt lgkmcnt(8)
	s_barrier
	s_waitcnt lgkmcnt(0)
	s_setprio 1
	s_waitcnt lgkmcnt(0)
	v_mfma_f32_16x16x32_bf16 v[84:87], v[148:151], v[164:167], v[84:87]
	v_mfma_f32_16x16x32_bf16 v[76:79], v[156:159], v[164:167], v[76:79]
	v_mfma_f32_16x16x32_bf16 v[64:67], v[148:151], v[172:175], v[64:67]
	v_mfma_f32_16x16x32_bf16 v[60:63], v[156:159], v[172:175], v[60:63]
	v_mfma_f32_16x16x32_bf16 v[48:51], v[148:151], v[180:183], v[48:51]
	v_mfma_f32_16x16x32_bf16 v[44:47], v[156:159], v[180:183], v[44:47]
	v_mfma_f32_16x16x32_bf16 v[32:35], v[148:151], v[188:191], v[32:35]
	v_mfma_f32_16x16x32_bf16 v[24:27], v[156:159], v[188:191], v[24:27]
	v_mfma_f32_16x16x32_bf16 v[84:87], v[152:155], v[168:171], v[84:87]
	v_mfma_f32_16x16x32_bf16 v[76:79], v[160:163], v[168:171], v[76:79]
	v_mfma_f32_16x16x32_bf16 v[64:67], v[152:155], v[176:179], v[64:67]
	v_mfma_f32_16x16x32_bf16 v[60:63], v[160:163], v[176:179], v[60:63]
	v_mfma_f32_16x16x32_bf16 v[48:51], v[152:155], v[184:187], v[48:51]
	v_mfma_f32_16x16x32_bf16 v[44:47], v[160:163], v[184:187], v[44:47]
	v_mfma_f32_16x16x32_bf16 v[32:35], v[152:155], v[192:195], v[32:35]
	v_mfma_f32_16x16x32_bf16 v[24:27], v[160:163], v[192:195], v[24:27]
	s_setprio 0
	s_barrier
	s_add_i32 s28, s47, s34
	v_add_u32_e32 v1, 0x1c000, v231
	v_lshl_add_u64 v[2:3], v[2:3], 0, s[14:15]
	s_mov_b32 m0, s28
	ds_read_b128 v[132:135], v1
	ds_read_b128 v[136:139], v1 offset:1024
	ds_read_b128 v[140:143], v1 offset:2048
	ds_read_b128 v[144:147], v1 offset:3072
	global_load_lds_dwordx4 v[2:3], off
	v_lshl_add_u64 v[2:3], v[220:221], 0, s[14:15]
	s_add_i32 m0, s28, 0x2000
	s_nop 0
	global_load_lds_dwordx4 v[2:3], off
	s_barrier
	s_waitcnt lgkmcnt(0)
	s_setprio 1
	s_waitcnt lgkmcnt(0)
	v_mfma_f32_16x16x32_bf16 v[72:75], v[132:135], v[164:167], v[72:75]
	v_mfma_f32_16x16x32_bf16 v[68:71], v[140:143], v[164:167], v[68:71]
	v_mfma_f32_16x16x32_bf16 v[56:59], v[132:135], v[172:175], v[56:59]
	v_mfma_f32_16x16x32_bf16 v[52:55], v[140:143], v[172:175], v[52:55]
	v_mfma_f32_16x16x32_bf16 v[40:43], v[132:135], v[180:183], v[40:43]
	v_mfma_f32_16x16x32_bf16 v[36:39], v[140:143], v[180:183], v[36:39]
	v_mfma_f32_16x16x32_bf16 v[20:23], v[132:135], v[188:191], v[20:23]
	v_mfma_f32_16x16x32_bf16 v[12:15], v[140:143], v[188:191], v[12:15]
	v_mfma_f32_16x16x32_bf16 v[72:75], v[136:139], v[168:171], v[72:75]
	v_mfma_f32_16x16x32_bf16 v[68:71], v[144:147], v[168:171], v[68:71]
	v_mfma_f32_16x16x32_bf16 v[56:59], v[136:139], v[176:179], v[56:59]
	v_mfma_f32_16x16x32_bf16 v[52:55], v[144:147], v[176:179], v[52:55]
	v_mfma_f32_16x16x32_bf16 v[40:43], v[136:139], v[184:187], v[40:43]
	v_mfma_f32_16x16x32_bf16 v[36:39], v[144:147], v[184:187], v[36:39]
	v_mfma_f32_16x16x32_bf16 v[20:23], v[136:139], v[192:195], v[20:23]
	v_mfma_f32_16x16x32_bf16 v[12:15], v[144:147], v[192:195], v[12:15]
	s_setprio 0
	s_mov_b32 m0, s53
	v_lshl_add_u64 v[2:3], v[222:223], 0, s[14:15]
	s_barrier
	ds_read_b128 v[188:191], v230 offset:49152
	ds_read_b128 v[192:195], v230 offset:50176
	ds_read_b128 v[180:183], v230 offset:51200
	ds_read_b128 v[184:187], v230 offset:52224
	ds_read_b128 v[172:175], v230 offset:53248
	ds_read_b128 v[176:179], v230 offset:54272
	ds_read_b128 v[164:167], v230 offset:55296
	ds_read_b128 v[168:171], v230 offset:56320
	global_load_lds_dwordx4 v[2:3], off
	v_lshl_add_u64 v[2:3], v[224:225], 0, s[14:15]
	s_mov_b32 m0, s54
	s_and_b64 vcc, exec, s[12:13]
	global_load_lds_dwordx4 v[2:3], off
	s_barrier
	s_waitcnt lgkmcnt(0)
	s_cbranch_vccnz .LBB0_3013
	s_setprio 1
	s_waitcnt lgkmcnt(0)
	v_mfma_f32_16x16x32_bf16 v[128:131], v[148:151], v[188:191], v[128:131]
	v_mfma_f32_16x16x32_bf16 v[124:127], v[156:159], v[188:191], v[124:127]
	v_mfma_f32_16x16x32_bf16 v[112:115], v[148:151], v[180:183], v[112:115]
	v_mfma_f32_16x16x32_bf16 v[108:111], v[156:159], v[180:183], v[108:111]
	v_mfma_f32_16x16x32_bf16 v[96:99], v[148:151], v[172:175], v[96:99]
	v_mfma_f32_16x16x32_bf16 v[92:95], v[156:159], v[172:175], v[92:95]
	v_mfma_f32_16x16x32_bf16 v[28:31], v[148:151], v[164:167], v[28:31]
	v_mfma_f32_16x16x32_bf16 v[16:19], v[156:159], v[164:167], v[16:19]
	v_mfma_f32_16x16x32_bf16 v[128:131], v[152:155], v[192:195], v[128:131]
	v_mfma_f32_16x16x32_bf16 v[124:127], v[160:163], v[192:195], v[124:127]
	v_mfma_f32_16x16x32_bf16 v[112:115], v[152:155], v[184:187], v[112:115]
	v_mfma_f32_16x16x32_bf16 v[108:111], v[160:163], v[184:187], v[108:111]
	v_mfma_f32_16x16x32_bf16 v[96:99], v[152:155], v[176:179], v[96:99]
	v_mfma_f32_16x16x32_bf16 v[92:95], v[160:163], v[176:179], v[92:95]
	v_mfma_f32_16x16x32_bf16 v[28:31], v[152:155], v[168:171], v[28:31]
	v_mfma_f32_16x16x32_bf16 v[16:19], v[160:163], v[168:171], v[16:19]
	s_setprio 0

.LBB0_3184:
	ds_read_b128 v[148:151], v223
	ds_read_b128 v[152:155], v223 offset:1024
	ds_read_b128 v[156:159], v223 offset:2048
	ds_read_b128 v[160:163], v223 offset:3072
	s_add_u32 s12, s16, 0xfffc0080
	s_addc_u32 s13, s17, -1
	s_cmp_eq_u32 s29, s48
	s_cselect_b32 s39, s2, s13
	s_cselect_b32 s38, s5, s12
	s_cselect_b32 s37, s20, s47
	s_cselect_b32 s36, s27, s46
	v_lshl_add_u64 v[2:3], s[16:17], 0, v[204:205]
	s_add_i32 m0, s52, 0xc000
	ds_read_b128 v[164:167], v224
	ds_read_b128 v[168:171], v224 offset:1024
	ds_read_b128 v[172:175], v224 offset:2048
	ds_read_b128 v[176:179], v224 offset:3072
	ds_read_b128 v[180:183], v224 offset:4096
	ds_read_b128 v[184:187], v224 offset:5120
	ds_read_b128 v[188:191], v224 offset:6144
	ds_read_b128 v[192:195], v224 offset:7168
	global_load_lds_dwordx4 v[2:3], off
	v_lshl_add_u64 v[2:3], s[16:17], 0, v[206:207]
	s_add_i32 m0, s52, 0xe000
	s_nop 0
	global_load_lds_dwordx4 v[2:3], off
	s_waitcnt lgkmcnt(8)
	s_barrier
	s_waitcnt lgkmcnt(0)
	s_setprio 1
	s_waitcnt lgkmcnt(0)
	v_mfma_f32_16x16x32_bf16 v[128:131], v[148:151], v[164:167], v[128:131]
	v_mfma_f32_16x16x32_bf16 v[124:127], v[156:159], v[164:167], v[124:127]
	v_mfma_f32_16x16x32_bf16 v[112:115], v[148:151], v[172:175], v[112:115]
	v_mfma_f32_16x16x32_bf16 v[108:111], v[156:159], v[172:175], v[108:111]
	v_mfma_f32_16x16x32_bf16 v[96:99], v[148:151], v[180:183], v[96:99]
	v_mfma_f32_16x16x32_bf16 v[92:95], v[156:159], v[180:183], v[92:95]
	v_mfma_f32_16x16x32_bf16 v[80:83], v[148:151], v[188:191], v[80:83]
	v_mfma_f32_16x16x32_bf16 v[76:79], v[156:159], v[188:191], v[76:79]
	v_mfma_f32_16x16x32_bf16 v[128:131], v[152:155], v[168:171], v[128:131]
	v_mfma_f32_16x16x32_bf16 v[124:127], v[160:163], v[168:171], v[124:127]
	v_mfma_f32_16x16x32_bf16 v[112:115], v[152:155], v[176:179], v[112:115]
	v_mfma_f32_16x16x32_bf16 v[108:111], v[160:163], v[176:179], v[108:111]
	v_mfma_f32_16x16x32_bf16 v[96:99], v[152:155], v[184:187], v[96:99]
	v_mfma_f32_16x16x32_bf16 v[92:95], v[160:163], v[184:187], v[92:95]
	v_mfma_f32_16x16x32_bf16 v[80:83], v[152:155], v[192:195], v[80:83]
	v_mfma_f32_16x16x32_bf16 v[76:79], v[160:163], v[192:195], v[76:79]
	s_setprio 0
	s_barrier
	s_add_i32 s12, s65, s19
	v_lshl_add_u64 v[2:3], s[36:37], 0, v[198:199]
	s_mov_b32 m0, s12
	ds_read_b128 v[132:135], v226
	ds_read_b128 v[136:139], v226 offset:1024
	ds_read_b128 v[140:143], v226 offset:2048
	ds_read_b128 v[144:147], v226 offset:3072
	global_load_lds_dwordx4 v[2:3], off
	v_lshl_add_u64 v[212:213], s[36:37], 0, v[202:203]
	s_add_i32 m0, s12, 0x2000
	s_nop 0
	global_load_lds_dwordx4 v[212:213], off
	s_barrier
	s_waitcnt lgkmcnt(0)
	s_setprio 1
	s_waitcnt lgkmcnt(0)
	v_mfma_f32_16x16x32_bf16 v[120:123], v[132:135], v[164:167], v[120:123]
	v_mfma_f32_16x16x32_bf16 v[116:119], v[140:143], v[164:167], v[116:119]
	v_mfma_f32_16x16x32_bf16 v[104:107], v[132:135], v[172:175], v[104:107]
	v_mfma_f32_16x16x32_bf16 v[100:103], v[140:143], v[172:175], v[100:103]
	v_mfma_f32_16x16x32_bf16 v[88:91], v[132:135], v[180:183], v[88:91]
	v_mfma_f32_16x16x32_bf16 v[84:87], v[140:143], v[180:183], v[84:87]
	v_mfma_f32_16x16x32_bf16 v[72:75], v[132:135], v[188:191], v[72:75]
	v_mfma_f32_16x16x32_bf16 v[68:71], v[140:143], v[188:191], v[68:71]
	v_mfma_f32_16x16x32_bf16 v[120:123], v[136:139], v[168:171], v[120:123]
	v_mfma_f32_16x16x32_bf16 v[116:119], v[144:147], v[168:171], v[116:119]
	v_mfma_f32_16x16x32_bf16 v[104:107], v[136:139], v[176:179], v[104:107]
	v_mfma_f32_16x16x32_bf16 v[100:103], v[144:147], v[176:179], v[100:103]
	v_mfma_f32_16x16x32_bf16 v[88:91], v[136:139], v[184:187], v[88:91]
	v_mfma_f32_16x16x32_bf16 v[84:87], v[144:147], v[184:187], v[84:87]
	v_mfma_f32_16x16x32_bf16 v[72:75], v[136:139], v[192:195], v[72:75]
	v_mfma_f32_16x16x32_bf16 v[68:71], v[144:147], v[192:195], v[68:71]
	s_setprio 0
	s_mov_b32 m0, s52
	v_lshl_add_u64 v[214:215], s[38:39], 0, v[196:197]
	s_barrier
	ds_read_b128 v[188:191], v224 offset:16384
	ds_read_b128 v[192:195], v224 offset:17408
	ds_read_b128 v[180:183], v224 offset:18432
	ds_read_b128 v[184:187], v224 offset:19456
	ds_read_b128 v[172:175], v224 offset:20480
	ds_read_b128 v[176:179], v224 offset:21504
	ds_read_b128 v[164:167], v224 offset:22528
	ds_read_b128 v[168:171], v224 offset:23552
	global_load_lds_dwordx4 v[214:215], off
	v_lshl_add_u64 v[216:217], s[38:39], 0, v[200:201]
	s_mov_b32 m0, s53
	v_cmp_ne_u32_e64 s[12:13], 1, v236
	global_load_lds_dwordx4 v[216:217], off
	s_barrier
	s_waitcnt lgkmcnt(0)
	s_andn2_b64 vcc, exec, s[14:15]
	s_cbranch_vccnz .LBB0_3186
	s_setprio 1
	s_waitcnt lgkmcnt(0)
	v_mfma_f32_16x16x32_bf16 v[64:67], v[148:151], v[188:191], v[64:67]
	v_mfma_f32_16x16x32_bf16 v[60:63], v[156:159], v[188:191], v[60:63]
	v_mfma_f32_16x16x32_bf16 v[48:51], v[148:151], v[180:183], v[48:51]
	v_mfma_f32_16x16x32_bf16 v[44:47], v[156:159], v[180:183], v[44:47]
	v_mfma_f32_16x16x32_bf16 v[32:35], v[148:151], v[172:175], v[32:35]
	v_mfma_f32_16x16x32_bf16 v[28:31], v[156:159], v[172:175], v[28:31]
	v_mfma_f32_16x16x32_bf16 v[16:19], v[148:151], v[164:167], v[16:19]
	v_mfma_f32_16x16x32_bf16 v[12:15], v[156:159], v[164:167], v[12:15]
	v_mfma_f32_16x16x32_bf16 v[64:67], v[152:155], v[192:195], v[64:67]
	v_mfma_f32_16x16x32_bf16 v[60:63], v[160:163], v[192:195], v[60:63]
	v_mfma_f32_16x16x32_bf16 v[48:51], v[152:155], v[184:187], v[48:51]
	v_mfma_f32_16x16x32_bf16 v[44:47], v[160:163], v[184:187], v[44:47]
	v_mfma_f32_16x16x32_bf16 v[32:35], v[152:155], v[176:179], v[32:35]
	v_mfma_f32_16x16x32_bf16 v[28:31], v[160:163], v[176:179], v[28:31]
	v_mfma_f32_16x16x32_bf16 v[16:19], v[152:155], v[168:171], v[16:19]
	v_mfma_f32_16x16x32_bf16 v[12:15], v[160:163], v[168:171], v[12:15]
	s_setprio 0

.LBB0_3188:
	s_add_i32 s49, 0, 0x18000
	v_add_u32_e32 v1, s49, v219
	s_barrier
	ds_read_b128 v[148:151], v1
	ds_read_b128 v[152:155], v1 offset:1024
	ds_read_b128 v[156:159], v1 offset:2048
	ds_read_b128 v[160:163], v1 offset:3072
	s_add_u32 s38, s38, 0x40000
	s_addc_u32 s39, s39, 0
	s_mov_b32 m0, s56
	v_lshl_add_u64 v[132:133], s[38:39], 0, v[196:197]
	ds_read_b128 v[164:167], v224 offset:32768
	ds_read_b128 v[168:171], v224 offset:33792
	ds_read_b128 v[172:175], v224 offset:34816
	ds_read_b128 v[176:179], v224 offset:35840
	ds_read_b128 v[180:183], v224 offset:36864
	ds_read_b128 v[184:187], v224 offset:37888
	ds_read_b128 v[188:191], v224 offset:38912
	ds_read_b128 v[192:195], v224 offset:39936
	global_load_lds_dwordx4 v[132:133], off
	v_lshl_add_u64 v[132:133], s[38:39], 0, v[200:201]
	s_mov_b32 m0, s57
	s_nop 0
	global_load_lds_dwordx4 v[132:133], off
	s_waitcnt lgkmcnt(8)
	s_barrier
	s_waitcnt lgkmcnt(0)
	s_setprio 1
	s_waitcnt lgkmcnt(0)
	v_mfma_f32_16x16x32_bf16 v[128:131], v[148:151], v[164:167], v[128:131]
	v_mfma_f32_16x16x32_bf16 v[124:127], v[156:159], v[164:167], v[124:127]
	v_mfma_f32_16x16x32_bf16 v[112:115], v[148:151], v[172:175], v[112:115]
	v_mfma_f32_16x16x32_bf16 v[108:111], v[156:159], v[172:175], v[108:111]
	v_mfma_f32_16x16x32_bf16 v[96:99], v[148:151], v[180:183], v[96:99]
	v_mfma_f32_16x16x32_bf16 v[92:95], v[156:159], v[180:183], v[92:95]
	v_mfma_f32_16x16x32_bf16 v[80:83], v[148:151], v[188:191], v[80:83]
	v_mfma_f32_16x16x32_bf16 v[76:79], v[156:159], v[188:191], v[76:79]
	v_mfma_f32_16x16x32_bf16 v[128:131], v[152:155], v[168:171], v[128:131]
	v_mfma_f32_16x16x32_bf16 v[124:127], v[160:163], v[168:171], v[124:127]
	v_mfma_f32_16x16x32_bf16 v[112:115], v[152:155], v[176:179], v[112:115]
	v_mfma_f32_16x16x32_bf16 v[108:111], v[160:163], v[176:179], v[108:111]
	v_mfma_f32_16x16x32_bf16 v[96:99], v[152:155], v[184:187], v[96:99]
	v_mfma_f32_16x16x32_bf16 v[92:95], v[160:163], v[184:187], v[92:95]
	v_mfma_f32_16x16x32_bf16 v[80:83], v[152:155], v[192:195], v[80:83]
	v_mfma_f32_16x16x32_bf16 v[76:79], v[160:163], v[192:195], v[76:79]
	s_setprio 0
	s_barrier
	s_add_i32 s38, s49, s19
	v_add_u32_e32 v1, 0x1c000, v225
	v_lshl_add_u64 v[2:3], v[2:3], 0, s[22:23]
	s_mov_b32 m0, s38
	ds_read_b128 v[132:135], v1
	ds_read_b128 v[136:139], v1 offset:1024
	ds_read_b128 v[140:143], v1 offset:2048
	ds_read_b128 v[144:147], v1 offset:3072
	global_load_lds_dwordx4 v[2:3], off
	v_lshl_add_u64 v[2:3], v[212:213], 0, s[22:23]
	s_add_i32 m0, s38, 0x2000
	s_nop 0
	global_load_lds_dwordx4 v[2:3], off
	s_barrier
	s_waitcnt lgkmcnt(0)
	s_setprio 1
	s_waitcnt lgkmcnt(0)
	v_mfma_f32_16x16x32_bf16 v[120:123], v[132:135], v[164:167], v[120:123]
	v_mfma_f32_16x16x32_bf16 v[116:119], v[140:143], v[164:167], v[116:119]
	v_mfma_f32_16x16x32_bf16 v[104:107], v[132:135], v[172:175], v[104:107]
	v_mfma_f32_16x16x32_bf16 v[100:103], v[140:143], v[172:175], v[100:103]
	v_mfma_f32_16x16x32_bf16 v[88:91], v[132:135], v[180:183], v[88:91]
	v_mfma_f32_16x16x32_bf16 v[84:87], v[140:143], v[180:183], v[84:87]
	v_mfma_f32_16x16x32_bf16 v[72:75], v[132:135], v[188:191], v[72:75]
	v_mfma_f32_16x16x32_bf16 v[68:71], v[140:143], v[188:191], v[68:71]
	v_mfma_f32_16x16x32_bf16 v[120:123], v[136:139], v[168:171], v[120:123]
	v_mfma_f32_16x16x32_bf16 v[116:119], v[144:147], v[168:171], v[116:119]
	v_mfma_f32_16x16x32_bf16 v[104:107], v[136:139], v[176:179], v[104:107]
	v_mfma_f32_16x16x32_bf16 v[100:103], v[144:147], v[176:179], v[100:103]
	v_mfma_f32_16x16x32_bf16 v[88:91], v[136:139], v[184:187], v[88:91]
	v_mfma_f32_16x16x32_bf16 v[84:87], v[144:147], v[184:187], v[84:87]
	v_mfma_f32_16x16x32_bf16 v[72:75], v[136:139], v[192:195], v[72:75]
	v_mfma_f32_16x16x32_bf16 v[68:71], v[144:147], v[192:195], v[68:71]
	s_setprio 0
	s_mov_b32 m0, s59
	v_lshl_add_u64 v[2:3], v[214:215], 0, s[22:23]
	s_barrier
	ds_read_b128 v[188:191], v224 offset:49152
	ds_read_b128 v[192:195], v224 offset:50176
	ds_read_b128 v[180:183], v224 offset:51200
	ds_read_b128 v[184:187], v224 offset:52224
	ds_read_b128 v[172:175], v224 offset:53248
	ds_read_b128 v[176:179], v224 offset:54272
	ds_read_b128 v[164:167], v224 offset:55296
	ds_read_b128 v[168:171], v224 offset:56320
	global_load_lds_dwordx4 v[2:3], off
	v_lshl_add_u64 v[2:3], v[216:217], 0, s[22:23]
	s_mov_b32 m0, s60
	s_and_b64 vcc, exec, s[12:13]
	global_load_lds_dwordx4 v[2:3], off
	s_barrier
	s_waitcnt lgkmcnt(0)
	s_cbranch_vccnz .LBB0_3190
	s_setprio 1
	s_waitcnt lgkmcnt(0)
	v_mfma_f32_16x16x32_bf16 v[64:67], v[148:151], v[188:191], v[64:67]
	v_mfma_f32_16x16x32_bf16 v[60:63], v[156:159], v[188:191], v[60:63]
	v_mfma_f32_16x16x32_bf16 v[48:51], v[148:151], v[180:183], v[48:51]
	v_mfma_f32_16x16x32_bf16 v[44:47], v[156:159], v[180:183], v[44:47]
	v_mfma_f32_16x16x32_bf16 v[32:35], v[148:151], v[172:175], v[32:35]
	v_mfma_f32_16x16x32_bf16 v[28:31], v[156:159], v[172:175], v[28:31]
	v_mfma_f32_16x16x32_bf16 v[16:19], v[148:151], v[164:167], v[16:19]
	v_mfma_f32_16x16x32_bf16 v[12:15], v[156:159], v[164:167], v[12:15]
	v_mfma_f32_16x16x32_bf16 v[64:67], v[152:155], v[192:195], v[64:67]
	v_mfma_f32_16x16x32_bf16 v[60:63], v[160:163], v[192:195], v[60:63]
	v_mfma_f32_16x16x32_bf16 v[48:51], v[152:155], v[184:187], v[48:51]
	v_mfma_f32_16x16x32_bf16 v[44:47], v[160:163], v[184:187], v[44:47]
	v_mfma_f32_16x16x32_bf16 v[32:35], v[152:155], v[176:179], v[32:35]
	v_mfma_f32_16x16x32_bf16 v[28:31], v[160:163], v[176:179], v[28:31]
	v_mfma_f32_16x16x32_bf16 v[16:19], v[152:155], v[168:171], v[16:19]
	v_mfma_f32_16x16x32_bf16 v[12:15], v[160:163], v[168:171], v[12:15]
	s_setprio 0

.LBB0_3442:
	ds_read_b128 v[156:159], v219
	ds_read_b128 v[160:163], v219 offset:1024
	ds_read_b128 v[164:167], v219 offset:2048
	ds_read_b128 v[168:171], v219 offset:3072
	s_mov_b64 s[10:11], s[4:5]
	s_add_u32 s4, s10, 0x100
	s_addc_u32 s5, s11, 0
	s_cmp_eq_u32 s47, s56
	s_cselect_b32 s23, s17, s5
	s_cselect_b32 s22, s16, s4
	s_cselect_b32 s21, s19, s49
	s_cselect_b32 s20, s18, s48
	v_lshl_add_u64 v[2:3], s[10:11], 0, v[204:205]
	s_add_i32 m0, s29, 0xc000
	ds_read_b128 v[104:107], v220
	ds_read_b128 v[172:175], v220 offset:1024
	ds_read_b128 v[176:179], v220 offset:2048
	ds_read_b128 v[180:183], v220 offset:3072
	ds_read_b128 v[184:187], v220 offset:4096
	ds_read_b128 v[188:191], v220 offset:5120
	ds_read_b128 v[192:195], v220 offset:6144
	ds_read_b128 v[212:215], v220 offset:7168
	global_load_lds_dwordx4 v[2:3], off
	v_lshl_add_u64 v[2:3], s[10:11], 0, v[206:207]
	s_add_i32 m0, s29, 0xe000
	s_nop 0
	global_load_lds_dwordx4 v[2:3], off
	s_waitcnt lgkmcnt(8)
	s_barrier
	s_waitcnt lgkmcnt(0)
	s_setprio 1
	s_waitcnt lgkmcnt(0)
	v_mfma_f32_16x16x32_bf16 v[100:103], v[156:159], v[104:107], v[152:155]
	v_mfma_f32_16x16x32_bf16 v[124:127], v[160:163], v[172:175], v[100:103]
	v_mfma_f32_16x16x32_bf16 v[100:103], v[164:167], v[104:107], v[148:151]
	v_mfma_f32_16x16x32_bf16 v[128:131], v[168:171], v[172:175], v[100:103]
	v_mfma_f32_16x16x32_bf16 v[100:103], v[156:159], v[176:179], v[120:123]
	v_mfma_f32_16x16x32_bf16 v[120:123], v[160:163], v[180:183], v[100:103]
	v_mfma_f32_16x16x32_bf16 v[100:103], v[164:167], v[176:179], v[116:119]
	v_mfma_f32_16x16x32_bf16 v[96:99], v[156:159], v[184:187], v[96:99]
	v_mfma_f32_16x16x32_bf16 v[92:95], v[164:167], v[184:187], v[92:95]
	v_mfma_f32_16x16x32_bf16 v[80:83], v[156:159], v[192:195], v[80:83]
	v_mfma_f32_16x16x32_bf16 v[76:79], v[164:167], v[192:195], v[76:79]
	v_mfma_f32_16x16x32_bf16 v[116:119], v[168:171], v[180:183], v[100:103]
	v_mfma_f32_16x16x32_bf16 v[96:99], v[160:163], v[188:191], v[96:99]
	v_mfma_f32_16x16x32_bf16 v[92:95], v[168:171], v[188:191], v[92:95]
	v_mfma_f32_16x16x32_bf16 v[80:83], v[160:163], v[212:215], v[80:83]
	v_mfma_f32_16x16x32_bf16 v[76:79], v[168:171], v[212:215], v[76:79]
	s_setprio 0
	s_barrier
	s_add_i32 s10, s55, s28
	v_lshl_add_u64 v[2:3], s[20:21], 0, v[198:199]
	s_mov_b32 m0, s10
	ds_read_b128 v[140:143], v222
	ds_read_b128 v[144:147], v222 offset:1024
	ds_read_b128 v[148:151], v222 offset:2048
	ds_read_b128 v[152:155], v222 offset:3072
	global_load_lds_dwordx4 v[2:3], off
	v_lshl_add_u64 v[210:211], s[20:21], 0, v[202:203]
	s_add_i32 m0, s10, 0x2000
	s_nop 0
	global_load_lds_dwordx4 v[210:211], off
	s_barrier
	s_waitcnt lgkmcnt(0)
	s_setprio 1
	s_waitcnt lgkmcnt(0)
	v_mfma_f32_16x16x32_bf16 v[100:103], v[140:143], v[104:107], v[136:139]
	v_mfma_f32_16x16x32_bf16 v[104:107], v[148:151], v[104:107], v[132:135]
	v_mfma_f32_16x16x32_bf16 v[112:115], v[140:143], v[176:179], v[112:115]
	v_mfma_f32_16x16x32_bf16 v[108:111], v[148:151], v[176:179], v[108:111]
	v_mfma_f32_16x16x32_bf16 v[88:91], v[140:143], v[184:187], v[88:91]
	v_mfma_f32_16x16x32_bf16 v[84:87], v[148:151], v[184:187], v[84:87]
	v_mfma_f32_16x16x32_bf16 v[72:75], v[140:143], v[192:195], v[72:75]
	v_mfma_f32_16x16x32_bf16 v[68:71], v[148:151], v[192:195], v[68:71]
	v_mfma_f32_16x16x32_bf16 v[100:103], v[144:147], v[172:175], v[100:103]
	v_mfma_f32_16x16x32_bf16 v[104:107], v[152:155], v[172:175], v[104:107]
	v_mfma_f32_16x16x32_bf16 v[112:115], v[144:147], v[180:183], v[112:115]
	v_mfma_f32_16x16x32_bf16 v[108:111], v[152:155], v[180:183], v[108:111]
	v_mfma_f32_16x16x32_bf16 v[88:91], v[144:147], v[188:191], v[88:91]
	v_mfma_f32_16x16x32_bf16 v[84:87], v[152:155], v[188:191], v[84:87]
	v_mfma_f32_16x16x32_bf16 v[72:75], v[144:147], v[212:215], v[72:75]
	v_mfma_f32_16x16x32_bf16 v[68:71], v[152:155], v[212:215], v[68:71]
	s_setprio 0
	s_mov_b32 m0, s29
	v_lshl_add_u64 v[212:213], s[22:23], 0, v[196:197]
	s_barrier
	ds_read_b128 v[188:191], v220 offset:16384
	ds_read_b128 v[192:195], v220 offset:17408
	ds_read_b128 v[180:183], v220 offset:18432
	ds_read_b128 v[184:187], v220 offset:19456
	ds_read_b128 v[172:175], v220 offset:20480
	ds_read_b128 v[176:179], v220 offset:21504
	ds_read_b128 v[132:135], v220 offset:22528
	ds_read_b128 v[136:139], v220 offset:23552
	global_load_lds_dwordx4 v[212:213], off
	v_lshl_add_u64 v[214:215], s[22:23], 0, v[200:201]
	s_mov_b32 m0, s30
	v_cmp_ne_u32_e64 s[10:11], 1, v224
	global_load_lds_dwordx4 v[214:215], off
	s_barrier
	s_waitcnt lgkmcnt(0)
	s_andn2_b64 vcc, exec, s[12:13]
	s_cbranch_vccnz .LBB0_3444
	s_setprio 1
	s_waitcnt lgkmcnt(0)
	v_mfma_f32_16x16x32_bf16 v[64:67], v[156:159], v[188:191], v[64:67]
	v_mfma_f32_16x16x32_bf16 v[60:63], v[164:167], v[188:191], v[60:63]
	v_mfma_f32_16x16x32_bf16 v[48:51], v[156:159], v[180:183], v[48:51]
	v_mfma_f32_16x16x32_bf16 v[44:47], v[164:167], v[180:183], v[44:47]
	v_mfma_f32_16x16x32_bf16 v[32:35], v[156:159], v[172:175], v[32:35]
	v_mfma_f32_16x16x32_bf16 v[28:31], v[164:167], v[172:175], v[28:31]
	v_mfma_f32_16x16x32_bf16 v[16:19], v[156:159], v[132:135], v[16:19]
	v_mfma_f32_16x16x32_bf16 v[12:15], v[164:167], v[132:135], v[12:15]
	v_mfma_f32_16x16x32_bf16 v[64:67], v[160:163], v[192:195], v[64:67]
	v_mfma_f32_16x16x32_bf16 v[60:63], v[168:171], v[192:195], v[60:63]
	v_mfma_f32_16x16x32_bf16 v[48:51], v[160:163], v[184:187], v[48:51]
	v_mfma_f32_16x16x32_bf16 v[44:47], v[168:171], v[184:187], v[44:47]
	v_mfma_f32_16x16x32_bf16 v[32:35], v[160:163], v[176:179], v[32:35]
	v_mfma_f32_16x16x32_bf16 v[28:31], v[168:171], v[176:179], v[28:31]
	v_mfma_f32_16x16x32_bf16 v[16:19], v[160:163], v[136:139], v[16:19]
	v_mfma_f32_16x16x32_bf16 v[12:15], v[168:171], v[136:139], v[12:15]
	s_setprio 0

.LBB0_3977:
	ds_read_b128 v[148:151], v205
	ds_read_b128 v[152:155], v205 offset:1024
	ds_read_b128 v[156:159], v205 offset:2048
	ds_read_b128 v[160:163], v205 offset:3072
	s_add_u32 s10, s30, 0xfff80080
	s_addc_u32 s11, s31, -1
	s_cmp_eq_u32 s21, s59
	s_cselect_b32 s37, s2, s11
	s_cselect_b32 s36, s5, s10
	s_cselect_b32 s35, s17, s58
	s_cselect_b32 s34, s19, s57
	v_lshl_add_u64 v[2:3], s[30:31], 0, v[214:215]
	s_add_i32 m0, s7, 0xc000
	ds_read_b128 v[164:167], v230
	ds_read_b128 v[168:171], v230 offset:1024
	ds_read_b128 v[172:175], v230 offset:2048
	ds_read_b128 v[176:179], v230 offset:3072
	ds_read_b128 v[180:183], v230 offset:4096
	ds_read_b128 v[184:187], v230 offset:5120
	ds_read_b128 v[188:191], v230 offset:6144
	ds_read_b128 v[192:195], v230 offset:7168
	global_load_lds_dwordx4 v[2:3], off
	v_lshl_add_u64 v[2:3], s[30:31], 0, v[216:217]
	s_add_i32 m0, s7, 0xe000
	s_nop 0
	global_load_lds_dwordx4 v[2:3], off
	s_waitcnt lgkmcnt(8)
	s_barrier
	s_waitcnt lgkmcnt(0)
	s_setprio 1
	s_waitcnt lgkmcnt(0)
	v_mfma_f32_16x16x32_bf16 v[84:87], v[148:151], v[164:167], v[84:87]
	v_mfma_f32_16x16x32_bf16 v[76:79], v[156:159], v[164:167], v[76:79]
	v_mfma_f32_16x16x32_bf16 v[64:67], v[148:151], v[172:175], v[64:67]
	v_mfma_f32_16x16x32_bf16 v[60:63], v[156:159], v[172:175], v[60:63]
	v_mfma_f32_16x16x32_bf16 v[48:51], v[148:151], v[180:183], v[48:51]
	v_mfma_f32_16x16x32_bf16 v[44:47], v[156:159], v[180:183], v[44:47]
	v_mfma_f32_16x16x32_bf16 v[32:35], v[148:151], v[188:191], v[32:35]
	v_mfma_f32_16x16x32_bf16 v[24:27], v[156:159], v[188:191], v[24:27]
	v_mfma_f32_16x16x32_bf16 v[84:87], v[152:155], v[168:171], v[84:87]
	v_mfma_f32_16x16x32_bf16 v[76:79], v[160:163], v[168:171], v[76:79]
	v_mfma_f32_16x16x32_bf16 v[64:67], v[152:155], v[176:179], v[64:67]
	v_mfma_f32_16x16x32_bf16 v[60:63], v[160:163], v[176:179], v[60:63]
	v_mfma_f32_16x16x32_bf16 v[48:51], v[152:155], v[184:187], v[48:51]
	v_mfma_f32_16x16x32_bf16 v[44:47], v[160:163], v[184:187], v[44:47]
	v_mfma_f32_16x16x32_bf16 v[32:35], v[152:155], v[192:195], v[32:35]
	v_mfma_f32_16x16x32_bf16 v[24:27], v[160:163], v[192:195], v[24:27]
	s_setprio 0
	s_barrier
	s_add_i32 s10, s55, s40
	v_lshl_add_u64 v[2:3], s[34:35], 0, v[198:199]
	s_mov_b32 m0, s10
	ds_read_b128 v[132:135], v232
	ds_read_b128 v[136:139], v232 offset:1024
	ds_read_b128 v[140:143], v232 offset:2048
	ds_read_b128 v[144:147], v232 offset:3072
	global_load_lds_dwordx4 v[2:3], off
	v_lshl_add_u64 v[220:221], s[34:35], 0, v[202:203]
	s_add_i32 m0, s10, 0x2000
	s_nop 0
	global_load_lds_dwordx4 v[220:221], off
	s_barrier
	s_waitcnt lgkmcnt(0)
	s_setprio 1
	s_waitcnt lgkmcnt(0)
	v_mfma_f32_16x16x32_bf16 v[72:75], v[132:135], v[164:167], v[72:75]
	v_mfma_f32_16x16x32_bf16 v[68:71], v[140:143], v[164:167], v[68:71]
	v_mfma_f32_16x16x32_bf16 v[56:59], v[132:135], v[172:175], v[56:59]
	v_mfma_f32_16x16x32_bf16 v[52:55], v[140:143], v[172:175], v[52:55]
	v_mfma_f32_16x16x32_bf16 v[40:43], v[132:135], v[180:183], v[40:43]
	v_mfma_f32_16x16x32_bf16 v[36:39], v[140:143], v[180:183], v[36:39]
	v_mfma_f32_16x16x32_bf16 v[20:23], v[132:135], v[188:191], v[20:23]
	v_mfma_f32_16x16x32_bf16 v[12:15], v[140:143], v[188:191], v[12:15]
	v_mfma_f32_16x16x32_bf16 v[72:75], v[136:139], v[168:171], v[72:75]
	v_mfma_f32_16x16x32_bf16 v[68:71], v[144:147], v[168:171], v[68:71]
	v_mfma_f32_16x16x32_bf16 v[56:59], v[136:139], v[176:179], v[56:59]
	v_mfma_f32_16x16x32_bf16 v[52:55], v[144:147], v[176:179], v[52:55]
	v_mfma_f32_16x16x32_bf16 v[40:43], v[136:139], v[184:187], v[40:43]
	v_mfma_f32_16x16x32_bf16 v[36:39], v[144:147], v[184:187], v[36:39]
	v_mfma_f32_16x16x32_bf16 v[20:23], v[136:139], v[192:195], v[20:23]
	v_mfma_f32_16x16x32_bf16 v[12:15], v[144:147], v[192:195], v[12:15]
	s_setprio 0
	s_mov_b32 m0, s7
	v_lshl_add_u64 v[222:223], s[36:37], 0, v[196:197]
	s_barrier
	ds_read_b128 v[188:191], v230 offset:16384
	ds_read_b128 v[192:195], v230 offset:17408
	ds_read_b128 v[180:183], v230 offset:18432
	ds_read_b128 v[184:187], v230 offset:19456
	ds_read_b128 v[172:175], v230 offset:20480
	ds_read_b128 v[176:179], v230 offset:21504
	ds_read_b128 v[164:167], v230 offset:22528
	ds_read_b128 v[168:171], v230 offset:23552
	global_load_lds_dwordx4 v[222:223], off
	v_lshl_add_u64 v[224:225], s[36:37], 0, v[200:201]
	s_mov_b32 m0, s41
	v_cmp_ne_u32_e64 s[10:11], 1, v233
	global_load_lds_dwordx4 v[224:225], off
	s_barrier
	s_waitcnt lgkmcnt(0)
	s_andn2_b64 vcc, exec, s[28:29]
	s_cbranch_vccnz .LBB0_3979
	s_setprio 1
	s_waitcnt lgkmcnt(0)
	v_mfma_f32_16x16x32_bf16 v[128:131], v[148:151], v[188:191], v[128:131]
	v_mfma_f32_16x16x32_bf16 v[124:127], v[156:159], v[188:191], v[124:127]
	v_mfma_f32_16x16x32_bf16 v[112:115], v[148:151], v[180:183], v[112:115]
	v_mfma_f32_16x16x32_bf16 v[108:111], v[156:159], v[180:183], v[108:111]
	v_mfma_f32_16x16x32_bf16 v[96:99], v[148:151], v[172:175], v[96:99]
	v_mfma_f32_16x16x32_bf16 v[92:95], v[156:159], v[172:175], v[92:95]
	v_mfma_f32_16x16x32_bf16 v[28:31], v[148:151], v[164:167], v[28:31]
	v_mfma_f32_16x16x32_bf16 v[16:19], v[156:159], v[164:167], v[16:19]
	v_mfma_f32_16x16x32_bf16 v[128:131], v[152:155], v[192:195], v[128:131]
	v_mfma_f32_16x16x32_bf16 v[124:127], v[160:163], v[192:195], v[124:127]
	v_mfma_f32_16x16x32_bf16 v[112:115], v[152:155], v[184:187], v[112:115]
	v_mfma_f32_16x16x32_bf16 v[108:111], v[160:163], v[184:187], v[108:111]
	v_mfma_f32_16x16x32_bf16 v[96:99], v[152:155], v[176:179], v[96:99]
	v_mfma_f32_16x16x32_bf16 v[92:95], v[160:163], v[176:179], v[92:95]
	v_mfma_f32_16x16x32_bf16 v[28:31], v[152:155], v[168:171], v[28:31]
	v_mfma_f32_16x16x32_bf16 v[16:19], v[160:163], v[168:171], v[16:19]
	s_setprio 0

.LBB0_3981:
	s_add_i32 s60, 0, 0x18000
	v_add_u32_e32 v1, s60, v226
	s_barrier
	ds_read_b128 v[148:151], v1
	ds_read_b128 v[152:155], v1 offset:1024
	ds_read_b128 v[156:159], v1 offset:2048
	ds_read_b128 v[160:163], v1 offset:3072
	s_add_u32 s36, s36, 0x80000
	s_addc_u32 s37, s37, 0
	s_mov_b32 m0, s46
	v_lshl_add_u64 v[132:133], s[36:37], 0, v[196:197]
	ds_read_b128 v[164:167], v230 offset:32768
	ds_read_b128 v[168:171], v230 offset:33792
	ds_read_b128 v[172:175], v230 offset:34816
	ds_read_b128 v[176:179], v230 offset:35840
	ds_read_b128 v[180:183], v230 offset:36864
	ds_read_b128 v[184:187], v230 offset:37888
	ds_read_b128 v[188:191], v230 offset:38912
	ds_read_b128 v[192:195], v230 offset:39936
	global_load_lds_dwordx4 v[132:133], off
	v_lshl_add_u64 v[132:133], s[36:37], 0, v[200:201]
	s_mov_b32 m0, s47
	s_nop 0
	global_load_lds_dwordx4 v[132:133], off
	s_waitcnt lgkmcnt(8)
	s_barrier
	s_waitcnt lgkmcnt(0)
	s_setprio 1
	s_waitcnt lgkmcnt(0)
	v_mfma_f32_16x16x32_bf16 v[84:87], v[148:151], v[164:167], v[84:87]
	v_mfma_f32_16x16x32_bf16 v[76:79], v[156:159], v[164:167], v[76:79]
	v_mfma_f32_16x16x32_bf16 v[64:67], v[148:151], v[172:175], v[64:67]
	v_mfma_f32_16x16x32_bf16 v[60:63], v[156:159], v[172:175], v[60:63]
	v_mfma_f32_16x16x32_bf16 v[48:51], v[148:151], v[180:183], v[48:51]
	v_mfma_f32_16x16x32_bf16 v[44:47], v[156:159], v[180:183], v[44:47]
	v_mfma_f32_16x16x32_bf16 v[32:35], v[148:151], v[188:191], v[32:35]
	v_mfma_f32_16x16x32_bf16 v[24:27], v[156:159], v[188:191], v[24:27]
	v_mfma_f32_16x16x32_bf16 v[84:87], v[152:155], v[168:171], v[84:87]
	v_mfma_f32_16x16x32_bf16 v[76:79], v[160:163], v[168:171], v[76:79]
	v_mfma_f32_16x16x32_bf16 v[64:67], v[152:155], v[176:179], v[64:67]
	v_mfma_f32_16x16x32_bf16 v[60:63], v[160:163], v[176:179], v[60:63]
	v_mfma_f32_16x16x32_bf16 v[48:51], v[152:155], v[184:187], v[48:51]
	v_mfma_f32_16x16x32_bf16 v[44:47], v[160:163], v[184:187], v[44:47]
	v_mfma_f32_16x16x32_bf16 v[32:35], v[152:155], v[192:195], v[32:35]
	v_mfma_f32_16x16x32_bf16 v[24:27], v[160:163], v[192:195], v[24:27]
	s_setprio 0
	s_barrier
	s_add_i32 s36, s60, s40
	v_add_u32_e32 v1, 0x1c000, v231
	v_lshl_add_u64 v[2:3], v[2:3], 0, s[14:15]
	s_mov_b32 m0, s36
	ds_read_b128 v[132:135], v1
	ds_read_b128 v[136:139], v1 offset:1024
	ds_read_b128 v[140:143], v1 offset:2048
	ds_read_b128 v[144:147], v1 offset:3072
	global_load_lds_dwordx4 v[2:3], off
	v_lshl_add_u64 v[2:3], v[220:221], 0, s[14:15]
	s_add_i32 m0, s36, 0x2000
	s_nop 0
	global_load_lds_dwordx4 v[2:3], off
	s_barrier
	s_waitcnt lgkmcnt(0)
	s_setprio 1
	s_waitcnt lgkmcnt(0)
	v_mfma_f32_16x16x32_bf16 v[72:75], v[132:135], v[164:167], v[72:75]
	v_mfma_f32_16x16x32_bf16 v[68:71], v[140:143], v[164:167], v[68:71]
	v_mfma_f32_16x16x32_bf16 v[56:59], v[132:135], v[172:175], v[56:59]
	v_mfma_f32_16x16x32_bf16 v[52:55], v[140:143], v[172:175], v[52:55]
	v_mfma_f32_16x16x32_bf16 v[40:43], v[132:135], v[180:183], v[40:43]
	v_mfma_f32_16x16x32_bf16 v[36:39], v[140:143], v[180:183], v[36:39]
	v_mfma_f32_16x16x32_bf16 v[20:23], v[132:135], v[188:191], v[20:23]
	v_mfma_f32_16x16x32_bf16 v[12:15], v[140:143], v[188:191], v[12:15]
	v_mfma_f32_16x16x32_bf16 v[72:75], v[136:139], v[168:171], v[72:75]
	v_mfma_f32_16x16x32_bf16 v[68:71], v[144:147], v[168:171], v[68:71]
	v_mfma_f32_16x16x32_bf16 v[56:59], v[136:139], v[176:179], v[56:59]
	v_mfma_f32_16x16x32_bf16 v[52:55], v[144:147], v[176:179], v[52:55]
	v_mfma_f32_16x16x32_bf16 v[40:43], v[136:139], v[184:187], v[40:43]
	v_mfma_f32_16x16x32_bf16 v[36:39], v[144:147], v[184:187], v[36:39]
	v_mfma_f32_16x16x32_bf16 v[20:23], v[136:139], v[192:195], v[20:23]
	v_mfma_f32_16x16x32_bf16 v[12:15], v[144:147], v[192:195], v[12:15]
	s_setprio 0
	s_mov_b32 m0, s49
	v_lshl_add_u64 v[2:3], v[222:223], 0, s[14:15]
	s_barrier
	ds_read_b128 v[188:191], v230 offset:49152
	ds_read_b128 v[192:195], v230 offset:50176
	ds_read_b128 v[180:183], v230 offset:51200
	ds_read_b128 v[184:187], v230 offset:52224
	ds_read_b128 v[172:175], v230 offset:53248
	ds_read_b128 v[176:179], v230 offset:54272
	ds_read_b128 v[164:167], v230 offset:55296
	ds_read_b128 v[168:171], v230 offset:56320
	global_load_lds_dwordx4 v[2:3], off
	v_lshl_add_u64 v[2:3], v[224:225], 0, s[14:15]
	s_mov_b32 m0, s50
	s_and_b64 vcc, exec, s[10:11]
	global_load_lds_dwordx4 v[2:3], off
	s_barrier
	s_waitcnt lgkmcnt(0)
	s_cbranch_vccnz .LBB0_3983
	s_setprio 1
	s_waitcnt lgkmcnt(0)
	v_mfma_f32_16x16x32_bf16 v[128:131], v[148:151], v[188:191], v[128:131]
	v_mfma_f32_16x16x32_bf16 v[124:127], v[156:159], v[188:191], v[124:127]
	v_mfma_f32_16x16x32_bf16 v[112:115], v[148:151], v[180:183], v[112:115]
	v_mfma_f32_16x16x32_bf16 v[108:111], v[156:159], v[180:183], v[108:111]
	v_mfma_f32_16x16x32_bf16 v[96:99], v[148:151], v[172:175], v[96:99]
	v_mfma_f32_16x16x32_bf16 v[92:95], v[156:159], v[172:175], v[92:95]
	v_mfma_f32_16x16x32_bf16 v[28:31], v[148:151], v[164:167], v[28:31]
	v_mfma_f32_16x16x32_bf16 v[16:19], v[156:159], v[164:167], v[16:19]
	v_mfma_f32_16x16x32_bf16 v[128:131], v[152:155], v[192:195], v[128:131]
	v_mfma_f32_16x16x32_bf16 v[124:127], v[160:163], v[192:195], v[124:127]
	v_mfma_f32_16x16x32_bf16 v[112:115], v[152:155], v[184:187], v[112:115]
	v_mfma_f32_16x16x32_bf16 v[108:111], v[160:163], v[184:187], v[108:111]
	v_mfma_f32_16x16x32_bf16 v[96:99], v[152:155], v[176:179], v[96:99]
	v_mfma_f32_16x16x32_bf16 v[92:95], v[160:163], v[176:179], v[92:95]
	v_mfma_f32_16x16x32_bf16 v[28:31], v[152:155], v[168:171], v[28:31]
	v_mfma_f32_16x16x32_bf16 v[16:19], v[160:163], v[168:171], v[16:19]
	s_setprio 0

.LBB0_4152:
	ds_read_b128 v[148:151], v222
	ds_read_b128 v[152:155], v222 offset:1024
	ds_read_b128 v[156:159], v222 offset:2048
	ds_read_b128 v[160:163], v222 offset:3072
	s_add_u32 s8, s26, 0xfffc0080
	s_addc_u32 s9, s27, -1
	s_cmp_eq_u32 s52, s55
	s_cselect_b32 s31, s2, s9
	s_cselect_b32 s30, s13, s8
	s_cselect_b32 s29, s15, s54
	s_cselect_b32 s28, s21, s53
	v_lshl_add_u64 v[2:3], s[26:27], 0, v[204:205]
	s_add_i32 m0, s36, 0xc000
	ds_read_b128 v[164:167], v223
	ds_read_b128 v[168:171], v223 offset:1024
	ds_read_b128 v[172:175], v223 offset:2048
	ds_read_b128 v[176:179], v223 offset:3072
	ds_read_b128 v[180:183], v223 offset:4096
	ds_read_b128 v[184:187], v223 offset:5120
	ds_read_b128 v[188:191], v223 offset:6144
	ds_read_b128 v[192:195], v223 offset:7168
	global_load_lds_dwordx4 v[2:3], off
	v_lshl_add_u64 v[2:3], s[26:27], 0, v[206:207]
	s_add_i32 m0, s36, 0xe000
	s_nop 0
	global_load_lds_dwordx4 v[2:3], off
	s_waitcnt lgkmcnt(8)
	s_barrier
	s_waitcnt lgkmcnt(0)
	s_setprio 1
	s_waitcnt lgkmcnt(0)
	v_mfma_f32_16x16x32_bf16 v[124:127], v[148:151], v[164:167], v[124:127]
	v_mfma_f32_16x16x32_bf16 v[116:119], v[156:159], v[164:167], v[116:119]
	v_mfma_f32_16x16x32_bf16 v[108:111], v[148:151], v[172:175], v[108:111]
	v_mfma_f32_16x16x32_bf16 v[100:103], v[156:159], v[172:175], v[100:103]
	v_mfma_f32_16x16x32_bf16 v[92:95], v[148:151], v[180:183], v[92:95]
	v_mfma_f32_16x16x32_bf16 v[84:87], v[156:159], v[180:183], v[84:87]
	v_mfma_f32_16x16x32_bf16 v[76:79], v[148:151], v[188:191], v[76:79]
	v_mfma_f32_16x16x32_bf16 v[72:75], v[156:159], v[188:191], v[72:75]
	v_mfma_f32_16x16x32_bf16 v[124:127], v[152:155], v[168:171], v[124:127]
	v_mfma_f32_16x16x32_bf16 v[116:119], v[160:163], v[168:171], v[116:119]
	v_mfma_f32_16x16x32_bf16 v[108:111], v[152:155], v[176:179], v[108:111]
	v_mfma_f32_16x16x32_bf16 v[100:103], v[160:163], v[176:179], v[100:103]
	v_mfma_f32_16x16x32_bf16 v[92:95], v[152:155], v[184:187], v[92:95]
	v_mfma_f32_16x16x32_bf16 v[84:87], v[160:163], v[184:187], v[84:87]
	v_mfma_f32_16x16x32_bf16 v[76:79], v[152:155], v[192:195], v[76:79]
	v_mfma_f32_16x16x32_bf16 v[72:75], v[160:163], v[192:195], v[72:75]
	s_setprio 0
	s_barrier
	s_add_i32 s8, s49, s23
	v_lshl_add_u64 v[2:3], s[28:29], 0, v[198:199]
	s_mov_b32 m0, s8
	ds_read_b128 v[132:135], v225
	ds_read_b128 v[136:139], v225 offset:1024
	ds_read_b128 v[140:143], v225 offset:2048
	ds_read_b128 v[144:147], v225 offset:3072
	global_load_lds_dwordx4 v[2:3], off
	v_lshl_add_u64 v[212:213], s[28:29], 0, v[202:203]
	s_add_i32 m0, s8, 0x2000
	s_nop 0
	global_load_lds_dwordx4 v[212:213], off
	s_barrier
	s_waitcnt lgkmcnt(0)
	s_setprio 1
	s_waitcnt lgkmcnt(0)
	v_mfma_f32_16x16x32_bf16 v[128:131], v[132:135], v[164:167], v[128:131]
	v_mfma_f32_16x16x32_bf16 v[120:123], v[140:143], v[164:167], v[120:123]
	v_mfma_f32_16x16x32_bf16 v[112:115], v[132:135], v[172:175], v[112:115]
	v_mfma_f32_16x16x32_bf16 v[104:107], v[140:143], v[172:175], v[104:107]
	v_mfma_f32_16x16x32_bf16 v[96:99], v[132:135], v[180:183], v[96:99]
	v_mfma_f32_16x16x32_bf16 v[88:91], v[140:143], v[180:183], v[88:91]
	v_mfma_f32_16x16x32_bf16 v[80:83], v[132:135], v[188:191], v[80:83]
	v_mfma_f32_16x16x32_bf16 v[68:71], v[140:143], v[188:191], v[68:71]
	v_mfma_f32_16x16x32_bf16 v[128:131], v[136:139], v[168:171], v[128:131]
	v_mfma_f32_16x16x32_bf16 v[120:123], v[144:147], v[168:171], v[120:123]
	v_mfma_f32_16x16x32_bf16 v[112:115], v[136:139], v[176:179], v[112:115]
	v_mfma_f32_16x16x32_bf16 v[104:107], v[144:147], v[176:179], v[104:107]
	v_mfma_f32_16x16x32_bf16 v[96:99], v[136:139], v[184:187], v[96:99]
	v_mfma_f32_16x16x32_bf16 v[88:91], v[144:147], v[184:187], v[88:91]
	v_mfma_f32_16x16x32_bf16 v[80:83], v[136:139], v[192:195], v[80:83]
	v_mfma_f32_16x16x32_bf16 v[68:71], v[144:147], v[192:195], v[68:71]
	s_setprio 0
	s_mov_b32 m0, s36
	v_lshl_add_u64 v[214:215], s[30:31], 0, v[196:197]
	s_barrier
	ds_read_b128 v[188:191], v223 offset:16384
	ds_read_b128 v[192:195], v223 offset:17408
	ds_read_b128 v[180:183], v223 offset:18432
	ds_read_b128 v[184:187], v223 offset:19456
	ds_read_b128 v[172:175], v223 offset:20480
	ds_read_b128 v[176:179], v223 offset:21504
	ds_read_b128 v[164:167], v223 offset:22528
	ds_read_b128 v[168:171], v223 offset:23552
	global_load_lds_dwordx4 v[214:215], off
	v_lshl_add_u64 v[216:217], s[30:31], 0, v[200:201]
	s_mov_b32 m0, s37
	v_cmp_ne_u32_e64 s[8:9], 1, v234
	global_load_lds_dwordx4 v[216:217], off
	s_barrier
	s_waitcnt lgkmcnt(0)
	s_andn2_b64 vcc, exec, s[24:25]
	s_cbranch_vccnz .LBB0_4154
	s_setprio 1
	s_waitcnt lgkmcnt(0)
	v_mfma_f32_16x16x32_bf16 v[60:63], v[148:151], v[188:191], v[60:63]
	v_mfma_f32_16x16x32_bf16 v[52:55], v[156:159], v[188:191], v[52:55]
	v_mfma_f32_16x16x32_bf16 v[44:47], v[148:151], v[180:183], v[44:47]
	v_mfma_f32_16x16x32_bf16 v[36:39], v[156:159], v[180:183], v[36:39]
	v_mfma_f32_16x16x32_bf16 v[28:31], v[148:151], v[172:175], v[28:31]
	v_mfma_f32_16x16x32_bf16 v[20:23], v[156:159], v[172:175], v[20:23]
	v_mfma_f32_16x16x32_bf16 v[12:15], v[148:151], v[164:167], v[12:15]
	v_mfma_f32_16x16x32_bf16 v[4:7], v[156:159], v[164:167], v[4:7]
	v_mfma_f32_16x16x32_bf16 v[60:63], v[152:155], v[192:195], v[60:63]
	v_mfma_f32_16x16x32_bf16 v[52:55], v[160:163], v[192:195], v[52:55]
	v_mfma_f32_16x16x32_bf16 v[44:47], v[152:155], v[184:187], v[44:47]
	v_mfma_f32_16x16x32_bf16 v[36:39], v[160:163], v[184:187], v[36:39]
	v_mfma_f32_16x16x32_bf16 v[28:31], v[152:155], v[176:179], v[28:31]
	v_mfma_f32_16x16x32_bf16 v[20:23], v[160:163], v[176:179], v[20:23]
	v_mfma_f32_16x16x32_bf16 v[12:15], v[152:155], v[168:171], v[12:15]
	v_mfma_f32_16x16x32_bf16 v[4:7], v[160:163], v[168:171], v[4:7]
	s_setprio 0

.LBB0_4156:
	s_add_i32 s56, 0, 0x18000
	v_add_u32_e32 v1, s56, v220
	s_barrier
	ds_read_b128 v[148:151], v1
	ds_read_b128 v[152:155], v1 offset:1024
	ds_read_b128 v[156:159], v1 offset:2048
	ds_read_b128 v[160:163], v1 offset:3072
	s_add_u32 s30, s30, 0x40000
	s_addc_u32 s31, s31, 0
	s_mov_b32 m0, s40
	v_lshl_add_u64 v[132:133], s[30:31], 0, v[196:197]
	ds_read_b128 v[164:167], v223 offset:32768
	ds_read_b128 v[168:171], v223 offset:33792
	ds_read_b128 v[172:175], v223 offset:34816
	ds_read_b128 v[176:179], v223 offset:35840
	ds_read_b128 v[180:183], v223 offset:36864
	ds_read_b128 v[184:187], v223 offset:37888
	ds_read_b128 v[188:191], v223 offset:38912
	ds_read_b128 v[192:195], v223 offset:39936
	global_load_lds_dwordx4 v[132:133], off
	v_lshl_add_u64 v[132:133], s[30:31], 0, v[200:201]
	s_mov_b32 m0, s41
	s_nop 0
	global_load_lds_dwordx4 v[132:133], off
	s_waitcnt lgkmcnt(8)
	s_barrier
	s_waitcnt lgkmcnt(0)
	s_setprio 1
	s_waitcnt lgkmcnt(0)
	v_mfma_f32_16x16x32_bf16 v[124:127], v[148:151], v[164:167], v[124:127]
	v_mfma_f32_16x16x32_bf16 v[116:119], v[156:159], v[164:167], v[116:119]
	v_mfma_f32_16x16x32_bf16 v[108:111], v[148:151], v[172:175], v[108:111]
	v_mfma_f32_16x16x32_bf16 v[100:103], v[156:159], v[172:175], v[100:103]
	v_mfma_f32_16x16x32_bf16 v[92:95], v[148:151], v[180:183], v[92:95]
	v_mfma_f32_16x16x32_bf16 v[84:87], v[156:159], v[180:183], v[84:87]
	v_mfma_f32_16x16x32_bf16 v[76:79], v[148:151], v[188:191], v[76:79]
	v_mfma_f32_16x16x32_bf16 v[72:75], v[156:159], v[188:191], v[72:75]
	v_mfma_f32_16x16x32_bf16 v[124:127], v[152:155], v[168:171], v[124:127]
	v_mfma_f32_16x16x32_bf16 v[116:119], v[160:163], v[168:171], v[116:119]
	v_mfma_f32_16x16x32_bf16 v[108:111], v[152:155], v[176:179], v[108:111]
	v_mfma_f32_16x16x32_bf16 v[100:103], v[160:163], v[176:179], v[100:103]
	v_mfma_f32_16x16x32_bf16 v[92:95], v[152:155], v[184:187], v[92:95]
	v_mfma_f32_16x16x32_bf16 v[84:87], v[160:163], v[184:187], v[84:87]
	v_mfma_f32_16x16x32_bf16 v[76:79], v[152:155], v[192:195], v[76:79]
	v_mfma_f32_16x16x32_bf16 v[72:75], v[160:163], v[192:195], v[72:75]
	s_setprio 0
	s_barrier
	s_add_i32 s30, s56, s23
	v_add_u32_e32 v1, 0x1c000, v224
	v_lshl_add_u64 v[2:3], v[2:3], 0, s[10:11]
	s_mov_b32 m0, s30
	ds_read_b128 v[132:135], v1
	ds_read_b128 v[136:139], v1 offset:1024
	ds_read_b128 v[140:143], v1 offset:2048
	ds_read_b128 v[144:147], v1 offset:3072
	global_load_lds_dwordx4 v[2:3], off
	v_lshl_add_u64 v[2:3], v[212:213], 0, s[10:11]
	s_add_i32 m0, s30, 0x2000
	s_nop 0
	global_load_lds_dwordx4 v[2:3], off
	s_barrier
	s_waitcnt lgkmcnt(0)
	s_setprio 1
	s_waitcnt lgkmcnt(0)
	v_mfma_f32_16x16x32_bf16 v[128:131], v[132:135], v[164:167], v[128:131]
	v_mfma_f32_16x16x32_bf16 v[120:123], v[140:143], v[164:167], v[120:123]
	v_mfma_f32_16x16x32_bf16 v[112:115], v[132:135], v[172:175], v[112:115]
	v_mfma_f32_16x16x32_bf16 v[104:107], v[140:143], v[172:175], v[104:107]
	v_mfma_f32_16x16x32_bf16 v[96:99], v[132:135], v[180:183], v[96:99]
	v_mfma_f32_16x16x32_bf16 v[88:91], v[140:143], v[180:183], v[88:91]
	v_mfma_f32_16x16x32_bf16 v[80:83], v[132:135], v[188:191], v[80:83]
	v_mfma_f32_16x16x32_bf16 v[68:71], v[140:143], v[188:191], v[68:71]
	v_mfma_f32_16x16x32_bf16 v[128:131], v[136:139], v[168:171], v[128:131]
	v_mfma_f32_16x16x32_bf16 v[120:123], v[144:147], v[168:171], v[120:123]
	v_mfma_f32_16x16x32_bf16 v[112:115], v[136:139], v[176:179], v[112:115]
	v_mfma_f32_16x16x32_bf16 v[104:107], v[144:147], v[176:179], v[104:107]
	v_mfma_f32_16x16x32_bf16 v[96:99], v[136:139], v[184:187], v[96:99]
	v_mfma_f32_16x16x32_bf16 v[88:91], v[144:147], v[184:187], v[88:91]
	v_mfma_f32_16x16x32_bf16 v[80:83], v[136:139], v[192:195], v[80:83]
	v_mfma_f32_16x16x32_bf16 v[68:71], v[144:147], v[192:195], v[68:71]
	s_setprio 0
	s_mov_b32 m0, s43
	v_lshl_add_u64 v[2:3], v[214:215], 0, s[10:11]
	s_barrier
	ds_read_b128 v[188:191], v223 offset:49152
	ds_read_b128 v[192:195], v223 offset:50176
	ds_read_b128 v[180:183], v223 offset:51200
	ds_read_b128 v[184:187], v223 offset:52224
	ds_read_b128 v[172:175], v223 offset:53248
	ds_read_b128 v[176:179], v223 offset:54272
	ds_read_b128 v[164:167], v223 offset:55296
	ds_read_b128 v[168:171], v223 offset:56320
	global_load_lds_dwordx4 v[2:3], off
	v_lshl_add_u64 v[2:3], v[216:217], 0, s[10:11]
	s_mov_b32 m0, s44
	s_and_b64 vcc, exec, s[8:9]
	global_load_lds_dwordx4 v[2:3], off
	s_barrier
	s_waitcnt lgkmcnt(0)
	s_cbranch_vccnz .LBB0_4158
	s_setprio 1
	s_waitcnt lgkmcnt(0)
	v_mfma_f32_16x16x32_bf16 v[60:63], v[148:151], v[188:191], v[60:63]
	v_mfma_f32_16x16x32_bf16 v[52:55], v[156:159], v[188:191], v[52:55]
	v_mfma_f32_16x16x32_bf16 v[44:47], v[148:151], v[180:183], v[44:47]
	v_mfma_f32_16x16x32_bf16 v[36:39], v[156:159], v[180:183], v[36:39]
	v_mfma_f32_16x16x32_bf16 v[28:31], v[148:151], v[172:175], v[28:31]
	v_mfma_f32_16x16x32_bf16 v[20:23], v[156:159], v[172:175], v[20:23]
	v_mfma_f32_16x16x32_bf16 v[12:15], v[148:151], v[164:167], v[12:15]
	v_mfma_f32_16x16x32_bf16 v[2:5], v[156:159], v[164:167], v[4:7]
	v_mfma_f32_16x16x32_bf16 v[60:63], v[152:155], v[192:195], v[60:63]
	v_mfma_f32_16x16x32_bf16 v[52:55], v[160:163], v[192:195], v[52:55]
	v_mfma_f32_16x16x32_bf16 v[44:47], v[152:155], v[184:187], v[44:47]
	v_mfma_f32_16x16x32_bf16 v[36:39], v[160:163], v[184:187], v[36:39]
	v_mfma_f32_16x16x32_bf16 v[28:31], v[152:155], v[176:179], v[28:31]
	v_mfma_f32_16x16x32_bf16 v[20:23], v[160:163], v[176:179], v[20:23]
	v_mfma_f32_16x16x32_bf16 v[12:15], v[152:155], v[168:171], v[12:15]
	v_mfma_f32_16x16x32_bf16 v[4:7], v[160:163], v[168:171], v[2:5]
	s_setprio 0

.LBB0_4258:
	ds_read_b128 v[148:151], v205
	ds_read_b128 v[152:155], v205 offset:1024
	ds_read_b128 v[156:159], v205 offset:2048
	ds_read_b128 v[160:163], v205 offset:3072
	s_mov_b64 s[10:11], s[22:23]
	s_add_u32 s22, s10, 0x100
	s_addc_u32 s23, s11, 0
	s_cmp_eq_u32 s5, s53
	s_cselect_b32 s29, s19, s23
	s_cselect_b32 s28, s18, s22
	s_cselect_b32 s27, s21, s17
	s_cselect_b32 s26, s20, s12
	v_lshl_add_u64 v[2:3], s[10:11], 0, v[214:215]
	s_add_i32 m0, s36, 0xc000
	ds_read_b128 v[164:167], v230
	ds_read_b128 v[168:171], v230 offset:1024
	ds_read_b128 v[172:175], v230 offset:2048
	ds_read_b128 v[176:179], v230 offset:3072
	ds_read_b128 v[180:183], v230 offset:4096
	ds_read_b128 v[184:187], v230 offset:5120
	ds_read_b128 v[188:191], v230 offset:6144
	ds_read_b128 v[192:195], v230 offset:7168
	global_load_lds_dwordx4 v[2:3], off
	v_lshl_add_u64 v[2:3], s[10:11], 0, v[216:217]
	s_add_i32 m0, s36, 0xe000
	s_nop 0
	global_load_lds_dwordx4 v[2:3], off
	s_waitcnt lgkmcnt(8)
	s_barrier
	s_waitcnt lgkmcnt(0)
	s_setprio 1
	s_waitcnt lgkmcnt(0)
	v_mfma_f32_16x16x32_bf16 v[84:87], v[148:151], v[164:167], v[84:87]
	v_mfma_f32_16x16x32_bf16 v[76:79], v[156:159], v[164:167], v[76:79]
	v_mfma_f32_16x16x32_bf16 v[64:67], v[148:151], v[172:175], v[64:67]
	v_mfma_f32_16x16x32_bf16 v[60:63], v[156:159], v[172:175], v[60:63]
	v_mfma_f32_16x16x32_bf16 v[48:51], v[148:151], v[180:183], v[48:51]
	v_mfma_f32_16x16x32_bf16 v[44:47], v[156:159], v[180:183], v[44:47]
	v_mfma_f32_16x16x32_bf16 v[32:35], v[148:151], v[188:191], v[32:35]
	v_mfma_f32_16x16x32_bf16 v[24:27], v[156:159], v[188:191], v[24:27]
	v_mfma_f32_16x16x32_bf16 v[84:87], v[152:155], v[168:171], v[84:87]
	v_mfma_f32_16x16x32_bf16 v[76:79], v[160:163], v[168:171], v[76:79]
	v_mfma_f32_16x16x32_bf16 v[64:67], v[152:155], v[176:179], v[64:67]
	v_mfma_f32_16x16x32_bf16 v[60:63], v[160:163], v[176:179], v[60:63]
	v_mfma_f32_16x16x32_bf16 v[48:51], v[152:155], v[184:187], v[48:51]
	v_mfma_f32_16x16x32_bf16 v[44:47], v[160:163], v[184:187], v[44:47]
	v_mfma_f32_16x16x32_bf16 v[32:35], v[152:155], v[192:195], v[32:35]
	v_mfma_f32_16x16x32_bf16 v[24:27], v[160:163], v[192:195], v[24:27]
	s_setprio 0
	s_barrier
	s_add_i32 s10, s49, s34
	v_lshl_add_u64 v[2:3], s[26:27], 0, v[198:199]
	s_mov_b32 m0, s10
	ds_read_b128 v[132:135], v232
	ds_read_b128 v[136:139], v232 offset:1024
	ds_read_b128 v[140:143], v232 offset:2048
	ds_read_b128 v[144:147], v232 offset:3072
	global_load_lds_dwordx4 v[2:3], off
	v_lshl_add_u64 v[220:221], s[26:27], 0, v[202:203]
	s_add_i32 m0, s10, 0x2000
	s_nop 0
	global_load_lds_dwordx4 v[220:221], off
	s_barrier
	s_waitcnt lgkmcnt(0)
	s_setprio 1
	s_waitcnt lgkmcnt(0)
	v_mfma_f32_16x16x32_bf16 v[72:75], v[132:135], v[164:167], v[72:75]
	v_mfma_f32_16x16x32_bf16 v[68:71], v[140:143], v[164:167], v[68:71]
	v_mfma_f32_16x16x32_bf16 v[56:59], v[132:135], v[172:175], v[56:59]
	v_mfma_f32_16x16x32_bf16 v[52:55], v[140:143], v[172:175], v[52:55]
	v_mfma_f32_16x16x32_bf16 v[40:43], v[132:135], v[180:183], v[40:43]
	v_mfma_f32_16x16x32_bf16 v[36:39], v[140:143], v[180:183], v[36:39]
	v_mfma_f32_16x16x32_bf16 v[20:23], v[132:135], v[188:191], v[20:23]
	v_mfma_f32_16x16x32_bf16 v[12:15], v[140:143], v[188:191], v[12:15]
	v_mfma_f32_16x16x32_bf16 v[72:75], v[136:139], v[168:171], v[72:75]
	v_mfma_f32_16x16x32_bf16 v[68:71], v[144:147], v[168:171], v[68:71]
	v_mfma_f32_16x16x32_bf16 v[56:59], v[136:139], v[176:179], v[56:59]
	v_mfma_f32_16x16x32_bf16 v[52:55], v[144:147], v[176:179], v[52:55]
	v_mfma_f32_16x16x32_bf16 v[40:43], v[136:139], v[184:187], v[40:43]
	v_mfma_f32_16x16x32_bf16 v[36:39], v[144:147], v[184:187], v[36:39]
	v_mfma_f32_16x16x32_bf16 v[20:23], v[136:139], v[192:195], v[20:23]
	v_mfma_f32_16x16x32_bf16 v[12:15], v[144:147], v[192:195], v[12:15]
	s_setprio 0
	s_mov_b32 m0, s36
	v_lshl_add_u64 v[222:223], s[28:29], 0, v[196:197]
	s_barrier
	ds_read_b128 v[188:191], v230 offset:16384
	ds_read_b128 v[192:195], v230 offset:17408
	ds_read_b128 v[180:183], v230 offset:18432
	ds_read_b128 v[184:187], v230 offset:19456
	ds_read_b128 v[172:175], v230 offset:20480
	ds_read_b128 v[176:179], v230 offset:21504
	ds_read_b128 v[164:167], v230 offset:22528
	ds_read_b128 v[168:171], v230 offset:23552
	global_load_lds_dwordx4 v[222:223], off
	v_lshl_add_u64 v[224:225], s[28:29], 0, v[200:201]
	s_mov_b32 m0, s37
	v_cmp_ne_u32_e64 s[10:11], 1, v233
	global_load_lds_dwordx4 v[224:225], off
	s_barrier
	s_waitcnt lgkmcnt(0)
	s_andn2_b64 vcc, exec, s[24:25]
	s_cbranch_vccnz .LBB0_4260
	s_setprio 1
	s_waitcnt lgkmcnt(0)
	v_mfma_f32_16x16x32_bf16 v[128:131], v[148:151], v[188:191], v[128:131]
	v_mfma_f32_16x16x32_bf16 v[124:127], v[156:159], v[188:191], v[124:127]
	v_mfma_f32_16x16x32_bf16 v[112:115], v[148:151], v[180:183], v[112:115]
	v_mfma_f32_16x16x32_bf16 v[108:111], v[156:159], v[180:183], v[108:111]
	v_mfma_f32_16x16x32_bf16 v[96:99], v[148:151], v[172:175], v[96:99]
	v_mfma_f32_16x16x32_bf16 v[92:95], v[156:159], v[172:175], v[92:95]
	v_mfma_f32_16x16x32_bf16 v[28:31], v[148:151], v[164:167], v[28:31]
	v_mfma_f32_16x16x32_bf16 v[16:19], v[156:159], v[164:167], v[16:19]
	v_mfma_f32_16x16x32_bf16 v[128:131], v[152:155], v[192:195], v[128:131]
	v_mfma_f32_16x16x32_bf16 v[124:127], v[160:163], v[192:195], v[124:127]
	v_mfma_f32_16x16x32_bf16 v[112:115], v[152:155], v[184:187], v[112:115]
	v_mfma_f32_16x16x32_bf16 v[108:111], v[160:163], v[184:187], v[108:111]
	v_mfma_f32_16x16x32_bf16 v[96:99], v[152:155], v[176:179], v[96:99]
	v_mfma_f32_16x16x32_bf16 v[92:95], v[160:163], v[176:179], v[92:95]
	v_mfma_f32_16x16x32_bf16 v[28:31], v[152:155], v[168:171], v[28:31]
	v_mfma_f32_16x16x32_bf16 v[16:19], v[160:163], v[168:171], v[16:19]
	s_setprio 0

.LBB0_4262:
	s_add_i32 s54, 0, 0x18000
	v_add_u32_e32 v1, s54, v226
	s_barrier
	ds_read_b128 v[148:151], v1
	ds_read_b128 v[152:155], v1 offset:1024
	ds_read_b128 v[156:159], v1 offset:2048
	ds_read_b128 v[160:163], v1 offset:3072
	s_add_u32 s28, s28, 0xb0000
	s_addc_u32 s29, s29, 0
	s_mov_b32 m0, s40
	v_lshl_add_u64 v[132:133], s[28:29], 0, v[196:197]
	ds_read_b128 v[164:167], v230 offset:32768
	ds_read_b128 v[168:171], v230 offset:33792
	ds_read_b128 v[172:175], v230 offset:34816
	ds_read_b128 v[176:179], v230 offset:35840
	ds_read_b128 v[180:183], v230 offset:36864
	ds_read_b128 v[184:187], v230 offset:37888
	ds_read_b128 v[188:191], v230 offset:38912
	ds_read_b128 v[192:195], v230 offset:39936
	global_load_lds_dwordx4 v[132:133], off
	v_lshl_add_u64 v[132:133], s[28:29], 0, v[200:201]
	s_mov_b32 m0, s41
	s_nop 0
	global_load_lds_dwordx4 v[132:133], off
	s_waitcnt lgkmcnt(8)
	s_barrier
	s_waitcnt lgkmcnt(0)
	s_setprio 1
	s_waitcnt lgkmcnt(0)
	v_mfma_f32_16x16x32_bf16 v[84:87], v[148:151], v[164:167], v[84:87]
	v_mfma_f32_16x16x32_bf16 v[76:79], v[156:159], v[164:167], v[76:79]
	v_mfma_f32_16x16x32_bf16 v[64:67], v[148:151], v[172:175], v[64:67]
	v_mfma_f32_16x16x32_bf16 v[60:63], v[156:159], v[172:175], v[60:63]
	v_mfma_f32_16x16x32_bf16 v[48:51], v[148:151], v[180:183], v[48:51]
	v_mfma_f32_16x16x32_bf16 v[44:47], v[156:159], v[180:183], v[44:47]
	v_mfma_f32_16x16x32_bf16 v[32:35], v[148:151], v[188:191], v[32:35]
	v_mfma_f32_16x16x32_bf16 v[24:27], v[156:159], v[188:191], v[24:27]
	v_mfma_f32_16x16x32_bf16 v[84:87], v[152:155], v[168:171], v[84:87]
	v_mfma_f32_16x16x32_bf16 v[76:79], v[160:163], v[168:171], v[76:79]
	v_mfma_f32_16x16x32_bf16 v[64:67], v[152:155], v[176:179], v[64:67]
	v_mfma_f32_16x16x32_bf16 v[60:63], v[160:163], v[176:179], v[60:63]
	v_mfma_f32_16x16x32_bf16 v[48:51], v[152:155], v[184:187], v[48:51]
	v_mfma_f32_16x16x32_bf16 v[44:47], v[160:163], v[184:187], v[44:47]
	v_mfma_f32_16x16x32_bf16 v[32:35], v[152:155], v[192:195], v[32:35]
	v_mfma_f32_16x16x32_bf16 v[24:27], v[160:163], v[192:195], v[24:27]
	s_setprio 0
	s_barrier
	s_add_i32 s28, s54, s34
	v_add_u32_e32 v1, 0x1c000, v231
	v_lshl_add_u64 v[2:3], v[2:3], 0, s[14:15]
	s_mov_b32 m0, s28
	ds_read_b128 v[132:135], v1
	ds_read_b128 v[136:139], v1 offset:1024
	ds_read_b128 v[140:143], v1 offset:2048
	ds_read_b128 v[144:147], v1 offset:3072
	global_load_lds_dwordx4 v[2:3], off
	v_lshl_add_u64 v[2:3], v[220:221], 0, s[14:15]
	s_add_i32 m0, s28, 0x2000
	s_nop 0
	global_load_lds_dwordx4 v[2:3], off
	s_barrier
	s_waitcnt lgkmcnt(0)
	s_setprio 1
	s_waitcnt lgkmcnt(0)
	v_mfma_f32_16x16x32_bf16 v[72:75], v[132:135], v[164:167], v[72:75]
	v_mfma_f32_16x16x32_bf16 v[68:71], v[140:143], v[164:167], v[68:71]
	v_mfma_f32_16x16x32_bf16 v[56:59], v[132:135], v[172:175], v[56:59]
	v_mfma_f32_16x16x32_bf16 v[52:55], v[140:143], v[172:175], v[52:55]
	v_mfma_f32_16x16x32_bf16 v[40:43], v[132:135], v[180:183], v[40:43]
	v_mfma_f32_16x16x32_bf16 v[36:39], v[140:143], v[180:183], v[36:39]
	v_mfma_f32_16x16x32_bf16 v[20:23], v[132:135], v[188:191], v[20:23]
	v_mfma_f32_16x16x32_bf16 v[12:15], v[140:143], v[188:191], v[12:15]
	v_mfma_f32_16x16x32_bf16 v[72:75], v[136:139], v[168:171], v[72:75]
	v_mfma_f32_16x16x32_bf16 v[68:71], v[144:147], v[168:171], v[68:71]
	v_mfma_f32_16x16x32_bf16 v[56:59], v[136:139], v[176:179], v[56:59]
	v_mfma_f32_16x16x32_bf16 v[52:55], v[144:147], v[176:179], v[52:55]
	v_mfma_f32_16x16x32_bf16 v[40:43], v[136:139], v[184:187], v[40:43]
	v_mfma_f32_16x16x32_bf16 v[36:39], v[144:147], v[184:187], v[36:39]
	v_mfma_f32_16x16x32_bf16 v[20:23], v[136:139], v[192:195], v[20:23]
	v_mfma_f32_16x16x32_bf16 v[12:15], v[144:147], v[192:195], v[12:15]
	s_setprio 0
	s_mov_b32 m0, s43
	v_lshl_add_u64 v[2:3], v[222:223], 0, s[14:15]
	s_barrier
	ds_read_b128 v[188:191], v230 offset:49152
	ds_read_b128 v[192:195], v230 offset:50176
	ds_read_b128 v[180:183], v230 offset:51200
	ds_read_b128 v[184:187], v230 offset:52224
	ds_read_b128 v[172:175], v230 offset:53248
	ds_read_b128 v[176:179], v230 offset:54272
	ds_read_b128 v[164:167], v230 offset:55296
	ds_read_b128 v[168:171], v230 offset:56320
	global_load_lds_dwordx4 v[2:3], off
	v_lshl_add_u64 v[2:3], v[224:225], 0, s[14:15]
	s_mov_b32 m0, s44
	s_and_b64 vcc, exec, s[10:11]
	global_load_lds_dwordx4 v[2:3], off
	s_barrier
	s_waitcnt lgkmcnt(0)
	s_cbranch_vccnz .LBB0_4264
	s_setprio 1
	s_waitcnt lgkmcnt(0)
	v_mfma_f32_16x16x32_bf16 v[128:131], v[148:151], v[188:191], v[128:131]
	v_mfma_f32_16x16x32_bf16 v[124:127], v[156:159], v[188:191], v[124:127]
	v_mfma_f32_16x16x32_bf16 v[112:115], v[148:151], v[180:183], v[112:115]
	v_mfma_f32_16x16x32_bf16 v[108:111], v[156:159], v[180:183], v[108:111]
	v_mfma_f32_16x16x32_bf16 v[96:99], v[148:151], v[172:175], v[96:99]
	v_mfma_f32_16x16x32_bf16 v[92:95], v[156:159], v[172:175], v[92:95]
	v_mfma_f32_16x16x32_bf16 v[28:31], v[148:151], v[164:167], v[28:31]
	v_mfma_f32_16x16x32_bf16 v[16:19], v[156:159], v[164:167], v[16:19]
	v_mfma_f32_16x16x32_bf16 v[128:131], v[152:155], v[192:195], v[128:131]
	v_mfma_f32_16x16x32_bf16 v[124:127], v[160:163], v[192:195], v[124:127]
	v_mfma_f32_16x16x32_bf16 v[112:115], v[152:155], v[184:187], v[112:115]
	v_mfma_f32_16x16x32_bf16 v[108:111], v[160:163], v[184:187], v[108:111]
	v_mfma_f32_16x16x32_bf16 v[96:99], v[152:155], v[176:179], v[96:99]
	v_mfma_f32_16x16x32_bf16 v[92:95], v[160:163], v[176:179], v[92:95]
	v_mfma_f32_16x16x32_bf16 v[28:31], v[152:155], v[168:171], v[28:31]
	v_mfma_f32_16x16x32_bf16 v[16:19], v[160:163], v[168:171], v[16:19]
	s_setprio 0
